# speedup vs baseline: 1.0185x; 1.0054x over previous
; #define MFMA32(a, b, c) __builtin_amdgcn_mfma_f32_32x32x16_bf16((a), (b), (c), 0, 0, 0)
; DI unsigned fkey(float f) { const unsigned u = __float_as_uint(f); return (u & 0x80000000u) ? ~u : (u | 0x80000000u); }
; DI void topk_phase(unsigned char* smem_, const bf16_t* __restrict__ qp, const bf16_t* __restrict__ keys, int* __restrict__ eidx, float* __restrict__ gate) {
;     ...
;         if (h != cur_h) {
;             cur_h = h;
; #pragma unroll
;             for (int p = 0; p < 2; ++p)
; #pragma unroll
;                 for (int ks = 0; ks < 8; ++ks) kf[p][ks] = *(const bf16x8*)(keys + ((size_t)(h * 2 + p) * 128 + 32 * wid + l31) * 128 + ks * 16 + hi * 8);
;         }
; #pragma unroll
;     for (int p = 0; p < 2; ++p) {
; #pragma unroll
;         for (int i = 0; i < 4; ++i) { const int c = tid + 256 * i; *(u32x4*)(As + (c >> 4) * LDA + (c & 15) * 8) = pre[i]; }
;         __syncthreads();
;         f32x16 acc[2];
; #pragma unroll
;         for (int i = 0; i < 16; ++i) { acc[0][i] = 0.f; acc[1][i] = 0.f; }
; #pragma unroll
;         for (int ks = 0; ks < 8; ++ks) {
; #pragma unroll
;             for (int th = 0; th < 2; ++th) { const bf16x8 qf = *(const bf16x8*)(As + (32 * th + l31) * LDA + ks * 16 + hi * 8); acc[th] = MFMA32(kf[p][ks], qf, acc[th]); }
;         }
; #pragma unroll
;         for (int th = 0; th < 2; ++th)
; #pragma unroll
;             for (int g = 0; g < 4; ++g) { f32x4 o; o.x = acc[th][4 * g]; o.y = acc[th][4 * g + 1]; o.z = acc[th][4 * g + 2]; o.w = acc[th][4 * g + 3]; *(f32x4*)(S + (32 * th + l31) * LDS_ + 32 * wid + 8 * g + 4 * hi) = o; }
;         __syncthreads();
;         if (p == 0) TK_PREFETCH(t, 1); else if (t + G < NT) TK_PREFETCH(t + G, 0);
;         unsigned v[32];
; #pragma unroll
;         for (int i = 0; i < 8; ++i) {
;             const f32x4 sv4 = *(const f32x4*)(S + row * LDS_ + 32 * q + 4 * i);
;             const int ib = 127 - (32 * q + 4 * i);
;             v[4 * i] = (fkey(sv4.x) & ~127u) | (unsigned)ib; v[4 * i + 1] = (fkey(sv4.y) & ~127u) | (unsigned)(ib - 1);
;             v[4 * i + 2] = (fkey(sv4.z) & ~127u) | (unsigned)(ib - 2); v[4 * i + 3] = (fkey(sv4.w) & ~127u) | (unsigned)(ib - 3);
.LBB0_55:
	s_mov_b32 s98, 0x80000000
	s_and_b32 s23, s18, 7
	s_lshl_b32 s0, s23, 8
	s_cmp_eq_u32 s23, s20
	s_cbranch_scc1 .LBB0_57
	v_or_b32_e32 v0, s0, v176
	v_lshlrev_b32_e32 v0, 8, v0
	v_mov_b32_e32 v1, v129
	v_lshl_add_u64 v[0:1], v[112:113], 0, v[0:1]
	global_load_dwordx4 v[32:35], v[0:1], off
	global_load_dwordx4 v[36:39], v[0:1], off offset:32
	global_load_dwordx4 v[40:43], v[0:1], off offset:64
	global_load_dwordx4 v[44:47], v[0:1], off offset:96
	global_load_dwordx4 v[48:51], v[0:1], off offset:128
	global_load_dwordx4 v[52:55], v[0:1], off offset:160
	global_load_dwordx4 v[56:59], v[0:1], off offset:192
	global_load_dwordx4 v[60:63], v[0:1], off offset:224
	v_add_co_u32_e32 v0, vcc, 0x8000, v0
	s_mov_b32 s20, s23
	s_nop 0
	v_addc_co_u32_e32 v1, vcc, 0, v1, vcc
	global_load_dwordx4 v[64:67], v[0:1], off
	global_load_dwordx4 v[68:71], v[0:1], off offset:32
	global_load_dwordx4 v[72:75], v[0:1], off offset:64
	global_load_dwordx4 v[76:79], v[0:1], off offset:96
	global_load_dwordx4 v[80:83], v[0:1], off offset:128
	global_load_dwordx4 v[84:87], v[0:1], off offset:160
	global_load_dwordx4 v[88:91], v[0:1], off offset:192
	global_load_dwordx4 v[92:95], v[0:1], off offset:224
.LBB0_57:
	s_waitcnt vmcnt(0)
	ds_write_b128 v234, v[96:99]
	ds_write_b128 v234, v[100:103] offset:4352
	ds_write_b128 v234, v[104:107] offset:8704
	ds_write_b128 v234, v[108:111] offset:13056
	s_waitcnt lgkmcnt(0)
	s_barrier
	ds_read_b128 v[0:3], v235
	ds_read_b128 v[96:99], v235 offset:32
	s_waitcnt lgkmcnt(1)
	v_mfma_f32_32x32x16_bf16 v[16:31], v[32:35], v[0:3], 0
	ds_read_b128 v[0:3], v235 offset:8704
	s_and_b32 s24, s22, 0xffffffc0
	s_lshl_b32 s0, s0, 1
	s_add_u32 s0, s86, s0
	s_addc_u32 s1, s87, 0
	s_waitcnt lgkmcnt(1)
	v_mfma_f32_32x32x16_bf16 v[16:31], v[36:39], v[96:99], v[16:31]
	ds_read_b128 v[96:99], v235 offset:8736
	s_waitcnt lgkmcnt(1)
	v_mfma_f32_32x32x16_bf16 v[0:15], v[32:35], v[0:3], 0
	s_waitcnt lgkmcnt(0)
	v_mfma_f32_32x32x16_bf16 v[0:15], v[36:39], v[96:99], v[0:15]
	ds_read_b128 v[96:99], v235 offset:64
	s_waitcnt lgkmcnt(0)
	v_mfma_f32_32x32x16_bf16 v[16:31], v[40:43], v[96:99], v[16:31]
	ds_read_b128 v[96:99], v235 offset:8768
	s_waitcnt lgkmcnt(0)
	v_mfma_f32_32x32x16_bf16 v[0:15], v[40:43], v[96:99], v[0:15]
	ds_read_b128 v[96:99], v235 offset:96
	s_waitcnt lgkmcnt(0)
	v_mfma_f32_32x32x16_bf16 v[16:31], v[44:47], v[96:99], v[16:31]
	ds_read_b128 v[96:99], v235 offset:8800
	s_waitcnt lgkmcnt(0)
	v_mfma_f32_32x32x16_bf16 v[0:15], v[44:47], v[96:99], v[0:15]
	ds_read_b128 v[96:99], v235 offset:128
	s_waitcnt lgkmcnt(0)
	v_mfma_f32_32x32x16_bf16 v[16:31], v[48:51], v[96:99], v[16:31]
	ds_read_b128 v[96:99], v235 offset:8832
	s_waitcnt lgkmcnt(0)
	v_mfma_f32_32x32x16_bf16 v[0:15], v[48:51], v[96:99], v[0:15]
	ds_read_b128 v[96:99], v235 offset:160
	s_waitcnt lgkmcnt(0)
	v_mfma_f32_32x32x16_bf16 v[16:31], v[52:55], v[96:99], v[16:31]
	ds_read_b128 v[96:99], v235 offset:8864
	s_waitcnt lgkmcnt(0)
	v_mfma_f32_32x32x16_bf16 v[0:15], v[52:55], v[96:99], v[0:15]
	ds_read_b128 v[96:99], v235 offset:192
	s_waitcnt lgkmcnt(0)
	v_mfma_f32_32x32x16_bf16 v[16:31], v[56:59], v[96:99], v[16:31]
	ds_read_b128 v[96:99], v235 offset:8896
	s_waitcnt lgkmcnt(0)
	v_mfma_f32_32x32x16_bf16 v[0:15], v[56:59], v[96:99], v[0:15]
	ds_read_b128 v[96:99], v235 offset:224
	s_waitcnt lgkmcnt(0)
	v_mfma_f32_32x32x16_bf16 v[16:31], v[60:63], v[96:99], v[16:31]
	ds_read_b128 v[96:99], v235 offset:8928
	s_nop 10
	ds_write_b128 v236, v[16:19] offset:17408
	ds_write_b128 v236, v[20:23] offset:17440
	ds_write_b128 v236, v[24:27] offset:17472
	ds_write_b128 v236, v[28:31] offset:17504
	s_waitcnt lgkmcnt(4)
	v_mfma_f32_32x32x16_bf16 v[0:15], v[60:63], v[96:99], v[0:15]
	s_nop 11
	ds_write_b128 v236, v[0:3] offset:34304
	ds_write_b128 v236, v[4:7] offset:34336
	ds_write_b128 v236, v[8:11] offset:34368
	ds_write_b128 v236, v[12:15] offset:34400
	v_or_b32_e32 v0, s24, v165
	v_ashrrev_i32_e32 v1, 31, v0
	v_lshlrev_b64 v[0:1], 12, v[0:1]
	v_lshl_add_u64 v[0:1], s[0:1], 0, v[0:1]
	v_lshl_add_u64 v[0:1], v[0:1], 0, v[128:129]
	s_waitcnt lgkmcnt(0)
	s_barrier
	global_load_dwordx4 v[96:99], v[0:1], off offset:256
	v_or_b32_e32 v0, s24, v166
	v_ashrrev_i32_e32 v1, 31, v0
	v_lshlrev_b64 v[0:1], 12, v[0:1]
	v_lshl_add_u64 v[0:1], s[0:1], 0, v[0:1]
	v_lshl_add_u64 v[0:1], v[0:1], 0, v[128:129]
	global_load_dwordx4 v[100:103], v[0:1], off offset:256
	v_or_b32_e32 v0, s24, v167
	v_ashrrev_i32_e32 v1, 31, v0
	v_lshlrev_b64 v[0:1], 12, v[0:1]
	v_lshl_add_u64 v[0:1], s[0:1], 0, v[0:1]
	v_lshl_add_u64 v[0:1], v[0:1], 0, v[128:129]
	global_load_dwordx4 v[104:107], v[0:1], off offset:256
	v_or_b32_e32 v0, s24, v168
	v_ashrrev_i32_e32 v1, 31, v0
	v_lshlrev_b64 v[0:1], 12, v[0:1]
	v_lshl_add_u64 v[0:1], s[0:1], 0, v[0:1]
	v_lshl_add_u64 v[4:5], v[0:1], 0, v[128:129]
	ds_read_b128 v[0:3], v171 offset:17408
	global_load_dwordx4 v[108:111], v[4:5], off offset:256
	ds_read_b128 v[4:7], v171 offset:17424
	ds_read_b128 v[8:11], v171 offset:17440
	ds_read_b128 v[12:15], v171 offset:17456
	s_waitcnt lgkmcnt(3)
	v_ashrrev_i32_e32 v16, 31, v0


; DI unsigned fkey(float f) { const unsigned u = __float_as_uint(f); return (u & 0x80000000u) ? ~u : (u | 0x80000000u); }
; DI void topk_phase(unsigned char* smem_, const bf16_t* __restrict__ qp, const bf16_t* __restrict__ keys, int* __restrict__ eidx, float* __restrict__ gate) {
;     ...
;         for (int i = 0; i < 8; ++i) {
;             const f32x4 sv4 = *(const f32x4*)(S + row * LDS_ + 32 * q + 4 * i);
;             const int ib = 127 - (32 * q + 4 * i);
;             v[4 * i] = (fkey(sv4.x) & ~127u) | (unsigned)ib; v[4 * i + 1] = (fkey(sv4.y) & ~127u) | (unsigned)(ib - 1);
;             v[4 * i + 2] = (fkey(sv4.z) & ~127u) | (unsigned)(ib - 2); v[4 * i + 3] = (fkey(sv4.w) & ~127u) | (unsigned)(ib - 3);
	s_waitcnt lgkmcnt(0)
	v_not_b32_e32 v20, v15
	v_or_b32_e32 v21, 0x80000000, v15
	v_bitop3_b32 v0, v16, s98, v0 bitop3:0x56
	v_ashrrev_i32_e32 v16, 31, v1


; DI unsigned fkey(float f) { const unsigned u = __float_as_uint(f); return (u & 0x80000000u) ? ~u : (u | 0x80000000u); }
; DI void topk_phase(unsigned char* smem_, const bf16_t* __restrict__ qp, const bf16_t* __restrict__ keys, int* __restrict__ eidx, float* __restrict__ gate) {
;     ...
;         for (int i = 0; i < 8; ++i) {
;             const f32x4 sv4 = *(const f32x4*)(S + row * LDS_ + 32 * q + 4 * i);
;             const int ib = 127 - (32 * q + 4 * i);
;             v[4 * i] = (fkey(sv4.x) & ~127u) | (unsigned)ib; v[4 * i + 1] = (fkey(sv4.y) & ~127u) | (unsigned)(ib - 1);
;             v[4 * i + 2] = (fkey(sv4.z) & ~127u) | (unsigned)(ib - 2); v[4 * i + 3] = (fkey(sv4.w) & ~127u) | (unsigned)(ib - 3);
	v_and_b32_e32 v0, 0xffffff80, v0
	v_sub_u32_e32 v0, v0, v170
	v_bitop3_b32 v1, v16, s98, v1 bitop3:0x56
	v_ashrrev_i32_e32 v16, 31, v2


; DI unsigned fkey(float f) { const unsigned u = __float_as_uint(f); return (u & 0x80000000u) ? ~u : (u | 0x80000000u); }
; DI void topk_phase(unsigned char* smem_, const bf16_t* __restrict__ qp, const bf16_t* __restrict__ keys, int* __restrict__ eidx, float* __restrict__ gate) {
;     ...
;         for (int i = 0; i < 8; ++i) {
;             const f32x4 sv4 = *(const f32x4*)(S + row * LDS_ + 32 * q + 4 * i);
;             const int ib = 127 - (32 * q + 4 * i);
;             v[4 * i] = (fkey(sv4.x) & ~127u) | (unsigned)ib; v[4 * i + 1] = (fkey(sv4.y) & ~127u) | (unsigned)(ib - 1);
;             v[4 * i + 2] = (fkey(sv4.z) & ~127u) | (unsigned)(ib - 2); v[4 * i + 3] = (fkey(sv4.w) & ~127u) | (unsigned)(ib - 3);
	v_and_b32_e32 v1, 0xffffff80, v1
	v_sub_u32_e32 v1, v1, v170
	v_bitop3_b32 v2, v16, s98, v2 bitop3:0x56
	v_ashrrev_i32_e32 v16, 31, v3


; DI unsigned fkey(float f) { const unsigned u = __float_as_uint(f); return (u & 0x80000000u) ? ~u : (u | 0x80000000u); }
; DI void topk_phase(unsigned char* smem_, const bf16_t* __restrict__ qp, const bf16_t* __restrict__ keys, int* __restrict__ eidx, float* __restrict__ gate) {
;     ...
;         for (int i = 0; i < 8; ++i) {
;             const f32x4 sv4 = *(const f32x4*)(S + row * LDS_ + 32 * q + 4 * i);
;             const int ib = 127 - (32 * q + 4 * i);
;             v[4 * i] = (fkey(sv4.x) & ~127u) | (unsigned)ib; v[4 * i + 1] = (fkey(sv4.y) & ~127u) | (unsigned)(ib - 1);
;             v[4 * i + 2] = (fkey(sv4.z) & ~127u) | (unsigned)(ib - 2); v[4 * i + 3] = (fkey(sv4.w) & ~127u) | (unsigned)(ib - 3);
	v_and_b32_e32 v2, 0xffffff80, v2
	v_sub_u32_e32 v2, v2, v170
	v_bitop3_b32 v3, v16, s98, v3 bitop3:0x56
	v_ashrrev_i32_e32 v16, 31, v4


; DI unsigned fkey(float f) { const unsigned u = __float_as_uint(f); return (u & 0x80000000u) ? ~u : (u | 0x80000000u); }
; DI void topk_phase(unsigned char* smem_, const bf16_t* __restrict__ qp, const bf16_t* __restrict__ keys, int* __restrict__ eidx, float* __restrict__ gate) {
;     ...
;         for (int i = 0; i < 8; ++i) {
;             const f32x4 sv4 = *(const f32x4*)(S + row * LDS_ + 32 * q + 4 * i);
;             const int ib = 127 - (32 * q + 4 * i);
;             v[4 * i] = (fkey(sv4.x) & ~127u) | (unsigned)ib; v[4 * i + 1] = (fkey(sv4.y) & ~127u) | (unsigned)(ib - 1);
;             v[4 * i + 2] = (fkey(sv4.z) & ~127u) | (unsigned)(ib - 2); v[4 * i + 3] = (fkey(sv4.w) & ~127u) | (unsigned)(ib - 3);
	v_and_b32_e32 v3, 0xffffff80, v3
	v_sub_u32_e32 v3, v3, v170
	v_bitop3_b32 v4, v16, s98, v4 bitop3:0x56
	v_ashrrev_i32_e32 v16, 31, v5


; DI unsigned fkey(float f) { const unsigned u = __float_as_uint(f); return (u & 0x80000000u) ? ~u : (u | 0x80000000u); }
; DI void topk_phase(unsigned char* smem_, const bf16_t* __restrict__ qp, const bf16_t* __restrict__ keys, int* __restrict__ eidx, float* __restrict__ gate) {
;     ...
;         for (int i = 0; i < 8; ++i) {
;             const f32x4 sv4 = *(const f32x4*)(S + row * LDS_ + 32 * q + 4 * i);
;             const int ib = 127 - (32 * q + 4 * i);
;             v[4 * i] = (fkey(sv4.x) & ~127u) | (unsigned)ib; v[4 * i + 1] = (fkey(sv4.y) & ~127u) | (unsigned)(ib - 1);
;             v[4 * i + 2] = (fkey(sv4.z) & ~127u) | (unsigned)(ib - 2); v[4 * i + 3] = (fkey(sv4.w) & ~127u) | (unsigned)(ib - 3);
	v_and_b32_e32 v4, 0xffffff80, v4
	v_sub_u32_e32 v4, v4, v177
	v_bitop3_b32 v5, v16, s98, v5 bitop3:0x56
	v_ashrrev_i32_e32 v16, 31, v6


; DI unsigned fkey(float f) { const unsigned u = __float_as_uint(f); return (u & 0x80000000u) ? ~u : (u | 0x80000000u); }
; DI void topk_phase(unsigned char* smem_, const bf16_t* __restrict__ qp, const bf16_t* __restrict__ keys, int* __restrict__ eidx, float* __restrict__ gate) {
;     ...
;         for (int i = 0; i < 8; ++i) {
;             const f32x4 sv4 = *(const f32x4*)(S + row * LDS_ + 32 * q + 4 * i);
;             const int ib = 127 - (32 * q + 4 * i);
;             v[4 * i] = (fkey(sv4.x) & ~127u) | (unsigned)ib; v[4 * i + 1] = (fkey(sv4.y) & ~127u) | (unsigned)(ib - 1);
;             v[4 * i + 2] = (fkey(sv4.z) & ~127u) | (unsigned)(ib - 2); v[4 * i + 3] = (fkey(sv4.w) & ~127u) | (unsigned)(ib - 3);
	v_and_b32_e32 v5, 0xffffff80, v5
	v_sub_u32_e32 v5, v5, v177
	v_bitop3_b32 v6, v16, s98, v6 bitop3:0x56
	v_ashrrev_i32_e32 v16, 31, v7


; DI unsigned fkey(float f) { const unsigned u = __float_as_uint(f); return (u & 0x80000000u) ? ~u : (u | 0x80000000u); }
; DI void topk_phase(unsigned char* smem_, const bf16_t* __restrict__ qp, const bf16_t* __restrict__ keys, int* __restrict__ eidx, float* __restrict__ gate) {
;     ...
;         for (int i = 0; i < 8; ++i) {
;             const f32x4 sv4 = *(const f32x4*)(S + row * LDS_ + 32 * q + 4 * i);
;             const int ib = 127 - (32 * q + 4 * i);
;             v[4 * i] = (fkey(sv4.x) & ~127u) | (unsigned)ib; v[4 * i + 1] = (fkey(sv4.y) & ~127u) | (unsigned)(ib - 1);
;             v[4 * i + 2] = (fkey(sv4.z) & ~127u) | (unsigned)(ib - 2); v[4 * i + 3] = (fkey(sv4.w) & ~127u) | (unsigned)(ib - 3);
	v_and_b32_e32 v6, 0xffffff80, v6
	v_sub_u32_e32 v6, v6, v177
	v_bitop3_b32 v7, v16, s98, v7 bitop3:0x56
	v_ashrrev_i32_e32 v16, 31, v8


; DI unsigned fkey(float f) { const unsigned u = __float_as_uint(f); return (u & 0x80000000u) ? ~u : (u | 0x80000000u); }
; DI void topk_phase(unsigned char* smem_, const bf16_t* __restrict__ qp, const bf16_t* __restrict__ keys, int* __restrict__ eidx, float* __restrict__ gate) {
;     ...
;         for (int i = 0; i < 8; ++i) {
;             const f32x4 sv4 = *(const f32x4*)(S + row * LDS_ + 32 * q + 4 * i);
;             const int ib = 127 - (32 * q + 4 * i);
;             v[4 * i] = (fkey(sv4.x) & ~127u) | (unsigned)ib; v[4 * i + 1] = (fkey(sv4.y) & ~127u) | (unsigned)(ib - 1);
;             v[4 * i + 2] = (fkey(sv4.z) & ~127u) | (unsigned)(ib - 2); v[4 * i + 3] = (fkey(sv4.w) & ~127u) | (unsigned)(ib - 3);
	v_and_b32_e32 v7, 0xffffff80, v7
	v_sub_u32_e32 v7, v7, v177
	v_bitop3_b32 v8, v16, s98, v8 bitop3:0x56
	v_ashrrev_i32_e32 v16, 31, v9


; DI unsigned fkey(float f) { const unsigned u = __float_as_uint(f); return (u & 0x80000000u) ? ~u : (u | 0x80000000u); }
; DI void topk_phase(unsigned char* smem_, const bf16_t* __restrict__ qp, const bf16_t* __restrict__ keys, int* __restrict__ eidx, float* __restrict__ gate) {
;     ...
;         for (int i = 0; i < 8; ++i) {
;             const f32x4 sv4 = *(const f32x4*)(S + row * LDS_ + 32 * q + 4 * i);
;             const int ib = 127 - (32 * q + 4 * i);
;             v[4 * i] = (fkey(sv4.x) & ~127u) | (unsigned)ib; v[4 * i + 1] = (fkey(sv4.y) & ~127u) | (unsigned)(ib - 1);
;             v[4 * i + 2] = (fkey(sv4.z) & ~127u) | (unsigned)(ib - 2); v[4 * i + 3] = (fkey(sv4.w) & ~127u) | (unsigned)(ib - 3);
	v_and_b32_e32 v8, 0xffffff80, v8
	v_sub_u32_e32 v8, v8, v178
	v_bitop3_b32 v9, v16, s98, v9 bitop3:0x56
	v_ashrrev_i32_e32 v16, 31, v10


; DI unsigned fkey(float f) { const unsigned u = __float_as_uint(f); return (u & 0x80000000u) ? ~u : (u | 0x80000000u); }
; DI void topk_phase(unsigned char* smem_, const bf16_t* __restrict__ qp, const bf16_t* __restrict__ keys, int* __restrict__ eidx, float* __restrict__ gate) {
;     ...
;         for (int i = 0; i < 8; ++i) {
;             const f32x4 sv4 = *(const f32x4*)(S + row * LDS_ + 32 * q + 4 * i);
;             const int ib = 127 - (32 * q + 4 * i);
;             v[4 * i] = (fkey(sv4.x) & ~127u) | (unsigned)ib; v[4 * i + 1] = (fkey(sv4.y) & ~127u) | (unsigned)(ib - 1);
;             v[4 * i + 2] = (fkey(sv4.z) & ~127u) | (unsigned)(ib - 2); v[4 * i + 3] = (fkey(sv4.w) & ~127u) | (unsigned)(ib - 3);
	v_and_b32_e32 v9, 0xffffff80, v9
	v_sub_u32_e32 v9, v9, v178
	v_bitop3_b32 v10, v16, s98, v10 bitop3:0x56
	v_and_b32_e32 v10, 0xffffff80, v10
	v_sub_u32_e32 v10, v10, v178
	v_add_u32_e32 v16, 0x7d, v10
	v_not_b32_e32 v10, v11
	v_or_b32_e32 v17, 0x80000000, v11
	v_cmp_gt_i32_e32 vcc, 0, v11
	v_ashrrev_i32_e32 v11, 31, v12
	v_add_u32_e32 v0, 0x7f, v0
	v_cndmask_b32_e32 v10, v17, v10, vcc
	v_and_b32_e32 v10, 0xffffff80, v10
	v_sub_u32_e32 v10, v10, v178
	v_add_u32_e32 v17, 0x7c, v10


; DI unsigned fkey(float f) { const unsigned u = __float_as_uint(f); return (u & 0x80000000u) ? ~u : (u | 0x80000000u); }
; DI void topk_phase(unsigned char* smem_, const bf16_t* __restrict__ qp, const bf16_t* __restrict__ keys, int* __restrict__ eidx, float* __restrict__ gate) {
;     ...
;         for (int i = 0; i < 8; ++i) {
;             const f32x4 sv4 = *(const f32x4*)(S + row * LDS_ + 32 * q + 4 * i);
;             const int ib = 127 - (32 * q + 4 * i);
;             v[4 * i] = (fkey(sv4.x) & ~127u) | (unsigned)ib; v[4 * i + 1] = (fkey(sv4.y) & ~127u) | (unsigned)(ib - 1);
;             v[4 * i + 2] = (fkey(sv4.z) & ~127u) | (unsigned)(ib - 2); v[4 * i + 3] = (fkey(sv4.w) & ~127u) | (unsigned)(ib - 3);
	v_add_u32_e32 v1, 0x7e, v1
	v_add_u32_e32 v2, 0x7d, v2
	v_bitop3_b32 v10, v11, s98, v12 bitop3:0x56
	v_and_b32_e32 v10, 0xffffff80, v10
	v_sub_u32_e32 v10, v10, v179
	v_add_u32_e32 v18, 0x7f, v10
	v_ashrrev_i32_e32 v10, 31, v13


; DI unsigned fkey(float f) { const unsigned u = __float_as_uint(f); return (u & 0x80000000u) ? ~u : (u | 0x80000000u); }
; DI void topk_phase(unsigned char* smem_, const bf16_t* __restrict__ qp, const bf16_t* __restrict__ keys, int* __restrict__ eidx, float* __restrict__ gate) {
;     ...
;         for (int i = 0; i < 8; ++i) {
;             const f32x4 sv4 = *(const f32x4*)(S + row * LDS_ + 32 * q + 4 * i);
;             const int ib = 127 - (32 * q + 4 * i);
;             v[4 * i] = (fkey(sv4.x) & ~127u) | (unsigned)ib; v[4 * i + 1] = (fkey(sv4.y) & ~127u) | (unsigned)(ib - 1);
;             v[4 * i + 2] = (fkey(sv4.z) & ~127u) | (unsigned)(ib - 2); v[4 * i + 3] = (fkey(sv4.w) & ~127u) | (unsigned)(ib - 3);
	v_add_u32_e32 v3, 0x7c, v3
	v_add_u32_e32 v4, 0x7f, v4
	v_bitop3_b32 v10, v10, s98, v13 bitop3:0x56
	v_and_b32_e32 v10, 0xffffff80, v10
	v_sub_u32_e32 v10, v10, v179
	v_add_u32_e32 v19, 0x7e, v10
	v_ashrrev_i32_e32 v10, 31, v14


; DI unsigned fkey(float f) { const unsigned u = __float_as_uint(f); return (u & 0x80000000u) ? ~u : (u | 0x80000000u); }
; DI void topk_phase(unsigned char* smem_, const bf16_t* __restrict__ qp, const bf16_t* __restrict__ keys, int* __restrict__ eidx, float* __restrict__ gate) {
;     ...
;         for (int i = 0; i < 8; ++i) {
;             const f32x4 sv4 = *(const f32x4*)(S + row * LDS_ + 32 * q + 4 * i);
;             const int ib = 127 - (32 * q + 4 * i);
;             v[4 * i] = (fkey(sv4.x) & ~127u) | (unsigned)ib; v[4 * i + 1] = (fkey(sv4.y) & ~127u) | (unsigned)(ib - 1);
;             v[4 * i + 2] = (fkey(sv4.z) & ~127u) | (unsigned)(ib - 2); v[4 * i + 3] = (fkey(sv4.w) & ~127u) | (unsigned)(ib - 3);
	v_add_u32_e32 v5, 0x7e, v5
	v_add_u32_e32 v6, 0x7d, v6
	v_bitop3_b32 v10, v10, s98, v14 bitop3:0x56
	v_and_b32_e32 v10, 0xffffff80, v10
	v_sub_u32_e32 v10, v10, v179
	v_add_u32_e32 v14, 0x7d, v10
	ds_read_b128 v[10:13], v171 offset:17472
	v_cmp_gt_i32_e32 vcc, 0, v15
	v_add_u32_e32 v7, 0x7c, v7
	v_add_u32_e32 v8, 0x7f, v8
	v_cndmask_b32_e32 v15, v21, v20, vcc
	s_waitcnt lgkmcnt(0)
	v_ashrrev_i32_e32 v20, 31, v10


; DI unsigned fkey(float f) { const unsigned u = __float_as_uint(f); return (u & 0x80000000u) ? ~u : (u | 0x80000000u); }
; DI void topk_phase(unsigned char* smem_, const bf16_t* __restrict__ qp, const bf16_t* __restrict__ keys, int* __restrict__ eidx, float* __restrict__ gate) {
;     ...
;         for (int i = 0; i < 8; ++i) {
;             const f32x4 sv4 = *(const f32x4*)(S + row * LDS_ + 32 * q + 4 * i);
;             const int ib = 127 - (32 * q + 4 * i);
;             v[4 * i] = (fkey(sv4.x) & ~127u) | (unsigned)ib; v[4 * i + 1] = (fkey(sv4.y) & ~127u) | (unsigned)(ib - 1);
;             v[4 * i + 2] = (fkey(sv4.z) & ~127u) | (unsigned)(ib - 2); v[4 * i + 3] = (fkey(sv4.w) & ~127u) | (unsigned)(ib - 3);
	v_not_b32_e32 v23, v13
	v_or_b32_e32 v24, 0x80000000, v13
	v_bitop3_b32 v10, v20, s98, v10 bitop3:0x56
	v_and_b32_e32 v10, 0xffffff80, v10
	v_sub_u32_e32 v10, v10, v180
	v_add_u32_e32 v20, 0x7f, v10
	v_not_b32_e32 v10, v11
	v_or_b32_e32 v21, 0x80000000, v11
	v_cmp_gt_i32_e32 vcc, 0, v11
	v_ashrrev_i32_e32 v11, 31, v12
	v_and_b32_e32 v15, 0xffffff80, v15
	v_cndmask_b32_e32 v10, v21, v10, vcc
	v_and_b32_e32 v10, 0xffffff80, v10
	v_sub_u32_e32 v10, v10, v180
	v_add_u32_e32 v21, 0x7e, v10


; DI unsigned fkey(float f) { const unsigned u = __float_as_uint(f); return (u & 0x80000000u) ? ~u : (u | 0x80000000u); }
; DI void topk_phase(unsigned char* smem_, const bf16_t* __restrict__ qp, const bf16_t* __restrict__ keys, int* __restrict__ eidx, float* __restrict__ gate) {
;     ...
;         for (int i = 0; i < 8; ++i) {
;             const f32x4 sv4 = *(const f32x4*)(S + row * LDS_ + 32 * q + 4 * i);
;             const int ib = 127 - (32 * q + 4 * i);
;             v[4 * i] = (fkey(sv4.x) & ~127u) | (unsigned)ib; v[4 * i + 1] = (fkey(sv4.y) & ~127u) | (unsigned)(ib - 1);
;             v[4 * i + 2] = (fkey(sv4.z) & ~127u) | (unsigned)(ib - 2); v[4 * i + 3] = (fkey(sv4.w) & ~127u) | (unsigned)(ib - 3);
	v_sub_u32_e32 v15, v15, v179
	v_add_u32_e32 v9, 0x7e, v9
	v_bitop3_b32 v10, v11, s98, v12 bitop3:0x56
	v_and_b32_e32 v10, 0xffffff80, v10
	v_sub_u32_e32 v10, v10, v180
	v_add_u32_e32 v22, 0x7d, v10
	v_cmp_gt_i32_e32 vcc, 0, v13
	ds_read_b128 v[10:13], v171 offset:17488
	v_add_u32_e32 v15, 0x7c, v15
	v_cndmask_b32_e32 v23, v24, v23, vcc
	v_and_b32_e32 v23, 0xffffff80, v23
	v_sub_u32_e32 v23, v23, v180
	s_waitcnt lgkmcnt(0)
	v_ashrrev_i32_e32 v24, 31, v10


; DI unsigned fkey(float f) { const unsigned u = __float_as_uint(f); return (u & 0x80000000u) ? ~u : (u | 0x80000000u); }
; DI void topk_phase(unsigned char* smem_, const bf16_t* __restrict__ qp, const bf16_t* __restrict__ keys, int* __restrict__ eidx, float* __restrict__ gate) {
;     ...
;         for (int i = 0; i < 8; ++i) {
;             const f32x4 sv4 = *(const f32x4*)(S + row * LDS_ + 32 * q + 4 * i);
;             const int ib = 127 - (32 * q + 4 * i);
;             v[4 * i] = (fkey(sv4.x) & ~127u) | (unsigned)ib; v[4 * i + 1] = (fkey(sv4.y) & ~127u) | (unsigned)(ib - 1);
;             v[4 * i + 2] = (fkey(sv4.z) & ~127u) | (unsigned)(ib - 2); v[4 * i + 3] = (fkey(sv4.w) & ~127u) | (unsigned)(ib - 3);
	v_not_b32_e32 v27, v13
	v_or_b32_e32 v28, 0x80000000, v13
	v_bitop3_b32 v10, v24, s98, v10 bitop3:0x56
	v_and_b32_e32 v10, 0xffffff80, v10
	v_sub_u32_e32 v10, v10, v181
	v_add_u32_e32 v24, 0x7f, v10
	v_not_b32_e32 v10, v11
	v_or_b32_e32 v25, 0x80000000, v11
	v_cmp_gt_i32_e32 vcc, 0, v11
	v_ashrrev_i32_e32 v11, 31, v12
	v_add_u32_e32 v23, 0x7c, v23
	v_cndmask_b32_e32 v10, v25, v10, vcc
	v_and_b32_e32 v10, 0xffffff80, v10
	v_sub_u32_e32 v10, v10, v181
	v_add_u32_e32 v25, 0x7e, v10


; DI unsigned fkey(float f) { const unsigned u = __float_as_uint(f); return (u & 0x80000000u) ? ~u : (u | 0x80000000u); }
; DI void topk_phase(unsigned char* smem_, const bf16_t* __restrict__ qp, const bf16_t* __restrict__ keys, int* __restrict__ eidx, float* __restrict__ gate) {
;     ...
;         for (int i = 0; i < 8; ++i) {
;             const f32x4 sv4 = *(const f32x4*)(S + row * LDS_ + 32 * q + 4 * i);
;             const int ib = 127 - (32 * q + 4 * i);
;             v[4 * i] = (fkey(sv4.x) & ~127u) | (unsigned)ib; v[4 * i + 1] = (fkey(sv4.y) & ~127u) | (unsigned)(ib - 1);
;             v[4 * i + 2] = (fkey(sv4.z) & ~127u) | (unsigned)(ib - 2); v[4 * i + 3] = (fkey(sv4.w) & ~127u) | (unsigned)(ib - 3);
	s_nop 1
	v_bitop3_b32 v10, v11, s98, v12 bitop3:0x56
	v_and_b32_e32 v10, 0xffffff80, v10
	v_sub_u32_e32 v10, v10, v181
	v_add_u32_e32 v26, 0x7d, v10
	v_cmp_gt_i32_e32 vcc, 0, v13
	ds_read_b128 v[10:13], v171 offset:17504
	s_waitcnt lgkmcnt(0)
	v_ashrrev_i32_e32 v29, 31, v10
	v_cndmask_b32_e32 v27, v28, v27, vcc


; DI unsigned fkey(float f) { const unsigned u = __float_as_uint(f); return (u & 0x80000000u) ? ~u : (u | 0x80000000u); }
; DI void topk_phase(unsigned char* smem_, const bf16_t* __restrict__ qp, const bf16_t* __restrict__ keys, int* __restrict__ eidx, float* __restrict__ gate) {
;     ...
;         for (int i = 0; i < 8; ++i) {
;             const f32x4 sv4 = *(const f32x4*)(S + row * LDS_ + 32 * q + 4 * i);
;             const int ib = 127 - (32 * q + 4 * i);
;             v[4 * i] = (fkey(sv4.x) & ~127u) | (unsigned)ib; v[4 * i + 1] = (fkey(sv4.y) & ~127u) | (unsigned)(ib - 1);
;             v[4 * i + 2] = (fkey(sv4.z) & ~127u) | (unsigned)(ib - 2); v[4 * i + 3] = (fkey(sv4.w) & ~127u) | (unsigned)(ib - 3);
	v_not_b32_e32 v31, v13
	v_or_b32_e32 v116, 0x80000000, v13
	v_bitop3_b32 v10, v29, s98, v10 bitop3:0x56
	v_and_b32_e32 v10, 0xffffff80, v10
	v_sub_u32_e32 v10, v10, v182
	v_add_u32_e32 v28, 0x7f, v10
	v_not_b32_e32 v10, v11
	v_or_b32_e32 v29, 0x80000000, v11
	v_cmp_gt_i32_e32 vcc, 0, v11
	v_ashrrev_i32_e32 v11, 31, v12
	v_and_b32_e32 v27, 0xffffff80, v27
	v_cndmask_b32_e32 v10, v29, v10, vcc
	v_and_b32_e32 v10, 0xffffff80, v10
	v_sub_u32_e32 v10, v10, v182
	v_add_u32_e32 v29, 0x7e, v10


; DI unsigned fkey(float f) { const unsigned u = __float_as_uint(f); return (u & 0x80000000u) ? ~u : (u | 0x80000000u); }
; DI void topk_phase(unsigned char* smem_, const bf16_t* __restrict__ qp, const bf16_t* __restrict__ keys, int* __restrict__ eidx, float* __restrict__ gate) {
;     ...
;         for (int i = 0; i < 8; ++i) {
;             const f32x4 sv4 = *(const f32x4*)(S + row * LDS_ + 32 * q + 4 * i);
;             const int ib = 127 - (32 * q + 4 * i);
;             v[4 * i] = (fkey(sv4.x) & ~127u) | (unsigned)ib; v[4 * i + 1] = (fkey(sv4.y) & ~127u) | (unsigned)(ib - 1);
;             v[4 * i + 2] = (fkey(sv4.z) & ~127u) | (unsigned)(ib - 2); v[4 * i + 3] = (fkey(sv4.w) & ~127u) | (unsigned)(ib - 3);
	v_sub_u32_e32 v27, v27, v181
	v_add_u32_e32 v27, 0x7c, v27
	v_bitop3_b32 v10, v11, s98, v12 bitop3:0x56
	v_and_b32_e32 v10, 0xffffff80, v10
	v_sub_u32_e32 v10, v10, v182
	v_add_u32_e32 v30, 0x7d, v10
	v_cmp_gt_i32_e32 vcc, 0, v13
	ds_read_b128 v[10:13], v171 offset:17520
	s_waitcnt lgkmcnt(0)
	v_ashrrev_i32_e32 v117, 31, v10
	v_cndmask_b32_e32 v31, v116, v31, vcc


; DI unsigned fkey(float f) { const unsigned u = __float_as_uint(f); return (u & 0x80000000u) ? ~u : (u | 0x80000000u); }
; DI void topk_phase(unsigned char* smem_, const bf16_t* __restrict__ qp, const bf16_t* __restrict__ keys, int* __restrict__ eidx, float* __restrict__ gate) {
;     ...
;         for (int i = 0; i < 8; ++i) {
;             const f32x4 sv4 = *(const f32x4*)(S + row * LDS_ + 32 * q + 4 * i);
;             const int ib = 127 - (32 * q + 4 * i);
;             v[4 * i] = (fkey(sv4.x) & ~127u) | (unsigned)ib; v[4 * i + 1] = (fkey(sv4.y) & ~127u) | (unsigned)(ib - 1);
;             v[4 * i + 2] = (fkey(sv4.z) & ~127u) | (unsigned)(ib - 2); v[4 * i + 3] = (fkey(sv4.w) & ~127u) | (unsigned)(ib - 3);
	v_and_b32_e32 v31, 0xffffff80, v31
	v_sub_u32_e32 v31, v31, v182
	v_bitop3_b32 v10, v117, s98, v10 bitop3:0x56
	v_ashrrev_i32_e32 v116, 31, v11


; DI unsigned fkey(float f) { const unsigned u = __float_as_uint(f); return (u & 0x80000000u) ? ~u : (u | 0x80000000u); }
; DI void topk_phase(unsigned char* smem_, const bf16_t* __restrict__ qp, const bf16_t* __restrict__ keys, int* __restrict__ eidx, float* __restrict__ gate) {
;     ...
;         for (int i = 0; i < 8; ++i) {
;             const f32x4 sv4 = *(const f32x4*)(S + row * LDS_ + 32 * q + 4 * i);
;             const int ib = 127 - (32 * q + 4 * i);
;             v[4 * i] = (fkey(sv4.x) & ~127u) | (unsigned)ib; v[4 * i + 1] = (fkey(sv4.y) & ~127u) | (unsigned)(ib - 1);
;             v[4 * i + 2] = (fkey(sv4.z) & ~127u) | (unsigned)(ib - 2); v[4 * i + 3] = (fkey(sv4.w) & ~127u) | (unsigned)(ib - 3);
	v_and_b32_e32 v10, 0xffffff80, v10
	v_sub_u32_e32 v10, v10, v183
	v_bitop3_b32 v11, v116, s98, v11 bitop3:0x56
	v_ashrrev_i32_e32 v116, 31, v12


; DI unsigned fkey(float f) { const unsigned u = __float_as_uint(f); return (u & 0x80000000u) ? ~u : (u | 0x80000000u); }
; DI void topk_phase(unsigned char* smem_, const bf16_t* __restrict__ qp, const bf16_t* __restrict__ keys, int* __restrict__ eidx, float* __restrict__ gate) {
;     ...
;         for (int i = 0; i < 8; ++i) {
;             const f32x4 sv4 = *(const f32x4*)(S + row * LDS_ + 32 * q + 4 * i);
;             const int ib = 127 - (32 * q + 4 * i);
;             v[4 * i] = (fkey(sv4.x) & ~127u) | (unsigned)ib; v[4 * i + 1] = (fkey(sv4.y) & ~127u) | (unsigned)(ib - 1);
;             v[4 * i + 2] = (fkey(sv4.z) & ~127u) | (unsigned)(ib - 2); v[4 * i + 3] = (fkey(sv4.w) & ~127u) | (unsigned)(ib - 3);
	v_and_b32_e32 v11, 0xffffff80, v11
	v_sub_u32_e32 v11, v11, v183
	v_bitop3_b32 v12, v116, s98, v12 bitop3:0x56
	v_ashrrev_i32_e32 v116, 31, v13


; template <int N> DI void bitonic_sort_desc(unsigned (&v)[N]) {
; #pragma unroll
;     for (int k = 2; k <= N; k <<= 1)
; #pragma unroll
;         for (int j = k >> 1; j > 0; j >>= 1)
; #pragma unroll
;             for (int i = 0; i < N; ++i) { const int l = i ^ j; if (l > i) { if ((i & k) == 0) cswap(v[i], v[l]); else cswap(v[l], v[i]); } }
	v_and_b32_e32 v12, 0xffffff80, v12
	v_sub_u32_e32 v12, v12, v183
	v_bitop3_b32 v13, v116, s98, v13 bitop3:0x56
	v_and_b32_e32 v13, 0xffffff80, v13
	v_sub_u32_e32 v13, v13, v183
	v_add_u32_e32 v31, 0x7c, v31
	v_add_u32_e32 v10, 0x7f, v10
	v_add_u32_e32 v11, 0x7e, v11
	v_add_u32_e32 v12, 0x7d, v12
	v_add_u32_e32 v13, 0x7c, v13
	v_max_u32_e32 v116, v0, v1
	v_min_u32_e32 v0, v0, v1
	v_max_u32_e32 v1, v3, v2
	v_min_u32_e32 v2, v3, v2
	v_max_u32_e32 v3, v4, v5
	v_min_u32_e32 v4, v4, v5
	v_max_u32_e32 v5, v7, v6
	v_min_u32_e32 v6, v7, v6
	v_max_u32_e32 v7, v8, v9
	v_min_u32_e32 v8, v8, v9
	v_max_u32_e32 v9, v17, v16
	v_min_u32_e32 v16, v17, v16
	v_max_u32_e32 v17, v18, v19
	v_min_u32_e32 v18, v18, v19
	v_max_u32_e32 v19, v15, v14
	v_min_u32_e32 v14, v15, v14
	v_max_u32_e32 v15, v20, v21
	v_min_u32_e32 v20, v20, v21
	v_max_u32_e32 v21, v23, v22
	v_min_u32_e32 v22, v23, v22
	v_max_u32_e32 v23, v24, v25
	v_min_u32_e32 v24, v24, v25
	v_max_u32_e32 v25, v27, v26
	v_min_u32_e32 v26, v27, v26
	v_max_u32_e32 v27, v28, v29
	v_min_u32_e32 v28, v28, v29
	v_max_u32_e32 v29, v31, v30
	v_min_u32_e32 v30, v31, v30
	v_max_u32_e32 v31, v10, v11
	v_min_u32_e32 v10, v10, v11
	v_max_u32_e32 v11, v13, v12
	v_min_u32_e32 v12, v13, v12
	v_max_u32_e32 v13, v116, v2
	v_min_u32_e32 v2, v116, v2
	v_max_u32_e32 v116, v0, v1
	v_min_u32_e32 v0, v0, v1
	v_max_u32_e32 v1, v6, v3
	v_min_u32_e32 v3, v6, v3
	v_max_u32_e32 v6, v5, v4
	v_min_u32_e32 v4, v5, v4
	v_max_u32_e32 v5, v7, v16
	v_min_u32_e32 v7, v7, v16
	v_max_u32_e32 v16, v8, v9
	v_min_u32_e32 v8, v8, v9
	v_max_u32_e32 v9, v14, v17
	v_min_u32_e32 v14, v14, v17
	v_max_u32_e32 v17, v19, v18
	v_min_u32_e32 v18, v19, v18
	v_max_u32_e32 v19, v15, v22
	v_min_u32_e32 v15, v15, v22
	v_max_u32_e32 v22, v20, v21
	v_min_u32_e32 v20, v20, v21
	v_max_u32_e32 v21, v26, v23
	v_min_u32_e32 v23, v26, v23
	v_max_u32_e32 v26, v25, v24
	v_min_u32_e32 v24, v25, v24
	v_max_u32_e32 v25, v27, v30
	v_min_u32_e32 v27, v27, v30
	v_max_u32_e32 v30, v28, v29
	v_min_u32_e32 v28, v28, v29
	v_max_u32_e32 v29, v12, v31
	v_min_u32_e32 v12, v12, v31
	v_max_u32_e32 v31, v11, v10
	v_min_u32_e32 v10, v11, v10
	v_max_u32_e32 v11, v13, v116
	v_min_u32_e32 v13, v13, v116
	v_max_u32_e32 v116, v2, v0
	v_min_u32_e32 v0, v2, v0
	v_max_u32_e32 v2, v4, v3
	v_min_u32_e32 v3, v4, v3
	v_max_u32_e32 v4, v6, v1
	v_min_u32_e32 v1, v6, v1
	v_max_u32_e32 v6, v5, v16
	v_min_u32_e32 v5, v5, v16
	v_max_u32_e32 v16, v7, v8
	v_min_u32_e32 v7, v7, v8
	v_max_u32_e32 v8, v18, v14
	v_min_u32_e32 v14, v18, v14
	v_max_u32_e32 v18, v17, v9
	v_min_u32_e32 v9, v17, v9
	v_max_u32_e32 v17, v19, v22
	v_min_u32_e32 v19, v19, v22
	v_max_u32_e32 v22, v15, v20
	v_min_u32_e32 v15, v15, v20
	v_max_u32_e32 v20, v24, v23
	v_min_u32_e32 v23, v24, v23
	v_max_u32_e32 v24, v26, v21
	v_min_u32_e32 v21, v26, v21
	v_max_u32_e32 v26, v25, v30
	v_min_u32_e32 v25, v25, v30
	v_max_u32_e32 v30, v27, v28
	v_min_u32_e32 v27, v27, v28
	v_max_u32_e32 v28, v10, v12
	v_min_u32_e32 v10, v10, v12
	v_max_u32_e32 v12, v31, v29
	v_min_u32_e32 v29, v31, v29
	v_max_u32_e32 v31, v11, v3
	v_min_u32_e32 v3, v11, v3
	v_max_u32_e32 v11, v13, v2
	v_min_u32_e32 v2, v13, v2
	v_max_u32_e32 v13, v116, v1
	v_min_u32_e32 v1, v116, v1
	v_max_u32_e32 v116, v0, v4
	v_min_u32_e32 v0, v0, v4
	v_max_u32_e32 v4, v14, v6
	v_min_u32_e32 v6, v14, v6
	v_max_u32_e32 v14, v8, v5
	v_min_u32_e32 v5, v8, v5
	v_max_u32_e32 v8, v9, v16
	v_min_u32_e32 v9, v9, v16
	v_max_u32_e32 v16, v18, v7
	v_min_u32_e32 v7, v18, v7
	v_max_u32_e32 v18, v17, v23
	v_min_u32_e32 v17, v17, v23
	v_max_u32_e32 v23, v19, v20
	v_min_u32_e32 v19, v19, v20
	v_max_u32_e32 v20, v22, v21
	v_min_u32_e32 v21, v22, v21
	v_max_u32_e32 v22, v15, v24
	v_min_u32_e32 v15, v15, v24
	v_max_u32_e32 v24, v10, v26
	v_min_u32_e32 v10, v10, v26
	v_max_u32_e32 v26, v28, v25
	v_min_u32_e32 v25, v28, v25
	v_max_u32_e32 v28, v29, v30
	v_min_u32_e32 v29, v29, v30
	v_max_u32_e32 v30, v12, v27
	v_min_u32_e32 v12, v12, v27
	v_max_u32_e32 v27, v31, v13
	v_min_u32_e32 v13, v31, v13
	v_max_u32_e32 v31, v11, v116
	v_min_u32_e32 v11, v11, v116
	v_max_u32_e32 v116, v3, v1
	v_min_u32_e32 v1, v3, v1
	v_max_u32_e32 v3, v2, v0
	v_min_u32_e32 v0, v2, v0
	v_max_u32_e32 v2, v9, v6
	v_min_u32_e32 v6, v9, v6
	v_max_u32_e32 v9, v7, v5
	v_min_u32_e32 v5, v7, v5
	v_max_u32_e32 v7, v8, v4
	v_min_u32_e32 v4, v8, v4
	v_max_u32_e32 v8, v16, v14
	v_min_u32_e32 v14, v16, v14
	v_max_u32_e32 v16, v18, v20
	v_min_u32_e32 v18, v18, v20
	v_max_u32_e32 v20, v23, v22
	v_min_u32_e32 v22, v23, v22
	v_max_u32_e32 v23, v17, v21
	v_min_u32_e32 v17, v17, v21
	v_max_u32_e32 v21, v19, v15
	v_min_u32_e32 v15, v19, v15
	v_max_u32_e32 v19, v29, v10
	v_min_u32_e32 v10, v29, v10
	v_max_u32_e32 v29, v12, v25
	v_min_u32_e32 v12, v12, v25
	v_max_u32_e32 v25, v28, v24
	v_min_u32_e32 v24, v28, v24
	v_max_u32_e32 v28, v30, v26
	v_min_u32_e32 v26, v30, v26
	v_max_u32_e32 v30, v27, v31
	v_min_u32_e32 v27, v27, v31
	v_max_u32_e32 v31, v13, v11
	v_min_u32_e32 v11, v13, v11
	v_max_u32_e32 v13, v116, v3
	v_min_u32_e32 v3, v116, v3
	v_max_u32_e32 v116, v1, v0
	v_min_u32_e32 v0, v1, v0
	v_max_u32_e32 v1, v5, v6
	v_min_u32_e32 v5, v5, v6
	v_max_u32_e32 v6, v9, v2
	v_min_u32_e32 v2, v9, v2
	v_max_u32_e32 v9, v14, v4
	v_min_u32_e32 v4, v14, v4
	v_max_u32_e32 v14, v8, v7
	v_min_u32_e32 v7, v8, v7
	v_max_u32_e32 v8, v16, v20
	v_min_u32_e32 v16, v16, v20
	v_max_u32_e32 v20, v18, v22
	v_min_u32_e32 v18, v18, v22
	v_max_u32_e32 v22, v23, v21
	v_min_u32_e32 v21, v23, v21
	v_max_u32_e32 v23, v17, v15
	v_min_u32_e32 v15, v17, v15
	v_max_u32_e32 v17, v12, v10
	v_min_u32_e32 v10, v12, v10
	v_max_u32_e32 v12, v29, v19
	v_min_u32_e32 v19, v29, v19
	v_max_u32_e32 v29, v26, v24
; template <int N> DI void bitonic_sort_desc(unsigned (&v)[N]) {
; #pragma unroll
;     for (int k = 2; k <= N; k <<= 1)
; #pragma unroll
;         for (int j = k >> 1; j > 0; j >>= 1)
; #pragma unroll
;             for (int i = 0; i < N; ++i) { const int l = i ^ j; if (l > i) { if ((i & k) == 0) cswap(v[i], v[l]); else cswap(v[l], v[i]); } }
; }
; DI void merge_top16(unsigned (&v)[16], int st) {
;     unsigned x[16];
; #pragma unroll
;     for (int i = 0; i < 16; ++i) x[i] = (unsigned)__shfl_xor((int)v[15 - i], st);
; #pragma unroll
;     for (int i = 0; i < 16; ++i) v[i] = max(v[i], x[i]);
; #pragma unroll
;     for (int j = 8; j > 0; j >>= 1)
; #pragma unroll
;         for (int i = 0; i < 16; ++i) { const int l = i ^ j; if (l > i) cswap(v[i], v[l]); }
; }
	v_min_u32_e32 v24, v26, v24
	v_max_u32_e32 v26, v28, v25
	v_min_u32_e32 v25, v28, v25
	v_max_u32_e32 v28, v30, v5
	v_min_u32_e32 v5, v30, v5
	v_max_u32_e32 v30, v27, v1
	v_min_u32_e32 v1, v27, v1
	v_max_u32_e32 v27, v31, v2
	v_min_u32_e32 v2, v31, v2
	v_max_u32_e32 v31, v11, v6
	v_min_u32_e32 v6, v11, v6
	v_max_u32_e32 v11, v13, v4
	v_min_u32_e32 v4, v13, v4
	v_max_u32_e32 v13, v3, v9
	v_min_u32_e32 v3, v3, v9
	v_max_u32_e32 v9, v116, v7
	v_min_u32_e32 v7, v116, v7
	v_max_u32_e32 v116, v0, v14
	v_min_u32_e32 v0, v0, v14
	v_max_u32_e32 v14, v10, v8
	v_min_u32_e32 v8, v10, v8
	v_max_u32_e32 v10, v17, v16
	v_min_u32_e32 v16, v17, v16
	v_max_u32_e32 v17, v19, v20
	v_min_u32_e32 v19, v19, v20
	v_max_u32_e32 v20, v12, v18
	v_min_u32_e32 v12, v12, v18
	v_max_u32_e32 v18, v24, v22
	v_min_u32_e32 v22, v24, v22
	v_max_u32_e32 v24, v29, v21
	v_min_u32_e32 v21, v29, v21
	v_max_u32_e32 v29, v25, v23
	v_min_u32_e32 v23, v25, v23
	v_max_u32_e32 v25, v26, v15
	v_min_u32_e32 v15, v26, v15
	v_max_u32_e32 v26, v28, v11
	v_min_u32_e32 v11, v28, v11
	v_max_u32_e32 v28, v30, v13
	v_min_u32_e32 v13, v30, v13
	v_max_u32_e32 v30, v27, v9
	v_min_u32_e32 v9, v27, v9
	v_max_u32_e32 v27, v31, v116
	v_min_u32_e32 v31, v31, v116
	v_max_u32_e32 v116, v5, v4
	v_min_u32_e32 v4, v5, v4
	v_max_u32_e32 v5, v1, v3
	v_min_u32_e32 v1, v1, v3
	v_max_u32_e32 v3, v2, v7
	v_min_u32_e32 v2, v2, v7
	v_max_u32_e32 v7, v6, v0
	v_min_u32_e32 v0, v6, v0
	v_max_u32_e32 v6, v22, v8
	v_min_u32_e32 v8, v22, v8
	v_max_u32_e32 v22, v21, v16
	v_min_u32_e32 v16, v21, v16
	v_max_u32_e32 v21, v23, v19
	v_min_u32_e32 v19, v23, v19
	v_max_u32_e32 v23, v15, v12
	v_min_u32_e32 v12, v15, v12
	v_max_u32_e32 v15, v18, v14
	v_min_u32_e32 v14, v18, v14
	v_max_u32_e32 v18, v24, v10
	v_min_u32_e32 v10, v24, v10
	v_max_u32_e32 v24, v29, v17
	v_min_u32_e32 v17, v29, v17
	v_max_u32_e32 v29, v25, v20
	v_min_u32_e32 v20, v25, v20
	v_max_u32_e32 v25, v26, v30
	v_min_u32_e32 v26, v26, v30
	v_max_u32_e32 v30, v28, v27
	v_min_u32_e32 v27, v28, v27
	v_max_u32_e32 v28, v11, v9
	v_min_u32_e32 v9, v11, v9
	v_max_u32_e32 v11, v13, v31
	v_min_u32_e32 v13, v13, v31
	v_max_u32_e32 v31, v116, v3
	v_min_u32_e32 v3, v116, v3
	v_max_u32_e32 v116, v5, v7
	v_min_u32_e32 v5, v5, v7
	v_max_u32_e32 v7, v4, v2
	v_min_u32_e32 v2, v4, v2
	v_max_u32_e32 v4, v1, v0
	v_min_u32_e32 v0, v1, v0
	v_max_u32_e32 v1, v19, v8
	v_min_u32_e32 v8, v19, v8
	v_max_u32_e32 v19, v12, v16
	v_min_u32_e32 v12, v12, v16
	v_max_u32_e32 v16, v21, v6
	v_min_u32_e32 v6, v21, v6
	v_max_u32_e32 v21, v23, v22
	v_min_u32_e32 v22, v23, v22
	v_max_u32_e32 v23, v17, v14
	v_min_u32_e32 v14, v17, v14
	v_max_u32_e32 v17, v20, v10
	v_min_u32_e32 v10, v20, v10
	v_max_u32_e32 v20, v24, v15
	v_min_u32_e32 v15, v24, v15
	v_max_u32_e32 v24, v29, v18
	v_min_u32_e32 v18, v29, v18
	v_min_u32_e32 v29, v25, v30
	v_min_u32_e32 v117, v26, v27
	v_min_u32_e32 v118, v28, v11
	v_min_u32_e32 v119, v9, v13
	v_min_u32_e32 v120, v31, v116
	v_min_u32_e32 v121, v3, v5
	v_min_u32_e32 v122, v7, v4
	v_min_u32_e32 v123, v2, v0
	v_min_u32_e32 v124, v12, v8
	v_min_u32_e32 v125, v19, v1
	v_min_u32_e32 v126, v22, v6
	v_min_u32_e32 v127, v21, v16
	v_min_u32_e32 v142, v10, v14
	v_min_u32_e32 v143, v17, v23
	v_min_u32_e32 v144, v18, v15
	v_min_u32_e32 v145, v24, v20
	v_max3_u32 v25, v25, v30, v124
	v_max3_u32 v8, v29, v12, v8
	v_max3_u32 v12, v26, v27, v125
	v_max3_u32 v1, v117, v19, v1
	v_max3_u32 v11, v28, v11, v126
	v_max3_u32 v6, v118, v22, v6
	v_max3_u32 v9, v9, v13, v127
	v_max3_u32 v13, v119, v21, v16
	v_max3_u32 v16, v31, v116, v142
	v_max3_u32 v10, v120, v10, v14
	v_max3_u32 v3, v3, v5, v143
	v_max3_u32 v5, v121, v17, v23
	v_max3_u32 v4, v7, v4, v144
	v_max3_u32 v7, v122, v18, v15
	v_max3_u32 v0, v2, v0, v145
	v_max3_u32 v2, v123, v24, v20
	v_max_u32_e32 v14, v25, v16
	v_min_u32_e32 v15, v25, v16
	v_max_u32_e32 v16, v8, v10
	v_min_u32_e32 v8, v8, v10
	v_max_u32_e32 v10, v12, v3
	v_min_u32_e32 v3, v12, v3
	v_max_u32_e32 v12, v1, v5
	v_min_u32_e32 v1, v1, v5
	v_max_u32_e32 v5, v11, v4
	v_min_u32_e32 v4, v11, v4
	v_max_u32_e32 v11, v6, v7
	v_min_u32_e32 v6, v6, v7
	v_max_u32_e32 v7, v9, v0
	v_min_u32_e32 v0, v9, v0
	v_max_u32_e32 v9, v13, v2
	v_min_u32_e32 v2, v13, v2
	v_max_u32_e32 v13, v14, v5
	v_min_u32_e32 v5, v14, v5
	v_max_u32_e32 v14, v16, v11
	v_min_u32_e32 v11, v16, v11
	v_max_u32_e32 v16, v10, v7
	v_min_u32_e32 v7, v10, v7
	v_max_u32_e32 v10, v12, v9
	v_min_u32_e32 v9, v12, v9
	v_max_u32_e32 v12, v15, v4
	v_min_u32_e32 v4, v15, v4
	v_max_u32_e32 v15, v8, v6
	v_min_u32_e32 v6, v8, v6
	v_max_u32_e32 v8, v3, v0
	v_min_u32_e32 v0, v3, v0
	v_max_u32_e32 v3, v1, v2
	v_min_u32_e32 v1, v1, v2
	v_max_u32_e32 v2, v13, v16
	v_min_u32_e32 v13, v13, v16
	v_max_u32_e32 v16, v14, v10
	v_min_u32_e32 v10, v14, v10
	v_max_u32_e32 v14, v5, v7
	v_min_u32_e32 v5, v5, v7
	v_max_u32_e32 v7, v11, v9
	v_min_u32_e32 v9, v11, v9
	v_max_u32_e32 v11, v12, v8
	v_min_u32_e32 v8, v12, v8
	v_max_u32_e32 v12, v15, v3
	v_min_u32_e32 v3, v15, v3
	v_max_u32_e32 v15, v4, v0
	v_min_u32_e32 v0, v4, v0
	v_max_u32_e32 v4, v6, v1
	v_min_u32_e32 v1, v6, v1
	v_max_u32_e32 v6, v2, v16
	v_min_u32_e32 v2, v2, v16
	v_max_u32_e32 v16, v13, v10
	v_min_u32_e32 v10, v13, v10
	v_max_u32_e32 v13, v14, v7
	v_min_u32_e32 v7, v14, v7
	v_max_u32_e32 v14, v5, v9
	v_min_u32_e32 v5, v5, v9
	v_max_u32_e32 v9, v11, v12
	v_min_u32_e32 v11, v11, v12
	v_max_u32_e32 v12, v8, v3
	v_min_u32_e32 v3, v8, v3
	v_max_u32_e32 v8, v15, v4
	v_min_u32_e32 v4, v15, v4
	v_max_u32_e32 v15, v0, v1
	v_min_u32_e32 v0, v0, v1
	s_nop 1
	v_mov_b32_dpp v1, v0 quad_perm:[1,0,3,2] row_mask:0xf bank_mask:0xf
	v_mov_b32_dpp v17, v15 quad_perm:[1,0,3,2] row_mask:0xf bank_mask:0xf
	v_mov_b32_dpp v18, v4 quad_perm:[1,0,3,2] row_mask:0xf bank_mask:0xf
	v_mov_b32_dpp v19, v8 quad_perm:[1,0,3,2] row_mask:0xf bank_mask:0xf
	v_mov_b32_dpp v20, v3 quad_perm:[1,0,3,2] row_mask:0xf bank_mask:0xf
	v_mov_b32_dpp v21, v12 quad_perm:[1,0,3,2] row_mask:0xf bank_mask:0xf
	v_mov_b32_dpp v22, v11 quad_perm:[1,0,3,2] row_mask:0xf bank_mask:0xf
	v_mov_b32_dpp v23, v9 quad_perm:[1,0,3,2] row_mask:0xf bank_mask:0xf
	v_mov_b32_dpp v24, v5 quad_perm:[1,0,3,2] row_mask:0xf bank_mask:0xf
	v_mov_b32_dpp v25, v14 quad_perm:[1,0,3,2] row_mask:0xf bank_mask:0xf
	v_mov_b32_dpp v26, v7 quad_perm:[1,0,3,2] row_mask:0xf bank_mask:0xf
	v_mov_b32_dpp v27, v13 quad_perm:[1,0,3,2] row_mask:0xf bank_mask:0xf
	v_mov_b32_dpp v28, v10 quad_perm:[1,0,3,2] row_mask:0xf bank_mask:0xf
	v_mov_b32_dpp v29, v16 quad_perm:[1,0,3,2] row_mask:0xf bank_mask:0xf
	v_mov_b32_dpp v30, v2 quad_perm:[1,0,3,2] row_mask:0xf bank_mask:0xf
	v_mov_b32_dpp v31, v6 quad_perm:[1,0,3,2] row_mask:0xf bank_mask:0xf
	s_waitcnt lgkmcnt(0)
; DI void merge_top16(unsigned (&v)[16], int st) {
;     unsigned x[16];
; #pragma unroll
;     for (int i = 0; i < 16; ++i) x[i] = (unsigned)__shfl_xor((int)v[15 - i], st);
; #pragma unroll
;     for (int i = 0; i < 16; ++i) v[i] = max(v[i], x[i]);
; #pragma unroll
;     for (int j = 8; j > 0; j >>= 1)
; #pragma unroll
;         for (int i = 0; i < 16; ++i) { const int l = i ^ j; if (l > i) cswap(v[i], v[l]); }
; }
; DI void topk_phase(unsigned char* smem_, const bf16_t* __restrict__ qp, const bf16_t* __restrict__ keys, int* __restrict__ eidx, float* __restrict__ gate) {
;     ...
;         for (int i = 0; i < 16; ++i) t16[i] = v[i];
;         merge_top16(t16, 1);
;         merge_top16(t16, 2);
; #pragma unroll
;         for (int i = 0; i < 16; ++i) if ((i >> 2) == q) { const int idx = 127 - (int)(t16[i] & 127u); SI[row * 32 + 16 * p + i] = idx; SV[row * 32 + 16 * p + i] = S[row * LDS_ + idx]; }
	v_max_u32_e32 v1, v6, v1
	v_max_u32_e32 v2, v2, v17
	v_max_u32_e32 v6, v16, v18
	v_max_u32_e32 v10, v10, v19
	v_max_u32_e32 v13, v13, v20
	v_max_u32_e32 v7, v7, v21
	v_max_u32_e32 v14, v14, v22
	v_max_u32_e32 v5, v5, v23
	v_max_u32_e32 v9, v9, v24
	v_max_u32_e32 v11, v11, v25
	v_max_u32_e32 v12, v12, v26
	v_max_u32_e32 v3, v3, v27
	v_max_u32_e32 v8, v8, v28
	v_max_u32_e32 v4, v4, v29
	v_max_u32_e32 v15, v15, v30
	v_max_u32_e32 v0, v0, v31
	v_max_u32_e32 v16, v1, v9
	v_min_u32_e32 v1, v1, v9
	v_max_u32_e32 v9, v2, v11
	v_min_u32_e32 v2, v2, v11
	v_max_u32_e32 v11, v6, v12
	v_min_u32_e32 v6, v6, v12
	v_max_u32_e32 v12, v10, v3
	v_min_u32_e32 v3, v10, v3
	v_max_u32_e32 v10, v13, v8
	v_min_u32_e32 v8, v13, v8
	v_max_u32_e32 v13, v7, v4
	v_min_u32_e32 v4, v7, v4
	v_max_u32_e32 v7, v14, v15
	v_min_u32_e32 v14, v14, v15
	v_max_u32_e32 v15, v5, v0
	v_min_u32_e32 v0, v5, v0
	v_max_u32_e32 v5, v16, v10
	v_min_u32_e32 v10, v16, v10
	v_max_u32_e32 v16, v9, v13
	v_min_u32_e32 v9, v9, v13
	v_max_u32_e32 v13, v11, v7
	v_min_u32_e32 v7, v11, v7
	v_max_u32_e32 v11, v12, v15
	v_min_u32_e32 v12, v12, v15
	v_max_u32_e32 v15, v1, v8
	v_min_u32_e32 v1, v1, v8
	v_max_u32_e32 v8, v2, v4
	v_min_u32_e32 v2, v2, v4
	v_max_u32_e32 v4, v6, v14
	v_min_u32_e32 v6, v6, v14
	v_max_u32_e32 v14, v3, v0
	v_min_u32_e32 v0, v3, v0
	v_max_u32_e32 v3, v5, v13
	v_min_u32_e32 v5, v5, v13
	v_max_u32_e32 v13, v16, v11
	v_min_u32_e32 v11, v16, v11
	v_max_u32_e32 v16, v10, v7
	v_min_u32_e32 v7, v10, v7
	v_max_u32_e32 v10, v9, v12
	v_min_u32_e32 v9, v9, v12
	v_max_u32_e32 v12, v15, v4
	v_min_u32_e32 v4, v15, v4
	v_max_u32_e32 v15, v8, v14
	v_min_u32_e32 v8, v8, v14
	v_max_u32_e32 v14, v1, v6
	v_min_u32_e32 v1, v1, v6
	v_max_u32_e32 v6, v2, v0
	v_min_u32_e32 v0, v2, v0
	v_max_u32_e32 v2, v3, v13
	v_min_u32_e32 v3, v3, v13
	v_max_u32_e32 v13, v5, v11
	v_min_u32_e32 v5, v5, v11
	v_max_u32_e32 v11, v16, v10
	v_min_u32_e32 v10, v16, v10
	v_max_u32_e32 v16, v7, v9
	v_min_u32_e32 v7, v7, v9
	v_max_u32_e32 v9, v12, v15
	v_min_u32_e32 v12, v12, v15
	v_max_u32_e32 v15, v4, v8
	v_min_u32_e32 v17, v4, v8
	v_max_u32_e32 v18, v14, v6
	v_min_u32_e32 v14, v14, v6
	v_max_u32_e32 v19, v1, v0
	v_min_u32_e32 v20, v1, v0
	s_nop 1
	v_mov_b32_dpp v0, v20 quad_perm:[2,3,0,1] row_mask:0xf bank_mask:0xf
	v_mov_b32_dpp v1, v19 quad_perm:[2,3,0,1] row_mask:0xf bank_mask:0xf
	v_mov_b32_dpp v4, v14 quad_perm:[2,3,0,1] row_mask:0xf bank_mask:0xf
	v_mov_b32_dpp v6, v18 quad_perm:[2,3,0,1] row_mask:0xf bank_mask:0xf
	v_mov_b32_dpp v8, v17 quad_perm:[2,3,0,1] row_mask:0xf bank_mask:0xf
	v_mov_b32_dpp v21, v15 quad_perm:[2,3,0,1] row_mask:0xf bank_mask:0xf
	v_mov_b32_dpp v22, v12 quad_perm:[2,3,0,1] row_mask:0xf bank_mask:0xf
	v_mov_b32_dpp v23, v9 quad_perm:[2,3,0,1] row_mask:0xf bank_mask:0xf
	v_mov_b32_dpp v24, v7 quad_perm:[2,3,0,1] row_mask:0xf bank_mask:0xf
	v_mov_b32_dpp v25, v16 quad_perm:[2,3,0,1] row_mask:0xf bank_mask:0xf
	v_mov_b32_dpp v26, v10 quad_perm:[2,3,0,1] row_mask:0xf bank_mask:0xf
	v_mov_b32_dpp v27, v11 quad_perm:[2,3,0,1] row_mask:0xf bank_mask:0xf
	v_mov_b32_dpp v28, v5 quad_perm:[2,3,0,1] row_mask:0xf bank_mask:0xf
	v_mov_b32_dpp v29, v13 quad_perm:[2,3,0,1] row_mask:0xf bank_mask:0xf
	v_mov_b32_dpp v30, v3 quad_perm:[2,3,0,1] row_mask:0xf bank_mask:0xf
	v_mov_b32_dpp v31, v2 quad_perm:[2,3,0,1] row_mask:0xf bank_mask:0xf
	s_waitcnt lgkmcnt(0)
	v_max_u32_e32 v0, v2, v0
	v_max_u32_e32 v1, v3, v1
	v_max_u32_e32 v2, v13, v4
	v_max_u32_e32 v3, v5, v6
	v_max_u32_e32 v4, v11, v8
	v_max_u32_e32 v5, v10, v21
	v_max_u32_e32 v6, v16, v22
	v_max_u32_e32 v7, v7, v23
	v_max_u32_e32 v8, v9, v24
	v_max_u32_e32 v9, v12, v25
	v_max_u32_e32 v10, v15, v26
	v_max_u32_e32 v11, v17, v27
	v_max_u32_e32 v12, v18, v28
	v_max_u32_e32 v13, v14, v29
	v_max_u32_e32 v14, v19, v30
	v_max_u32_e32 v15, v20, v31
	v_max_u32_e32 v16, v0, v8
	v_max_u32_e32 v17, v1, v9
	v_max_u32_e32 v18, v2, v10
	v_max_u32_e32 v19, v3, v11
	v_max_u32_e32 v20, v4, v12
	v_max_u32_e32 v21, v5, v13
	v_max_u32_e32 v22, v6, v14
	v_max_u32_e32 v23, v7, v15
	s_and_saveexec_b64 s[0:1], s[4:5]
	s_cbranch_execz .LBB0_59
	v_max_u32_e32 v24, v16, v20
	v_max_u32_e32 v25, v18, v22
	v_max_u32_e32 v27, v17, v21
	v_max_u32_e32 v28, v19, v23
	v_min_u32_e32 v26, v24, v25
	v_min_u32_e32 v29, v27, v28
	v_max_u32_e32 v24, v24, v25
	v_max_u32_e32 v25, v27, v28
	v_min_u32_e32 v30, v26, v29
	v_max_u32_e32 v29, v26, v29
	v_min_u32_e32 v26, v24, v25
	v_max_u32_e32 v24, v24, v25
	v_xor_b32_e32 v25, -1, v26
	v_xor_b32_e32 v24, -1, v24
	v_and_b32_e32 v25, 0x7f, v25
	v_and_b32_e32 v24, 0x7f, v24
	v_lshl_add_u32 v26, v24, 2, v169
	v_lshl_add_u32 v27, v25, 2, v169
	ds_read_b32 v26, v26 offset:17408
	ds_read_b32 v27, v27 offset:17408
	v_xor_b32_e32 v28, -1, v29
	s_waitcnt lgkmcnt(0)
	ds_write_b64 v175, v[26:27] offset:53248
	v_xor_b32_e32 v26, -1, v30
	v_and_b32_e32 v27, 0x7f, v26
	v_and_b32_e32 v26, 0x7f, v28
	v_lshl_add_u32 v28, v26, 2, v169
	ds_write_b128 v184, v[24:27] offset:61440
	v_lshl_add_u32 v24, v27, 2, v169
	ds_read_b32 v28, v28 offset:17408
	ds_read_b32 v29, v24 offset:17408
	s_waitcnt lgkmcnt(0)
	ds_write_b64 v184, v[28:29] offset:53256

; DI unsigned fkey(float f) { const unsigned u = __float_as_uint(f); return (u & 0x80000000u) ? ~u : (u | 0x80000000u); }
; DI void topk_phase(unsigned char* smem_, const bf16_t* __restrict__ qp, const bf16_t* __restrict__ keys, int* __restrict__ eidx, float* __restrict__ gate) {
;     ...
;         for (int i = 0; i < 8; ++i) {
;             const f32x4 sv4 = *(const f32x4*)(S + row * LDS_ + 32 * q + 4 * i);
;             const int ib = 127 - (32 * q + 4 * i);
;             v[4 * i] = (fkey(sv4.x) & ~127u) | (unsigned)ib; v[4 * i + 1] = (fkey(sv4.y) & ~127u) | (unsigned)(ib - 1);
;             v[4 * i + 2] = (fkey(sv4.z) & ~127u) | (unsigned)(ib - 2); v[4 * i + 3] = (fkey(sv4.w) & ~127u) | (unsigned)(ib - 3);
.LBB0_67:
	ds_read_b128 v[0:3], v171 offset:17408
	ds_read_b128 v[4:7], v171 offset:17424
	ds_read_b128 v[8:11], v171 offset:17440
	ds_read_b128 v[12:15], v171 offset:17456
	s_waitcnt lgkmcnt(3)
	v_ashrrev_i32_e32 v16, 31, v0


; DI unsigned fkey(float f) { const unsigned u = __float_as_uint(f); return (u & 0x80000000u) ? ~u : (u | 0x80000000u); }
; DI void topk_phase(unsigned char* smem_, const bf16_t* __restrict__ qp, const bf16_t* __restrict__ keys, int* __restrict__ eidx, float* __restrict__ gate) {
;     ...
;         for (int i = 0; i < 8; ++i) {
;             const f32x4 sv4 = *(const f32x4*)(S + row * LDS_ + 32 * q + 4 * i);
;             const int ib = 127 - (32 * q + 4 * i);
;             v[4 * i] = (fkey(sv4.x) & ~127u) | (unsigned)ib; v[4 * i + 1] = (fkey(sv4.y) & ~127u) | (unsigned)(ib - 1);
;             v[4 * i + 2] = (fkey(sv4.z) & ~127u) | (unsigned)(ib - 2); v[4 * i + 3] = (fkey(sv4.w) & ~127u) | (unsigned)(ib - 3);
	s_nop 1
	v_bitop3_b32 v0, v16, s98, v0 bitop3:0x56
	v_and_b32_e32 v0, 0xffffff80, v0
	v_sub_u32_e32 v0, v0, v170
	v_add_u32_e32 v16, 0x7f, v0
	v_not_b32_e32 v0, v1
	v_or_b32_e32 v17, 0x80000000, v1
	v_cmp_gt_i32_e32 vcc, 0, v1
	v_ashrrev_i32_e32 v1, 31, v2
	s_nop 0
	v_cndmask_b32_e32 v0, v17, v0, vcc
	v_and_b32_e32 v0, 0xffffff80, v0
	v_sub_u32_e32 v0, v0, v170
	v_add_u32_e32 v17, 0x7e, v0


; DI unsigned fkey(float f) { const unsigned u = __float_as_uint(f); return (u & 0x80000000u) ? ~u : (u | 0x80000000u); }
; DI void topk_phase(unsigned char* smem_, const bf16_t* __restrict__ qp, const bf16_t* __restrict__ keys, int* __restrict__ eidx, float* __restrict__ gate) {
;     ...
;         for (int i = 0; i < 8; ++i) {
;             const f32x4 sv4 = *(const f32x4*)(S + row * LDS_ + 32 * q + 4 * i);
;             const int ib = 127 - (32 * q + 4 * i);
;             v[4 * i] = (fkey(sv4.x) & ~127u) | (unsigned)ib; v[4 * i + 1] = (fkey(sv4.y) & ~127u) | (unsigned)(ib - 1);
;             v[4 * i + 2] = (fkey(sv4.z) & ~127u) | (unsigned)(ib - 2); v[4 * i + 3] = (fkey(sv4.w) & ~127u) | (unsigned)(ib - 3);
	s_nop 1
	v_bitop3_b32 v0, v1, s98, v2 bitop3:0x56
	v_and_b32_e32 v0, 0xffffff80, v0
	v_sub_u32_e32 v0, v0, v170
	v_add_u32_e32 v18, 0x7d, v0
	v_ashrrev_i32_e32 v0, 31, v3


; DI unsigned fkey(float f) { const unsigned u = __float_as_uint(f); return (u & 0x80000000u) ? ~u : (u | 0x80000000u); }
; DI void topk_phase(unsigned char* smem_, const bf16_t* __restrict__ qp, const bf16_t* __restrict__ keys, int* __restrict__ eidx, float* __restrict__ gate) {
;     ...
;         for (int i = 0; i < 8; ++i) {
;             const f32x4 sv4 = *(const f32x4*)(S + row * LDS_ + 32 * q + 4 * i);
;             const int ib = 127 - (32 * q + 4 * i);
;             v[4 * i] = (fkey(sv4.x) & ~127u) | (unsigned)ib; v[4 * i + 1] = (fkey(sv4.y) & ~127u) | (unsigned)(ib - 1);
;             v[4 * i + 2] = (fkey(sv4.z) & ~127u) | (unsigned)(ib - 2); v[4 * i + 3] = (fkey(sv4.w) & ~127u) | (unsigned)(ib - 3);
	s_nop 1
	v_bitop3_b32 v0, v0, s98, v3 bitop3:0x56
	v_and_b32_e32 v0, 0xffffff80, v0
	v_sub_u32_e32 v0, v0, v170
	v_add_u32_e32 v19, 0x7c, v0
	s_waitcnt lgkmcnt(2)
	v_ashrrev_i32_e32 v0, 31, v4


; DI unsigned fkey(float f) { const unsigned u = __float_as_uint(f); return (u & 0x80000000u) ? ~u : (u | 0x80000000u); }
; DI void topk_phase(unsigned char* smem_, const bf16_t* __restrict__ qp, const bf16_t* __restrict__ keys, int* __restrict__ eidx, float* __restrict__ gate) {
;     ...
;         for (int i = 0; i < 8; ++i) {
;             const f32x4 sv4 = *(const f32x4*)(S + row * LDS_ + 32 * q + 4 * i);
;             const int ib = 127 - (32 * q + 4 * i);
;             v[4 * i] = (fkey(sv4.x) & ~127u) | (unsigned)ib; v[4 * i + 1] = (fkey(sv4.y) & ~127u) | (unsigned)(ib - 1);
;             v[4 * i + 2] = (fkey(sv4.z) & ~127u) | (unsigned)(ib - 2); v[4 * i + 3] = (fkey(sv4.w) & ~127u) | (unsigned)(ib - 3);
	s_nop 1
	v_bitop3_b32 v0, v0, s98, v4 bitop3:0x56
	v_and_b32_e32 v0, 0xffffff80, v0
	v_sub_u32_e32 v0, v0, v177
	v_add_u32_e32 v20, 0x7f, v0
	v_ashrrev_i32_e32 v0, 31, v5


; DI unsigned fkey(float f) { const unsigned u = __float_as_uint(f); return (u & 0x80000000u) ? ~u : (u | 0x80000000u); }
; DI void topk_phase(unsigned char* smem_, const bf16_t* __restrict__ qp, const bf16_t* __restrict__ keys, int* __restrict__ eidx, float* __restrict__ gate) {
;     ...
;         for (int i = 0; i < 8; ++i) {
;             const f32x4 sv4 = *(const f32x4*)(S + row * LDS_ + 32 * q + 4 * i);
;             const int ib = 127 - (32 * q + 4 * i);
;             v[4 * i] = (fkey(sv4.x) & ~127u) | (unsigned)ib; v[4 * i + 1] = (fkey(sv4.y) & ~127u) | (unsigned)(ib - 1);
;             v[4 * i + 2] = (fkey(sv4.z) & ~127u) | (unsigned)(ib - 2); v[4 * i + 3] = (fkey(sv4.w) & ~127u) | (unsigned)(ib - 3);
	s_nop 1
	v_bitop3_b32 v0, v0, s98, v5 bitop3:0x56
	v_and_b32_e32 v0, 0xffffff80, v0
	v_sub_u32_e32 v0, v0, v177
	v_add_u32_e32 v21, 0x7e, v0
	v_ashrrev_i32_e32 v0, 31, v6


; DI unsigned fkey(float f) { const unsigned u = __float_as_uint(f); return (u & 0x80000000u) ? ~u : (u | 0x80000000u); }
; DI void topk_phase(unsigned char* smem_, const bf16_t* __restrict__ qp, const bf16_t* __restrict__ keys, int* __restrict__ eidx, float* __restrict__ gate) {
;     ...
;         for (int i = 0; i < 8; ++i) {
;             const f32x4 sv4 = *(const f32x4*)(S + row * LDS_ + 32 * q + 4 * i);
;             const int ib = 127 - (32 * q + 4 * i);
;             v[4 * i] = (fkey(sv4.x) & ~127u) | (unsigned)ib; v[4 * i + 1] = (fkey(sv4.y) & ~127u) | (unsigned)(ib - 1);
;             v[4 * i + 2] = (fkey(sv4.z) & ~127u) | (unsigned)(ib - 2); v[4 * i + 3] = (fkey(sv4.w) & ~127u) | (unsigned)(ib - 3);
	s_nop 1
	v_bitop3_b32 v0, v0, s98, v6 bitop3:0x56
	v_and_b32_e32 v0, 0xffffff80, v0
	v_sub_u32_e32 v0, v0, v177
	v_add_u32_e32 v22, 0x7d, v0
	v_ashrrev_i32_e32 v0, 31, v7


; DI unsigned fkey(float f) { const unsigned u = __float_as_uint(f); return (u & 0x80000000u) ? ~u : (u | 0x80000000u); }
; DI void topk_phase(unsigned char* smem_, const bf16_t* __restrict__ qp, const bf16_t* __restrict__ keys, int* __restrict__ eidx, float* __restrict__ gate) {
;     ...
;         for (int i = 0; i < 8; ++i) {
;             const f32x4 sv4 = *(const f32x4*)(S + row * LDS_ + 32 * q + 4 * i);
;             const int ib = 127 - (32 * q + 4 * i);
;             v[4 * i] = (fkey(sv4.x) & ~127u) | (unsigned)ib; v[4 * i + 1] = (fkey(sv4.y) & ~127u) | (unsigned)(ib - 1);
;             v[4 * i + 2] = (fkey(sv4.z) & ~127u) | (unsigned)(ib - 2); v[4 * i + 3] = (fkey(sv4.w) & ~127u) | (unsigned)(ib - 3);
	s_nop 1
	v_bitop3_b32 v0, v0, s98, v7 bitop3:0x56
	v_and_b32_e32 v0, 0xffffff80, v0
	v_sub_u32_e32 v0, v0, v177
	v_add_u32_e32 v23, 0x7c, v0
	s_waitcnt lgkmcnt(1)
	v_ashrrev_i32_e32 v0, 31, v8


; DI unsigned fkey(float f) { const unsigned u = __float_as_uint(f); return (u & 0x80000000u) ? ~u : (u | 0x80000000u); }
; DI void topk_phase(unsigned char* smem_, const bf16_t* __restrict__ qp, const bf16_t* __restrict__ keys, int* __restrict__ eidx, float* __restrict__ gate) {
;     ...
;         for (int i = 0; i < 8; ++i) {
;             const f32x4 sv4 = *(const f32x4*)(S + row * LDS_ + 32 * q + 4 * i);
;             const int ib = 127 - (32 * q + 4 * i);
;             v[4 * i] = (fkey(sv4.x) & ~127u) | (unsigned)ib; v[4 * i + 1] = (fkey(sv4.y) & ~127u) | (unsigned)(ib - 1);
;             v[4 * i + 2] = (fkey(sv4.z) & ~127u) | (unsigned)(ib - 2); v[4 * i + 3] = (fkey(sv4.w) & ~127u) | (unsigned)(ib - 3);
	s_nop 1
	v_bitop3_b32 v0, v0, s98, v8 bitop3:0x56
	v_and_b32_e32 v0, 0xffffff80, v0
	v_sub_u32_e32 v0, v0, v178
	v_add_u32_e32 v8, 0x7f, v0
	v_ashrrev_i32_e32 v0, 31, v9


; DI unsigned fkey(float f) { const unsigned u = __float_as_uint(f); return (u & 0x80000000u) ? ~u : (u | 0x80000000u); }
; DI void topk_phase(unsigned char* smem_, const bf16_t* __restrict__ qp, const bf16_t* __restrict__ keys, int* __restrict__ eidx, float* __restrict__ gate) {
;     ...
;         for (int i = 0; i < 8; ++i) {
;             const f32x4 sv4 = *(const f32x4*)(S + row * LDS_ + 32 * q + 4 * i);
;             const int ib = 127 - (32 * q + 4 * i);
;             v[4 * i] = (fkey(sv4.x) & ~127u) | (unsigned)ib; v[4 * i + 1] = (fkey(sv4.y) & ~127u) | (unsigned)(ib - 1);
;             v[4 * i + 2] = (fkey(sv4.z) & ~127u) | (unsigned)(ib - 2); v[4 * i + 3] = (fkey(sv4.w) & ~127u) | (unsigned)(ib - 3);
	s_nop 1
	v_bitop3_b32 v0, v0, s98, v9 bitop3:0x56
	v_and_b32_e32 v0, 0xffffff80, v0
	v_sub_u32_e32 v0, v0, v178
	v_add_u32_e32 v9, 0x7e, v0
	v_ashrrev_i32_e32 v0, 31, v10


; DI unsigned fkey(float f) { const unsigned u = __float_as_uint(f); return (u & 0x80000000u) ? ~u : (u | 0x80000000u); }
; DI void topk_phase(unsigned char* smem_, const bf16_t* __restrict__ qp, const bf16_t* __restrict__ keys, int* __restrict__ eidx, float* __restrict__ gate) {
;     ...
;         for (int i = 0; i < 8; ++i) {
;             const f32x4 sv4 = *(const f32x4*)(S + row * LDS_ + 32 * q + 4 * i);
;             const int ib = 127 - (32 * q + 4 * i);
;             v[4 * i] = (fkey(sv4.x) & ~127u) | (unsigned)ib; v[4 * i + 1] = (fkey(sv4.y) & ~127u) | (unsigned)(ib - 1);
;             v[4 * i + 2] = (fkey(sv4.z) & ~127u) | (unsigned)(ib - 2); v[4 * i + 3] = (fkey(sv4.w) & ~127u) | (unsigned)(ib - 3);
	s_nop 1
	v_bitop3_b32 v0, v0, s98, v10 bitop3:0x56
	v_and_b32_e32 v0, 0xffffff80, v0
	v_sub_u32_e32 v0, v0, v178
	v_add_u32_e32 v10, 0x7d, v0
	v_ashrrev_i32_e32 v0, 31, v11


; DI unsigned fkey(float f) { const unsigned u = __float_as_uint(f); return (u & 0x80000000u) ? ~u : (u | 0x80000000u); }
; DI void topk_phase(unsigned char* smem_, const bf16_t* __restrict__ qp, const bf16_t* __restrict__ keys, int* __restrict__ eidx, float* __restrict__ gate) {
;     ...
;         for (int i = 0; i < 8; ++i) {
;             const f32x4 sv4 = *(const f32x4*)(S + row * LDS_ + 32 * q + 4 * i);
;             const int ib = 127 - (32 * q + 4 * i);
;             v[4 * i] = (fkey(sv4.x) & ~127u) | (unsigned)ib; v[4 * i + 1] = (fkey(sv4.y) & ~127u) | (unsigned)(ib - 1);
;             v[4 * i + 2] = (fkey(sv4.z) & ~127u) | (unsigned)(ib - 2); v[4 * i + 3] = (fkey(sv4.w) & ~127u) | (unsigned)(ib - 3);
	s_nop 1
	v_bitop3_b32 v0, v0, s98, v11 bitop3:0x56
	v_and_b32_e32 v0, 0xffffff80, v0
	v_sub_u32_e32 v0, v0, v178
	v_add_u32_e32 v11, 0x7c, v0
	s_waitcnt lgkmcnt(0)
	v_ashrrev_i32_e32 v0, 31, v12


; DI unsigned fkey(float f) { const unsigned u = __float_as_uint(f); return (u & 0x80000000u) ? ~u : (u | 0x80000000u); }
; DI void topk_phase(unsigned char* smem_, const bf16_t* __restrict__ qp, const bf16_t* __restrict__ keys, int* __restrict__ eidx, float* __restrict__ gate) {
;     ...
;         for (int i = 0; i < 8; ++i) {
;             const f32x4 sv4 = *(const f32x4*)(S + row * LDS_ + 32 * q + 4 * i);
;             const int ib = 127 - (32 * q + 4 * i);
;             v[4 * i] = (fkey(sv4.x) & ~127u) | (unsigned)ib; v[4 * i + 1] = (fkey(sv4.y) & ~127u) | (unsigned)(ib - 1);
;             v[4 * i + 2] = (fkey(sv4.z) & ~127u) | (unsigned)(ib - 2); v[4 * i + 3] = (fkey(sv4.w) & ~127u) | (unsigned)(ib - 3);
	s_nop 1
	v_bitop3_b32 v0, v0, s98, v12 bitop3:0x56
	v_and_b32_e32 v0, 0xffffff80, v0
	v_sub_u32_e32 v0, v0, v179
	v_add_u32_e32 v12, 0x7f, v0
	v_ashrrev_i32_e32 v0, 31, v13


; DI unsigned fkey(float f) { const unsigned u = __float_as_uint(f); return (u & 0x80000000u) ? ~u : (u | 0x80000000u); }
; DI void topk_phase(unsigned char* smem_, const bf16_t* __restrict__ qp, const bf16_t* __restrict__ keys, int* __restrict__ eidx, float* __restrict__ gate) {
;     ...
;         for (int i = 0; i < 8; ++i) {
;             const f32x4 sv4 = *(const f32x4*)(S + row * LDS_ + 32 * q + 4 * i);
;             const int ib = 127 - (32 * q + 4 * i);
;             v[4 * i] = (fkey(sv4.x) & ~127u) | (unsigned)ib; v[4 * i + 1] = (fkey(sv4.y) & ~127u) | (unsigned)(ib - 1);
;             v[4 * i + 2] = (fkey(sv4.z) & ~127u) | (unsigned)(ib - 2); v[4 * i + 3] = (fkey(sv4.w) & ~127u) | (unsigned)(ib - 3);
	s_nop 1
	v_bitop3_b32 v0, v0, s98, v13 bitop3:0x56
	v_and_b32_e32 v0, 0xffffff80, v0
	v_sub_u32_e32 v0, v0, v179
	v_add_u32_e32 v13, 0x7e, v0
	v_ashrrev_i32_e32 v0, 31, v14


; DI unsigned fkey(float f) { const unsigned u = __float_as_uint(f); return (u & 0x80000000u) ? ~u : (u | 0x80000000u); }
; DI void topk_phase(unsigned char* smem_, const bf16_t* __restrict__ qp, const bf16_t* __restrict__ keys, int* __restrict__ eidx, float* __restrict__ gate) {
;     ...
;         for (int i = 0; i < 8; ++i) {
;             const f32x4 sv4 = *(const f32x4*)(S + row * LDS_ + 32 * q + 4 * i);
;             const int ib = 127 - (32 * q + 4 * i);
;             v[4 * i] = (fkey(sv4.x) & ~127u) | (unsigned)ib; v[4 * i + 1] = (fkey(sv4.y) & ~127u) | (unsigned)(ib - 1);
;             v[4 * i + 2] = (fkey(sv4.z) & ~127u) | (unsigned)(ib - 2); v[4 * i + 3] = (fkey(sv4.w) & ~127u) | (unsigned)(ib - 3);
	s_nop 1
	v_bitop3_b32 v0, v0, s98, v14 bitop3:0x56
	v_and_b32_e32 v0, 0xffffff80, v0
	v_sub_u32_e32 v0, v0, v179
	v_add_u32_e32 v14, 0x7d, v0
	v_ashrrev_i32_e32 v0, 31, v15


; DI unsigned fkey(float f) { const unsigned u = __float_as_uint(f); return (u & 0x80000000u) ? ~u : (u | 0x80000000u); }
; DI void topk_phase(unsigned char* smem_, const bf16_t* __restrict__ qp, const bf16_t* __restrict__ keys, int* __restrict__ eidx, float* __restrict__ gate) {
;     ...
;         for (int i = 0; i < 8; ++i) {
;             const f32x4 sv4 = *(const f32x4*)(S + row * LDS_ + 32 * q + 4 * i);
;             const int ib = 127 - (32 * q + 4 * i);
;             v[4 * i] = (fkey(sv4.x) & ~127u) | (unsigned)ib; v[4 * i + 1] = (fkey(sv4.y) & ~127u) | (unsigned)(ib - 1);
;             v[4 * i + 2] = (fkey(sv4.z) & ~127u) | (unsigned)(ib - 2); v[4 * i + 3] = (fkey(sv4.w) & ~127u) | (unsigned)(ib - 3);
	s_nop 1
	v_bitop3_b32 v4, v0, s98, v15 bitop3:0x56
	ds_read_b128 v[0:3], v171 offset:17472
	v_and_b32_e32 v4, 0xffffff80, v4
	v_sub_u32_e32 v4, v4, v179
	v_add_u32_e32 v15, 0x7c, v4
	ds_read_b128 v[4:7], v171 offset:17488
	s_waitcnt lgkmcnt(1)
	v_ashrrev_i32_e32 v24, 31, v0


; DI unsigned fkey(float f) { const unsigned u = __float_as_uint(f); return (u & 0x80000000u) ? ~u : (u | 0x80000000u); }
; DI void topk_phase(unsigned char* smem_, const bf16_t* __restrict__ qp, const bf16_t* __restrict__ keys, int* __restrict__ eidx, float* __restrict__ gate) {
;     ...
;         for (int i = 0; i < 8; ++i) {
;             const f32x4 sv4 = *(const f32x4*)(S + row * LDS_ + 32 * q + 4 * i);
;             const int ib = 127 - (32 * q + 4 * i);
;             v[4 * i] = (fkey(sv4.x) & ~127u) | (unsigned)ib; v[4 * i + 1] = (fkey(sv4.y) & ~127u) | (unsigned)(ib - 1);
;             v[4 * i + 2] = (fkey(sv4.z) & ~127u) | (unsigned)(ib - 2); v[4 * i + 3] = (fkey(sv4.w) & ~127u) | (unsigned)(ib - 3);
	s_nop 1
	v_bitop3_b32 v0, v24, s98, v0 bitop3:0x56
	v_and_b32_e32 v0, 0xffffff80, v0
	v_sub_u32_e32 v0, v0, v180
	v_add_u32_e32 v24, 0x7f, v0
	v_not_b32_e32 v0, v1
	v_or_b32_e32 v25, 0x80000000, v1
	v_cmp_gt_i32_e32 vcc, 0, v1
	v_ashrrev_i32_e32 v1, 31, v2
	s_nop 0
	v_cndmask_b32_e32 v0, v25, v0, vcc
	v_and_b32_e32 v0, 0xffffff80, v0
	v_sub_u32_e32 v0, v0, v180
	v_add_u32_e32 v25, 0x7e, v0


; DI unsigned fkey(float f) { const unsigned u = __float_as_uint(f); return (u & 0x80000000u) ? ~u : (u | 0x80000000u); }
; DI void topk_phase(unsigned char* smem_, const bf16_t* __restrict__ qp, const bf16_t* __restrict__ keys, int* __restrict__ eidx, float* __restrict__ gate) {
;     ...
;         for (int i = 0; i < 8; ++i) {
;             const f32x4 sv4 = *(const f32x4*)(S + row * LDS_ + 32 * q + 4 * i);
;             const int ib = 127 - (32 * q + 4 * i);
;             v[4 * i] = (fkey(sv4.x) & ~127u) | (unsigned)ib; v[4 * i + 1] = (fkey(sv4.y) & ~127u) | (unsigned)(ib - 1);
;             v[4 * i + 2] = (fkey(sv4.z) & ~127u) | (unsigned)(ib - 2); v[4 * i + 3] = (fkey(sv4.w) & ~127u) | (unsigned)(ib - 3);
	s_nop 1
	v_bitop3_b32 v0, v1, s98, v2 bitop3:0x56
	v_and_b32_e32 v0, 0xffffff80, v0
	v_sub_u32_e32 v0, v0, v180
	v_add_u32_e32 v26, 0x7d, v0
	v_ashrrev_i32_e32 v0, 31, v3


; DI unsigned fkey(float f) { const unsigned u = __float_as_uint(f); return (u & 0x80000000u) ? ~u : (u | 0x80000000u); }
; DI void topk_phase(unsigned char* smem_, const bf16_t* __restrict__ qp, const bf16_t* __restrict__ keys, int* __restrict__ eidx, float* __restrict__ gate) {
;     ...
;         for (int i = 0; i < 8; ++i) {
;             const f32x4 sv4 = *(const f32x4*)(S + row * LDS_ + 32 * q + 4 * i);
;             const int ib = 127 - (32 * q + 4 * i);
;             v[4 * i] = (fkey(sv4.x) & ~127u) | (unsigned)ib; v[4 * i + 1] = (fkey(sv4.y) & ~127u) | (unsigned)(ib - 1);
;             v[4 * i + 2] = (fkey(sv4.z) & ~127u) | (unsigned)(ib - 2); v[4 * i + 3] = (fkey(sv4.w) & ~127u) | (unsigned)(ib - 3);
	s_nop 1
	v_bitop3_b32 v0, v0, s98, v3 bitop3:0x56
	v_and_b32_e32 v0, 0xffffff80, v0
	v_sub_u32_e32 v0, v0, v180
	v_add_u32_e32 v27, 0x7c, v0
	s_waitcnt lgkmcnt(0)
	v_ashrrev_i32_e32 v0, 31, v4


; DI unsigned fkey(float f) { const unsigned u = __float_as_uint(f); return (u & 0x80000000u) ? ~u : (u | 0x80000000u); }
; DI void topk_phase(unsigned char* smem_, const bf16_t* __restrict__ qp, const bf16_t* __restrict__ keys, int* __restrict__ eidx, float* __restrict__ gate) {
;     ...
;         for (int i = 0; i < 8; ++i) {
;             const f32x4 sv4 = *(const f32x4*)(S + row * LDS_ + 32 * q + 4 * i);
;             const int ib = 127 - (32 * q + 4 * i);
;             v[4 * i] = (fkey(sv4.x) & ~127u) | (unsigned)ib; v[4 * i + 1] = (fkey(sv4.y) & ~127u) | (unsigned)(ib - 1);
;             v[4 * i + 2] = (fkey(sv4.z) & ~127u) | (unsigned)(ib - 2); v[4 * i + 3] = (fkey(sv4.w) & ~127u) | (unsigned)(ib - 3);
	s_nop 1
	v_bitop3_b32 v0, v0, s98, v4 bitop3:0x56
	v_and_b32_e32 v0, 0xffffff80, v0
	v_sub_u32_e32 v0, v0, v181
	v_add_u32_e32 v28, 0x7f, v0
	v_ashrrev_i32_e32 v0, 31, v5


; DI unsigned fkey(float f) { const unsigned u = __float_as_uint(f); return (u & 0x80000000u) ? ~u : (u | 0x80000000u); }
; DI void topk_phase(unsigned char* smem_, const bf16_t* __restrict__ qp, const bf16_t* __restrict__ keys, int* __restrict__ eidx, float* __restrict__ gate) {
;     ...
;         for (int i = 0; i < 8; ++i) {
;             const f32x4 sv4 = *(const f32x4*)(S + row * LDS_ + 32 * q + 4 * i);
;             const int ib = 127 - (32 * q + 4 * i);
;             v[4 * i] = (fkey(sv4.x) & ~127u) | (unsigned)ib; v[4 * i + 1] = (fkey(sv4.y) & ~127u) | (unsigned)(ib - 1);
;             v[4 * i + 2] = (fkey(sv4.z) & ~127u) | (unsigned)(ib - 2); v[4 * i + 3] = (fkey(sv4.w) & ~127u) | (unsigned)(ib - 3);
;         }
	s_nop 1
	v_bitop3_b32 v0, v0, s98, v5 bitop3:0x56
	v_and_b32_e32 v0, 0xffffff80, v0
	v_sub_u32_e32 v0, v0, v181
	v_add_u32_e32 v29, 0x7e, v0
	v_ashrrev_i32_e32 v0, 31, v6


; DI unsigned fkey(float f) { const unsigned u = __float_as_uint(f); return (u & 0x80000000u) ? ~u : (u | 0x80000000u); }
; DI void topk_phase(unsigned char* smem_, const bf16_t* __restrict__ qp, const bf16_t* __restrict__ keys, int* __restrict__ eidx, float* __restrict__ gate) {
;     ...
;         for (int i = 0; i < 8; ++i) {
;             const f32x4 sv4 = *(const f32x4*)(S + row * LDS_ + 32 * q + 4 * i);
;             const int ib = 127 - (32 * q + 4 * i);
;             v[4 * i] = (fkey(sv4.x) & ~127u) | (unsigned)ib; v[4 * i + 1] = (fkey(sv4.y) & ~127u) | (unsigned)(ib - 1);
;             v[4 * i + 2] = (fkey(sv4.z) & ~127u) | (unsigned)(ib - 2); v[4 * i + 3] = (fkey(sv4.w) & ~127u) | (unsigned)(ib - 3);
;         }
	s_nop 1
	v_bitop3_b32 v0, v0, s98, v6 bitop3:0x56
	v_and_b32_e32 v0, 0xffffff80, v0
	v_sub_u32_e32 v0, v0, v181
	v_add_u32_e32 v30, 0x7d, v0
	v_ashrrev_i32_e32 v0, 31, v7


; DI unsigned fkey(float f) { const unsigned u = __float_as_uint(f); return (u & 0x80000000u) ? ~u : (u | 0x80000000u); }
; DI void topk_phase(unsigned char* smem_, const bf16_t* __restrict__ qp, const bf16_t* __restrict__ keys, int* __restrict__ eidx, float* __restrict__ gate) {
;     ...
;         for (int i = 0; i < 8; ++i) {
;             const f32x4 sv4 = *(const f32x4*)(S + row * LDS_ + 32 * q + 4 * i);
;             const int ib = 127 - (32 * q + 4 * i);
;             v[4 * i] = (fkey(sv4.x) & ~127u) | (unsigned)ib; v[4 * i + 1] = (fkey(sv4.y) & ~127u) | (unsigned)(ib - 1);
;             v[4 * i + 2] = (fkey(sv4.z) & ~127u) | (unsigned)(ib - 2); v[4 * i + 3] = (fkey(sv4.w) & ~127u) | (unsigned)(ib - 3);
;         }
	s_nop 1
	v_bitop3_b32 v4, v0, s98, v7 bitop3:0x56
	ds_read_b128 v[0:3], v171 offset:17504
	v_and_b32_e32 v4, 0xffffff80, v4
	v_sub_u32_e32 v4, v4, v181
	v_add_u32_e32 v31, 0x7c, v4
	ds_read_b128 v[4:7], v171 offset:17520
	s_waitcnt lgkmcnt(1)
	v_ashrrev_i32_e32 v117, 31, v0


; DI unsigned fkey(float f) { const unsigned u = __float_as_uint(f); return (u & 0x80000000u) ? ~u : (u | 0x80000000u); }
; DI void topk_phase(unsigned char* smem_, const bf16_t* __restrict__ qp, const bf16_t* __restrict__ keys, int* __restrict__ eidx, float* __restrict__ gate) {
;     ...
;         for (int i = 0; i < 8; ++i) {
;             const f32x4 sv4 = *(const f32x4*)(S + row * LDS_ + 32 * q + 4 * i);
;             const int ib = 127 - (32 * q + 4 * i);
;             v[4 * i] = (fkey(sv4.x) & ~127u) | (unsigned)ib; v[4 * i + 1] = (fkey(sv4.y) & ~127u) | (unsigned)(ib - 1);
;             v[4 * i + 2] = (fkey(sv4.z) & ~127u) | (unsigned)(ib - 2); v[4 * i + 3] = (fkey(sv4.w) & ~127u) | (unsigned)(ib - 3);
;         }
	s_nop 1
	v_bitop3_b32 v0, v117, s98, v0 bitop3:0x56
	v_ashrrev_i32_e32 v117, 31, v1


; DI unsigned fkey(float f) { const unsigned u = __float_as_uint(f); return (u & 0x80000000u) ? ~u : (u | 0x80000000u); }
; DI void topk_phase(unsigned char* smem_, const bf16_t* __restrict__ qp, const bf16_t* __restrict__ keys, int* __restrict__ eidx, float* __restrict__ gate) {
;     ...
;         for (int i = 0; i < 8; ++i) {
;             const f32x4 sv4 = *(const f32x4*)(S + row * LDS_ + 32 * q + 4 * i);
;             const int ib = 127 - (32 * q + 4 * i);
;             v[4 * i] = (fkey(sv4.x) & ~127u) | (unsigned)ib; v[4 * i + 1] = (fkey(sv4.y) & ~127u) | (unsigned)(ib - 1);
;             v[4 * i + 2] = (fkey(sv4.z) & ~127u) | (unsigned)(ib - 2); v[4 * i + 3] = (fkey(sv4.w) & ~127u) | (unsigned)(ib - 3);
;         }
	v_and_b32_e32 v0, 0xffffff80, v0
	v_sub_u32_e32 v0, v0, v182
	v_bitop3_b32 v1, v117, s98, v1 bitop3:0x56
	v_ashrrev_i32_e32 v117, 31, v2


; DI unsigned fkey(float f) { const unsigned u = __float_as_uint(f); return (u & 0x80000000u) ? ~u : (u | 0x80000000u); }
; DI void topk_phase(unsigned char* smem_, const bf16_t* __restrict__ qp, const bf16_t* __restrict__ keys, int* __restrict__ eidx, float* __restrict__ gate) {
;     ...
;         for (int i = 0; i < 8; ++i) {
;             const f32x4 sv4 = *(const f32x4*)(S + row * LDS_ + 32 * q + 4 * i);
;             const int ib = 127 - (32 * q + 4 * i);
;             v[4 * i] = (fkey(sv4.x) & ~127u) | (unsigned)ib; v[4 * i + 1] = (fkey(sv4.y) & ~127u) | (unsigned)(ib - 1);
;             v[4 * i + 2] = (fkey(sv4.z) & ~127u) | (unsigned)(ib - 2); v[4 * i + 3] = (fkey(sv4.w) & ~127u) | (unsigned)(ib - 3);
;         }
	v_and_b32_e32 v1, 0xffffff80, v1
	v_sub_u32_e32 v1, v1, v182
	v_bitop3_b32 v2, v117, s98, v2 bitop3:0x56
	v_ashrrev_i32_e32 v117, 31, v3


; DI unsigned fkey(float f) { const unsigned u = __float_as_uint(f); return (u & 0x80000000u) ? ~u : (u | 0x80000000u); }
; DI void topk_phase(unsigned char* smem_, const bf16_t* __restrict__ qp, const bf16_t* __restrict__ keys, int* __restrict__ eidx, float* __restrict__ gate) {
;     ...
;         for (int i = 0; i < 8; ++i) {
;             const f32x4 sv4 = *(const f32x4*)(S + row * LDS_ + 32 * q + 4 * i);
;             const int ib = 127 - (32 * q + 4 * i);
;             v[4 * i] = (fkey(sv4.x) & ~127u) | (unsigned)ib; v[4 * i + 1] = (fkey(sv4.y) & ~127u) | (unsigned)(ib - 1);
;             v[4 * i + 2] = (fkey(sv4.z) & ~127u) | (unsigned)(ib - 2); v[4 * i + 3] = (fkey(sv4.w) & ~127u) | (unsigned)(ib - 3);
;         }
	v_and_b32_e32 v2, 0xffffff80, v2
	v_sub_u32_e32 v2, v2, v182
	v_bitop3_b32 v3, v117, s98, v3 bitop3:0x56
	s_waitcnt lgkmcnt(0)
	v_ashrrev_i32_e32 v117, 31, v4


; DI unsigned fkey(float f) { const unsigned u = __float_as_uint(f); return (u & 0x80000000u) ? ~u : (u | 0x80000000u); }
; DI void topk_phase(unsigned char* smem_, const bf16_t* __restrict__ qp, const bf16_t* __restrict__ keys, int* __restrict__ eidx, float* __restrict__ gate) {
;     ...
;         for (int i = 0; i < 8; ++i) {
;             const f32x4 sv4 = *(const f32x4*)(S + row * LDS_ + 32 * q + 4 * i);
;             const int ib = 127 - (32 * q + 4 * i);
;             v[4 * i] = (fkey(sv4.x) & ~127u) | (unsigned)ib; v[4 * i + 1] = (fkey(sv4.y) & ~127u) | (unsigned)(ib - 1);
;             v[4 * i + 2] = (fkey(sv4.z) & ~127u) | (unsigned)(ib - 2); v[4 * i + 3] = (fkey(sv4.w) & ~127u) | (unsigned)(ib - 3);
;         }
	v_and_b32_e32 v3, 0xffffff80, v3
	v_sub_u32_e32 v3, v3, v182
	v_bitop3_b32 v4, v117, s98, v4 bitop3:0x56
	v_ashrrev_i32_e32 v117, 31, v5


; DI unsigned fkey(float f) { const unsigned u = __float_as_uint(f); return (u & 0x80000000u) ? ~u : (u | 0x80000000u); }
; DI void topk_phase(unsigned char* smem_, const bf16_t* __restrict__ qp, const bf16_t* __restrict__ keys, int* __restrict__ eidx, float* __restrict__ gate) {
;     ...
;         for (int i = 0; i < 8; ++i) {
;             const f32x4 sv4 = *(const f32x4*)(S + row * LDS_ + 32 * q + 4 * i);
;             const int ib = 127 - (32 * q + 4 * i);
;             v[4 * i] = (fkey(sv4.x) & ~127u) | (unsigned)ib; v[4 * i + 1] = (fkey(sv4.y) & ~127u) | (unsigned)(ib - 1);
;             v[4 * i + 2] = (fkey(sv4.z) & ~127u) | (unsigned)(ib - 2); v[4 * i + 3] = (fkey(sv4.w) & ~127u) | (unsigned)(ib - 3);
;         }
	v_and_b32_e32 v4, 0xffffff80, v4
	v_sub_u32_e32 v4, v4, v183
	v_bitop3_b32 v5, v117, s98, v5 bitop3:0x56
	v_ashrrev_i32_e32 v117, 31, v6


; DI unsigned fkey(float f) { const unsigned u = __float_as_uint(f); return (u & 0x80000000u) ? ~u : (u | 0x80000000u); }
; DI void topk_phase(unsigned char* smem_, const bf16_t* __restrict__ qp, const bf16_t* __restrict__ keys, int* __restrict__ eidx, float* __restrict__ gate) {
;     ...
;         for (int i = 0; i < 8; ++i) {
;             const f32x4 sv4 = *(const f32x4*)(S + row * LDS_ + 32 * q + 4 * i);
;             const int ib = 127 - (32 * q + 4 * i);
;             v[4 * i] = (fkey(sv4.x) & ~127u) | (unsigned)ib; v[4 * i + 1] = (fkey(sv4.y) & ~127u) | (unsigned)(ib - 1);
;             v[4 * i + 2] = (fkey(sv4.z) & ~127u) | (unsigned)(ib - 2); v[4 * i + 3] = (fkey(sv4.w) & ~127u) | (unsigned)(ib - 3);
;         }
	v_and_b32_e32 v5, 0xffffff80, v5
	v_sub_u32_e32 v5, v5, v183
	v_bitop3_b32 v6, v117, s98, v6 bitop3:0x56
	v_ashrrev_i32_e32 v117, 31, v7


; DI unsigned fkey(float f) { const unsigned u = __float_as_uint(f); return (u & 0x80000000u) ? ~u : (u | 0x80000000u); }
; template <int N> DI void bitonic_sort_desc(unsigned (&v)[N]) {
; #pragma unroll
;     for (int k = 2; k <= N; k <<= 1)
; #pragma unroll
;         for (int j = k >> 1; j > 0; j >>= 1)
; #pragma unroll
;             for (int i = 0; i < N; ++i) { const int l = i ^ j; if (l > i) { if ((i & k) == 0) cswap(v[i], v[l]); else cswap(v[l], v[i]); } }
; }
; DI void topk_phase(unsigned char* smem_, const bf16_t* __restrict__ qp, const bf16_t* __restrict__ keys, int* __restrict__ eidx, float* __restrict__ gate) {
;     ...
;         for (int i = 0; i < 8; ++i) {
;             const f32x4 sv4 = *(const f32x4*)(S + row * LDS_ + 32 * q + 4 * i);
;             const int ib = 127 - (32 * q + 4 * i);
;             v[4 * i] = (fkey(sv4.x) & ~127u) | (unsigned)ib; v[4 * i + 1] = (fkey(sv4.y) & ~127u) | (unsigned)(ib - 1);
;             v[4 * i + 2] = (fkey(sv4.z) & ~127u) | (unsigned)(ib - 2); v[4 * i + 3] = (fkey(sv4.w) & ~127u) | (unsigned)(ib - 3);
;         }
;         bitonic_sort_desc<32>(v);
	v_and_b32_e32 v6, 0xffffff80, v6
	v_sub_u32_e32 v6, v6, v183
	v_bitop3_b32 v7, v117, s98, v7 bitop3:0x56
	v_and_b32_e32 v7, 0xffffff80, v7
	v_sub_u32_e32 v7, v7, v183
	v_add_u32_e32 v0, 0x7f, v0
	v_add_u32_e32 v1, 0x7e, v1
	v_add_u32_e32 v2, 0x7d, v2
	v_add_u32_e32 v3, 0x7c, v3
	v_add_u32_e32 v4, 0x7f, v4
	v_add_u32_e32 v5, 0x7e, v5
	v_add_u32_e32 v6, 0x7d, v6
	v_add_u32_e32 v7, 0x7c, v7
	v_max_u32_e32 v117, v16, v17
	v_min_u32_e32 v16, v16, v17
	v_max_u32_e32 v17, v19, v18
	v_min_u32_e32 v18, v19, v18
	v_max_u32_e32 v19, v20, v21
	v_min_u32_e32 v20, v20, v21
	v_max_u32_e32 v21, v23, v22
	v_min_u32_e32 v22, v23, v22
	v_max_u32_e32 v23, v8, v9
	v_min_u32_e32 v8, v8, v9
	v_max_u32_e32 v9, v11, v10
	v_min_u32_e32 v10, v11, v10
	v_max_u32_e32 v11, v12, v13
	v_min_u32_e32 v12, v12, v13
	v_max_u32_e32 v13, v15, v14
	v_min_u32_e32 v14, v15, v14
	v_max_u32_e32 v15, v24, v25
	v_min_u32_e32 v24, v24, v25
	v_max_u32_e32 v25, v27, v26
	v_min_u32_e32 v26, v27, v26
	v_max_u32_e32 v27, v28, v29
	v_min_u32_e32 v28, v28, v29
	v_max_u32_e32 v29, v31, v30
	v_min_u32_e32 v30, v31, v30
	v_max_u32_e32 v31, v0, v1
	v_min_u32_e32 v0, v0, v1
	v_max_u32_e32 v1, v3, v2
	v_min_u32_e32 v2, v3, v2
	v_max_u32_e32 v3, v4, v5
	v_min_u32_e32 v4, v4, v5
	v_max_u32_e32 v5, v7, v6
	v_min_u32_e32 v6, v7, v6
	v_max_u32_e32 v7, v117, v18
	v_min_u32_e32 v18, v117, v18
	v_max_u32_e32 v117, v16, v17
	v_min_u32_e32 v16, v16, v17
	v_max_u32_e32 v17, v22, v19
	v_min_u32_e32 v19, v22, v19
	v_max_u32_e32 v22, v21, v20
	v_min_u32_e32 v20, v21, v20
	v_max_u32_e32 v21, v23, v10
	v_min_u32_e32 v10, v23, v10
	v_max_u32_e32 v23, v8, v9
	v_min_u32_e32 v8, v8, v9
	v_max_u32_e32 v9, v14, v11
	v_min_u32_e32 v11, v14, v11
	v_max_u32_e32 v14, v13, v12
	v_min_u32_e32 v12, v13, v12
	v_max_u32_e32 v13, v15, v26
	v_min_u32_e32 v15, v15, v26
	v_max_u32_e32 v26, v24, v25
	v_min_u32_e32 v24, v24, v25
	v_max_u32_e32 v25, v30, v27
	v_min_u32_e32 v27, v30, v27
	v_max_u32_e32 v30, v29, v28
	v_min_u32_e32 v28, v29, v28
	v_max_u32_e32 v29, v31, v2
	v_min_u32_e32 v2, v31, v2
	v_max_u32_e32 v31, v0, v1
	v_min_u32_e32 v0, v0, v1
	v_max_u32_e32 v1, v6, v3
	v_min_u32_e32 v3, v6, v3
	v_max_u32_e32 v6, v5, v4
	v_min_u32_e32 v4, v5, v4
	v_max_u32_e32 v5, v7, v117
	v_min_u32_e32 v7, v7, v117
	v_max_u32_e32 v117, v18, v16
	v_min_u32_e32 v16, v18, v16
	v_max_u32_e32 v18, v20, v19
	v_min_u32_e32 v19, v20, v19
	v_max_u32_e32 v20, v22, v17
	v_min_u32_e32 v17, v22, v17
	v_max_u32_e32 v22, v21, v23
	v_min_u32_e32 v21, v21, v23
	v_max_u32_e32 v23, v10, v8
	v_min_u32_e32 v8, v10, v8
	v_max_u32_e32 v10, v12, v11
	v_min_u32_e32 v11, v12, v11
	v_max_u32_e32 v12, v14, v9
	v_min_u32_e32 v9, v14, v9
	v_max_u32_e32 v14, v13, v26
	v_min_u32_e32 v13, v13, v26
	v_max_u32_e32 v26, v15, v24
	v_min_u32_e32 v15, v15, v24
	v_max_u32_e32 v24, v28, v27
	v_min_u32_e32 v27, v28, v27
	v_max_u32_e32 v28, v30, v25
	v_min_u32_e32 v25, v30, v25
	v_max_u32_e32 v30, v29, v31
	v_min_u32_e32 v29, v29, v31
	v_max_u32_e32 v31, v2, v0
	v_min_u32_e32 v0, v2, v0
	v_max_u32_e32 v2, v4, v3
	v_min_u32_e32 v3, v4, v3
	v_max_u32_e32 v4, v6, v1
	v_min_u32_e32 v1, v6, v1
	v_max_u32_e32 v6, v5, v19
	v_min_u32_e32 v5, v5, v19
	v_max_u32_e32 v19, v7, v18
	v_min_u32_e32 v7, v7, v18
	v_max_u32_e32 v18, v117, v17
	v_min_u32_e32 v17, v117, v17
	v_max_u32_e32 v117, v16, v20
	v_min_u32_e32 v16, v16, v20
	v_max_u32_e32 v20, v11, v22
	v_min_u32_e32 v11, v11, v22
	v_max_u32_e32 v22, v10, v21
	v_min_u32_e32 v10, v10, v21
	v_max_u32_e32 v21, v9, v23
	v_min_u32_e32 v9, v9, v23
	v_max_u32_e32 v23, v12, v8
	v_min_u32_e32 v8, v12, v8
	v_max_u32_e32 v12, v14, v27
	v_min_u32_e32 v14, v14, v27
	v_max_u32_e32 v27, v13, v24
	v_min_u32_e32 v13, v13, v24
	v_max_u32_e32 v24, v26, v25
	v_min_u32_e32 v25, v26, v25
	v_max_u32_e32 v26, v15, v28
	v_min_u32_e32 v15, v15, v28
	v_max_u32_e32 v28, v3, v30
	v_min_u32_e32 v3, v3, v30
	v_max_u32_e32 v30, v2, v29
	v_min_u32_e32 v2, v2, v29
	v_max_u32_e32 v29, v1, v31
	v_min_u32_e32 v1, v1, v31
	v_max_u32_e32 v31, v4, v0
	v_min_u32_e32 v0, v4, v0
	v_max_u32_e32 v4, v6, v18
	v_min_u32_e32 v6, v6, v18
	v_max_u32_e32 v18, v19, v117
	v_min_u32_e32 v19, v19, v117
	v_max_u32_e32 v117, v5, v17
	v_min_u32_e32 v5, v5, v17
	v_max_u32_e32 v17, v7, v16
	v_min_u32_e32 v7, v7, v16
	v_max_u32_e32 v16, v9, v11
	v_min_u32_e32 v9, v9, v11
	v_max_u32_e32 v11, v8, v10
	v_min_u32_e32 v8, v8, v10
	v_max_u32_e32 v10, v21, v20
	v_min_u32_e32 v20, v21, v20
	v_max_u32_e32 v21, v23, v22
	v_min_u32_e32 v22, v23, v22
	v_max_u32_e32 v23, v12, v24
	v_min_u32_e32 v12, v12, v24
	v_max_u32_e32 v24, v27, v26
	v_min_u32_e32 v26, v27, v26
	v_max_u32_e32 v27, v14, v25
	v_min_u32_e32 v14, v14, v25
	v_max_u32_e32 v25, v13, v15
	v_min_u32_e32 v13, v13, v15
	v_max_u32_e32 v15, v1, v3
	v_min_u32_e32 v1, v1, v3
	v_max_u32_e32 v3, v0, v2
	v_min_u32_e32 v0, v0, v2
	v_max_u32_e32 v2, v29, v28
	v_min_u32_e32 v28, v29, v28
	v_max_u32_e32 v29, v31, v30
	v_min_u32_e32 v30, v31, v30
	v_max_u32_e32 v31, v4, v18
	v_min_u32_e32 v4, v4, v18
	v_max_u32_e32 v18, v6, v19
	v_min_u32_e32 v6, v6, v19
	v_max_u32_e32 v19, v117, v17
	v_min_u32_e32 v17, v117, v17
	v_max_u32_e32 v117, v5, v7
	v_min_u32_e32 v5, v5, v7
	v_max_u32_e32 v7, v8, v9
	v_min_u32_e32 v8, v8, v9
	v_max_u32_e32 v9, v11, v16
	v_min_u32_e32 v11, v11, v16
	v_max_u32_e32 v16, v22, v20
	v_min_u32_e32 v20, v22, v20
	v_max_u32_e32 v22, v21, v10
	v_min_u32_e32 v10, v21, v10
	v_max_u32_e32 v21, v23, v24
	v_min_u32_e32 v23, v23, v24
	v_max_u32_e32 v24, v12, v26
	v_min_u32_e32 v12, v12, v26
	v_max_u32_e32 v26, v27, v25
	v_min_u32_e32 v25, v27, v25
	v_max_u32_e32 v27, v14, v13
	v_min_u32_e32 v13, v14, v13
	v_max_u32_e32 v14, v0, v1
	v_min_u32_e32 v0, v0, v1
; template <int N> DI void bitonic_sort_desc(unsigned (&v)[N]) {
; #pragma unroll
;     for (int k = 2; k <= N; k <<= 1)
; #pragma unroll
;         for (int j = k >> 1; j > 0; j >>= 1)
; #pragma unroll
;             for (int i = 0; i < N; ++i) { const int l = i ^ j; if (l > i) { if ((i & k) == 0) cswap(v[i], v[l]); else cswap(v[l], v[i]); } }
; }
; DI void merge_top16(unsigned (&v)[16], int st) {
;     unsigned x[16];
; #pragma unroll
;     for (int i = 0; i < 16; ++i) x[i] = (unsigned)__shfl_xor((int)v[15 - i], st);
; #pragma unroll
;     for (int i = 0; i < 16; ++i) v[i] = max(v[i], x[i]);
; #pragma unroll
;     for (int j = 8; j > 0; j >>= 1)
; #pragma unroll
;         for (int i = 0; i < 16; ++i) { const int l = i ^ j; if (l > i) cswap(v[i], v[l]); }
; }
	v_max_u32_e32 v1, v3, v15
	v_min_u32_e32 v3, v3, v15
	v_max_u32_e32 v15, v30, v28
	v_min_u32_e32 v28, v30, v28
	v_max_u32_e32 v30, v29, v2
	v_min_u32_e32 v2, v29, v2
	v_max_u32_e32 v29, v31, v8
	v_min_u32_e32 v8, v31, v8
	v_max_u32_e32 v31, v4, v7
	v_min_u32_e32 v4, v4, v7
	v_max_u32_e32 v7, v18, v11
	v_min_u32_e32 v11, v18, v11
	v_max_u32_e32 v18, v6, v9
	v_min_u32_e32 v6, v6, v9
	v_max_u32_e32 v9, v19, v20
	v_min_u32_e32 v19, v19, v20
	v_max_u32_e32 v20, v17, v16
	v_min_u32_e32 v16, v17, v16
	v_max_u32_e32 v17, v117, v10
	v_min_u32_e32 v10, v117, v10
	v_max_u32_e32 v117, v5, v22
	v_min_u32_e32 v5, v5, v22
	v_max_u32_e32 v22, v0, v21
	v_min_u32_e32 v0, v0, v21
	v_max_u32_e32 v21, v14, v23
	v_min_u32_e32 v14, v14, v23
	v_max_u32_e32 v23, v3, v24
	v_min_u32_e32 v3, v3, v24
	v_max_u32_e32 v24, v1, v12
	v_min_u32_e32 v1, v1, v12
	v_max_u32_e32 v12, v28, v26
	v_min_u32_e32 v26, v28, v26
	v_max_u32_e32 v28, v15, v25
	v_min_u32_e32 v15, v15, v25
	v_max_u32_e32 v25, v2, v27
	v_min_u32_e32 v2, v2, v27
	v_max_u32_e32 v27, v30, v13
	v_min_u32_e32 v13, v30, v13
	v_max_u32_e32 v30, v29, v9
	v_min_u32_e32 v9, v29, v9
	v_max_u32_e32 v29, v31, v20
	v_min_u32_e32 v20, v31, v20
	v_max_u32_e32 v31, v7, v17
	v_min_u32_e32 v7, v7, v17
	v_max_u32_e32 v17, v18, v117
	v_min_u32_e32 v18, v18, v117
	v_max_u32_e32 v117, v8, v19
	v_min_u32_e32 v8, v8, v19
	v_max_u32_e32 v19, v4, v16
	v_min_u32_e32 v4, v4, v16
	v_max_u32_e32 v16, v11, v10
	v_min_u32_e32 v10, v11, v10
	v_max_u32_e32 v11, v6, v5
	v_min_u32_e32 v5, v6, v5
	v_max_u32_e32 v6, v26, v0
	v_min_u32_e32 v0, v26, v0
	v_max_u32_e32 v26, v15, v14
	v_min_u32_e32 v14, v15, v14
	v_max_u32_e32 v15, v2, v3
	v_min_u32_e32 v2, v2, v3
	v_max_u32_e32 v3, v13, v1
	v_min_u32_e32 v1, v13, v1
	v_max_u32_e32 v13, v12, v22
	v_min_u32_e32 v12, v12, v22
	v_max_u32_e32 v22, v28, v21
	v_min_u32_e32 v21, v28, v21
	v_max_u32_e32 v28, v25, v23
	v_min_u32_e32 v23, v25, v23
	v_max_u32_e32 v25, v27, v24
	v_min_u32_e32 v24, v27, v24
	v_max_u32_e32 v27, v30, v31
	v_min_u32_e32 v30, v30, v31
	v_max_u32_e32 v31, v29, v17
	v_min_u32_e32 v17, v29, v17
	v_max_u32_e32 v29, v9, v7
	v_min_u32_e32 v7, v9, v7
	v_max_u32_e32 v9, v20, v18
	v_min_u32_e32 v18, v20, v18
	v_max_u32_e32 v20, v117, v16
	v_min_u32_e32 v16, v117, v16
	v_max_u32_e32 v117, v19, v11
	v_min_u32_e32 v11, v19, v11
	v_max_u32_e32 v19, v8, v10
	v_min_u32_e32 v8, v8, v10
	v_max_u32_e32 v10, v4, v5
	v_min_u32_e32 v4, v4, v5
	v_max_u32_e32 v5, v2, v0
	v_min_u32_e32 v0, v2, v0
	v_max_u32_e32 v2, v1, v14
	v_min_u32_e32 v1, v1, v14
	v_max_u32_e32 v14, v15, v6
	v_min_u32_e32 v6, v15, v6
	v_max_u32_e32 v15, v3, v26
	v_min_u32_e32 v3, v3, v26
	v_max_u32_e32 v26, v23, v12
	v_min_u32_e32 v12, v23, v12
	v_max_u32_e32 v23, v24, v21
	v_min_u32_e32 v21, v24, v21
	v_max_u32_e32 v24, v28, v13
	v_min_u32_e32 v13, v28, v13
	v_max_u32_e32 v28, v25, v22
	v_min_u32_e32 v22, v25, v22
	v_min_u32_e32 v25, v27, v31
	v_min_u32_e32 v118, v30, v17
	v_min_u32_e32 v119, v29, v9
	v_min_u32_e32 v120, v7, v18
	v_min_u32_e32 v121, v20, v117
	v_min_u32_e32 v122, v16, v11
	v_min_u32_e32 v123, v19, v10
	v_min_u32_e32 v124, v8, v4
	v_min_u32_e32 v125, v1, v0
	v_min_u32_e32 v126, v2, v5
	v_min_u32_e32 v127, v3, v6
	v_min_u32_e32 v142, v15, v14
	v_min_u32_e32 v143, v21, v12
	v_min_u32_e32 v144, v23, v26
	v_min_u32_e32 v145, v22, v13
	v_min_u32_e32 v146, v28, v24
	v_max3_u32 v27, v27, v31, v125
	v_max3_u32 v0, v25, v1, v0
	v_max3_u32 v1, v30, v17, v126
	v_max3_u32 v2, v118, v2, v5
	v_max3_u32 v5, v29, v9, v127
	v_max3_u32 v3, v119, v3, v6
	v_max3_u32 v6, v7, v18, v142
	v_max3_u32 v7, v120, v15, v14
	v_max3_u32 v9, v20, v117, v143
	v_max3_u32 v12, v121, v21, v12
	v_max3_u32 v11, v16, v11, v144
	v_max3_u32 v14, v122, v23, v26
	v_max3_u32 v10, v19, v10, v145
	v_max3_u32 v13, v123, v22, v13
	v_max3_u32 v4, v8, v4, v146
	v_max3_u32 v8, v124, v28, v24
	v_max_u32_e32 v15, v27, v9
	v_min_u32_e32 v9, v27, v9
	v_max_u32_e32 v16, v0, v12
	v_min_u32_e32 v0, v0, v12
	v_max_u32_e32 v12, v1, v11
	v_min_u32_e32 v1, v1, v11
	v_max_u32_e32 v11, v2, v14
	v_min_u32_e32 v2, v2, v14
	v_max_u32_e32 v14, v5, v10
	v_min_u32_e32 v5, v5, v10
	v_max_u32_e32 v10, v3, v13
	v_min_u32_e32 v3, v3, v13
	v_max_u32_e32 v13, v6, v4
	v_min_u32_e32 v4, v6, v4
	v_max_u32_e32 v6, v7, v8
	v_min_u32_e32 v7, v7, v8
	v_max_u32_e32 v8, v15, v14
	v_min_u32_e32 v14, v15, v14
	v_max_u32_e32 v15, v16, v10
	v_min_u32_e32 v10, v16, v10
	v_max_u32_e32 v16, v12, v13
	v_min_u32_e32 v12, v12, v13
	v_max_u32_e32 v13, v11, v6
	v_min_u32_e32 v6, v11, v6
	v_max_u32_e32 v11, v9, v5
	v_min_u32_e32 v5, v9, v5
	v_max_u32_e32 v9, v0, v3
	v_min_u32_e32 v0, v0, v3
	v_max_u32_e32 v3, v1, v4
	v_min_u32_e32 v1, v1, v4
	v_max_u32_e32 v4, v2, v7
	v_min_u32_e32 v2, v2, v7
	v_max_u32_e32 v7, v8, v16
	v_min_u32_e32 v8, v8, v16
	v_max_u32_e32 v16, v15, v13
	v_min_u32_e32 v13, v15, v13
	v_max_u32_e32 v15, v14, v12
	v_min_u32_e32 v12, v14, v12
	v_max_u32_e32 v14, v10, v6
	v_min_u32_e32 v6, v10, v6
	v_max_u32_e32 v10, v11, v3
	v_min_u32_e32 v3, v11, v3
	v_max_u32_e32 v11, v9, v4
	v_min_u32_e32 v4, v9, v4
	v_max_u32_e32 v9, v5, v1
	v_min_u32_e32 v1, v5, v1
	v_max_u32_e32 v5, v0, v2
	v_min_u32_e32 v0, v0, v2
	v_max_u32_e32 v2, v7, v16
	v_min_u32_e32 v7, v7, v16
	v_max_u32_e32 v16, v8, v13
	v_min_u32_e32 v8, v8, v13
	v_max_u32_e32 v13, v15, v14
	v_min_u32_e32 v14, v15, v14
	v_max_u32_e32 v15, v12, v6
	v_min_u32_e32 v6, v12, v6
	v_max_u32_e32 v12, v10, v11
	v_min_u32_e32 v10, v10, v11
	v_max_u32_e32 v11, v3, v4
	v_min_u32_e32 v3, v3, v4
	v_max_u32_e32 v4, v9, v5
	v_min_u32_e32 v5, v9, v5
	v_max_u32_e32 v9, v1, v0
	v_min_u32_e32 v0, v1, v0
	s_nop 1
	v_mov_b32_dpp v1, v0 quad_perm:[1,0,3,2] row_mask:0xf bank_mask:0xf
	v_mov_b32_dpp v17, v9 quad_perm:[1,0,3,2] row_mask:0xf bank_mask:0xf
	v_mov_b32_dpp v18, v5 quad_perm:[1,0,3,2] row_mask:0xf bank_mask:0xf
	v_mov_b32_dpp v19, v4 quad_perm:[1,0,3,2] row_mask:0xf bank_mask:0xf
	v_mov_b32_dpp v20, v3 quad_perm:[1,0,3,2] row_mask:0xf bank_mask:0xf
	v_mov_b32_dpp v21, v11 quad_perm:[1,0,3,2] row_mask:0xf bank_mask:0xf
	v_mov_b32_dpp v22, v10 quad_perm:[1,0,3,2] row_mask:0xf bank_mask:0xf
	v_mov_b32_dpp v23, v12 quad_perm:[1,0,3,2] row_mask:0xf bank_mask:0xf
	v_mov_b32_dpp v24, v6 quad_perm:[1,0,3,2] row_mask:0xf bank_mask:0xf
	v_mov_b32_dpp v25, v15 quad_perm:[1,0,3,2] row_mask:0xf bank_mask:0xf
	v_mov_b32_dpp v26, v14 quad_perm:[1,0,3,2] row_mask:0xf bank_mask:0xf
	v_mov_b32_dpp v27, v13 quad_perm:[1,0,3,2] row_mask:0xf bank_mask:0xf
	v_mov_b32_dpp v28, v8 quad_perm:[1,0,3,2] row_mask:0xf bank_mask:0xf
	v_mov_b32_dpp v29, v16 quad_perm:[1,0,3,2] row_mask:0xf bank_mask:0xf
	v_mov_b32_dpp v30, v7 quad_perm:[1,0,3,2] row_mask:0xf bank_mask:0xf
	v_mov_b32_dpp v31, v2 quad_perm:[1,0,3,2] row_mask:0xf bank_mask:0xf
	s_waitcnt lgkmcnt(0)
; DI void merge_top16(unsigned (&v)[16], int st) {
;     unsigned x[16];
; #pragma unroll
;     for (int i = 0; i < 16; ++i) x[i] = (unsigned)__shfl_xor((int)v[15 - i], st);
; #pragma unroll
;     for (int i = 0; i < 16; ++i) v[i] = max(v[i], x[i]);
; #pragma unroll
;     for (int j = 8; j > 0; j >>= 1)
; #pragma unroll
;         for (int i = 0; i < 16; ++i) { const int l = i ^ j; if (l > i) cswap(v[i], v[l]); }
; }
; DI void topk_phase(unsigned char* smem_, const bf16_t* __restrict__ qp, const bf16_t* __restrict__ keys, int* __restrict__ eidx, float* __restrict__ gate) {
;     ...
;         merge_top16(t16, 1);
;         merge_top16(t16, 2);
; #pragma unroll
;         for (int i = 0; i < 16; ++i) if ((i >> 2) == q) { const int idx = 127 - (int)(t16[i] & 127u); SI[row * 32 + 16 * p + i] = idx; SV[row * 32 + 16 * p + i] = S[row * LDS_ + idx]; }
	v_max_u32_e32 v1, v2, v1
	v_max_u32_e32 v2, v7, v17
	v_max_u32_e32 v7, v16, v18
	v_max_u32_e32 v8, v8, v19
	v_max_u32_e32 v13, v13, v20
	v_max_u32_e32 v14, v14, v21
	v_max_u32_e32 v15, v15, v22
	v_max_u32_e32 v6, v6, v23
	v_max_u32_e32 v12, v12, v24
	v_max_u32_e32 v10, v10, v25
	v_max_u32_e32 v11, v11, v26
	v_max_u32_e32 v3, v3, v27
	v_max_u32_e32 v4, v4, v28
	v_max_u32_e32 v5, v5, v29
	v_max_u32_e32 v9, v9, v30
	v_max_u32_e32 v0, v0, v31
	v_max_u32_e32 v16, v1, v12
	v_min_u32_e32 v1, v1, v12
	v_max_u32_e32 v12, v2, v10
	v_min_u32_e32 v2, v2, v10
	v_max_u32_e32 v10, v7, v11
	v_min_u32_e32 v7, v7, v11
	v_max_u32_e32 v11, v8, v3
	v_min_u32_e32 v3, v8, v3
	v_max_u32_e32 v8, v13, v4
	v_min_u32_e32 v4, v13, v4
	v_max_u32_e32 v13, v14, v5
	v_min_u32_e32 v5, v14, v5
	v_max_u32_e32 v14, v15, v9
	v_min_u32_e32 v9, v15, v9
	v_max_u32_e32 v15, v6, v0
	v_min_u32_e32 v0, v6, v0
	v_max_u32_e32 v6, v16, v8
	v_min_u32_e32 v8, v16, v8
	v_max_u32_e32 v16, v12, v13
	v_min_u32_e32 v12, v12, v13
	v_max_u32_e32 v13, v10, v14
	v_min_u32_e32 v10, v10, v14
	v_max_u32_e32 v14, v11, v15
	v_min_u32_e32 v11, v11, v15
	v_max_u32_e32 v15, v1, v4
	v_min_u32_e32 v1, v1, v4
	v_max_u32_e32 v4, v2, v5
	v_min_u32_e32 v2, v2, v5
	v_max_u32_e32 v5, v7, v9
	v_min_u32_e32 v7, v7, v9
	v_max_u32_e32 v9, v3, v0
	v_min_u32_e32 v0, v3, v0
	v_max_u32_e32 v3, v6, v13
	v_min_u32_e32 v6, v6, v13
	v_max_u32_e32 v13, v16, v14
	v_min_u32_e32 v14, v16, v14
	v_max_u32_e32 v16, v8, v10
	v_min_u32_e32 v8, v8, v10
	v_max_u32_e32 v10, v12, v11
	v_min_u32_e32 v11, v12, v11
	v_max_u32_e32 v12, v15, v5
	v_min_u32_e32 v5, v15, v5
	v_max_u32_e32 v15, v4, v9
	v_min_u32_e32 v4, v4, v9
	v_max_u32_e32 v9, v1, v7
	v_min_u32_e32 v1, v1, v7
	v_max_u32_e32 v7, v2, v0
	v_min_u32_e32 v0, v2, v0
	v_max_u32_e32 v2, v3, v13
	v_min_u32_e32 v3, v3, v13
	v_max_u32_e32 v13, v6, v14
	v_min_u32_e32 v6, v6, v14
	v_max_u32_e32 v14, v16, v10
	v_min_u32_e32 v10, v16, v10
	v_max_u32_e32 v16, v8, v11
	v_min_u32_e32 v8, v8, v11
	v_max_u32_e32 v11, v12, v15
	v_min_u32_e32 v12, v12, v15
	v_max_u32_e32 v15, v5, v4
	v_min_u32_e32 v17, v5, v4
	v_max_u32_e32 v18, v9, v7
	v_min_u32_e32 v19, v9, v7
	v_max_u32_e32 v20, v1, v0
	v_min_u32_e32 v21, v1, v0
	s_nop 1
	v_mov_b32_dpp v0, v21 quad_perm:[2,3,0,1] row_mask:0xf bank_mask:0xf
	v_mov_b32_dpp v1, v20 quad_perm:[2,3,0,1] row_mask:0xf bank_mask:0xf
	v_mov_b32_dpp v4, v19 quad_perm:[2,3,0,1] row_mask:0xf bank_mask:0xf
	v_mov_b32_dpp v5, v18 quad_perm:[2,3,0,1] row_mask:0xf bank_mask:0xf
	v_mov_b32_dpp v7, v17 quad_perm:[2,3,0,1] row_mask:0xf bank_mask:0xf
	v_mov_b32_dpp v9, v15 quad_perm:[2,3,0,1] row_mask:0xf bank_mask:0xf
	v_mov_b32_dpp v22, v12 quad_perm:[2,3,0,1] row_mask:0xf bank_mask:0xf
	v_mov_b32_dpp v23, v11 quad_perm:[2,3,0,1] row_mask:0xf bank_mask:0xf
	v_mov_b32_dpp v24, v8 quad_perm:[2,3,0,1] row_mask:0xf bank_mask:0xf
	v_mov_b32_dpp v25, v16 quad_perm:[2,3,0,1] row_mask:0xf bank_mask:0xf
	v_mov_b32_dpp v26, v10 quad_perm:[2,3,0,1] row_mask:0xf bank_mask:0xf
	v_mov_b32_dpp v27, v14 quad_perm:[2,3,0,1] row_mask:0xf bank_mask:0xf
	v_mov_b32_dpp v28, v6 quad_perm:[2,3,0,1] row_mask:0xf bank_mask:0xf
	v_mov_b32_dpp v29, v13 quad_perm:[2,3,0,1] row_mask:0xf bank_mask:0xf
	v_mov_b32_dpp v30, v3 quad_perm:[2,3,0,1] row_mask:0xf bank_mask:0xf
	v_mov_b32_dpp v31, v2 quad_perm:[2,3,0,1] row_mask:0xf bank_mask:0xf
	s_waitcnt lgkmcnt(0)
	v_max_u32_e32 v0, v2, v0
	v_max_u32_e32 v1, v3, v1
	v_max_u32_e32 v2, v13, v4
	v_max_u32_e32 v3, v6, v5
	v_max_u32_e32 v4, v14, v7
	v_max_u32_e32 v5, v10, v9
	v_max_u32_e32 v6, v16, v22
	v_max_u32_e32 v7, v8, v23
	v_max_u32_e32 v8, v11, v24
	v_max_u32_e32 v9, v12, v25
	v_max_u32_e32 v10, v15, v26
	v_max_u32_e32 v11, v17, v27
	v_max_u32_e32 v12, v18, v28
	v_max_u32_e32 v13, v19, v29
	v_max_u32_e32 v14, v20, v30
	v_max_u32_e32 v15, v21, v31
	v_max_u32_e32 v16, v0, v8
	v_max_u32_e32 v17, v1, v9
	v_max_u32_e32 v18, v2, v10
	v_max_u32_e32 v19, v3, v11
	v_max_u32_e32 v20, v4, v12
	v_max_u32_e32 v21, v5, v13
	v_max_u32_e32 v22, v6, v14
	v_max_u32_e32 v23, v7, v15
	s_and_saveexec_b64 s[16:17], s[4:5]
	s_cbranch_execz .LBB0_69
	v_max_u32_e32 v24, v16, v20
	v_max_u32_e32 v25, v18, v22
	v_max_u32_e32 v27, v17, v21
	v_max_u32_e32 v28, v19, v23
	v_min_u32_e32 v26, v24, v25
	v_min_u32_e32 v29, v27, v28
	v_max_u32_e32 v24, v24, v25
	v_max_u32_e32 v25, v27, v28
	v_min_u32_e32 v30, v26, v29
	v_max_u32_e32 v29, v26, v29
	v_min_u32_e32 v26, v24, v25
	v_max_u32_e32 v24, v24, v25
	v_xor_b32_e32 v25, -1, v26
	v_xor_b32_e32 v24, -1, v24
	v_and_b32_e32 v25, 0x7f, v25
	v_and_b32_e32 v24, 0x7f, v24
	v_lshl_add_u32 v26, v24, 2, v169
	v_lshl_add_u32 v27, v25, 2, v169
	ds_read_b32 v26, v26 offset:17408
	ds_read_b32 v27, v27 offset:17408
	v_xor_b32_e32 v28, -1, v29
	s_waitcnt lgkmcnt(0)
	ds_write_b64 v184, v[26:27] offset:53312
	v_xor_b32_e32 v26, -1, v30
	v_and_b32_e32 v27, 0x7f, v26
	v_and_b32_e32 v26, 0x7f, v28
	v_lshl_add_u32 v28, v26, 2, v169
	ds_write2_b64 v116, v[24:25], v[26:27] offset0:8 offset1:9
	v_lshl_add_u32 v24, v27, 2, v169
	ds_read_b32 v28, v28 offset:17408
	ds_read_b32 v29, v24 offset:17408
	s_waitcnt lgkmcnt(0)
	ds_write_b64 v184, v[28:29] offset:53320

; DI unsigned fkey(float f) { const unsigned u = __float_as_uint(f); return (u & 0x80000000u) ? ~u : (u | 0x80000000u); }
; DI void topk_phase(unsigned char* smem_, const bf16_t* __restrict__ qp, const bf16_t* __restrict__ keys, int* __restrict__ eidx, float* __restrict__ gate) {
;     ...
;     __syncthreads();
;     constexpr unsigned KT[13] = {0x03020100u, 0x07060504u, 0x0b0a0908u, 0x0f0e0d0cu, 0x13121110u, 0x17161514u, 0x23222120u, 0x32313024u, 0x42414033u, 0x61605150u, 0x90807170u, 0xd0c0b0a0u, 0x0000f0e0u};
;     unsigned c16[16];
; #pragma unroll
;     for (int i = 0; i < 13; ++i) {
;         const unsigned ab = (KT[i] >> (8 * q)) & 255u;
;         const float c = SV[row * 32 + (ab >> 4)] + SV[row * 32 + 16 + (ab & 15u)];
;         c16[i] = (fkey(c) & ~255u) | (255u - ab);
;     }
.LBB0_75:
	s_or_b64 exec, exec, s[16:17]
	s_waitcnt lgkmcnt(0)
	s_barrier
	ds_read_b96 v[0:2], v175 offset:53248
	ds_read_b32 v5, v186 offset:53312
	ds_read_b32 v3, v188 offset:53312
	ds_read_b32 v4, v175 offset:53312
	s_mov_b32 s16, 0xff61b1e6
	s_waitcnt lgkmcnt(3)
	v_mov_b32_e32 v7, v2
	s_waitcnt lgkmcnt(2)
	v_add_f32_e32 v2, v0, v5
	v_ashrrev_i32_e32 v5, 31, v2


; DI unsigned fkey(float f) { const unsigned u = __float_as_uint(f); return (u & 0x80000000u) ? ~u : (u | 0x80000000u); }
; DI void topk_phase(unsigned char* smem_, const bf16_t* __restrict__ qp, const bf16_t* __restrict__ keys, int* __restrict__ eidx, float* __restrict__ gate) {
;     ...
;     constexpr unsigned KT[13] = {0x03020100u, 0x07060504u, 0x0b0a0908u, 0x0f0e0d0cu, 0x13121110u, 0x17161514u, 0x23222120u, 0x32313024u, 0x42414033u, 0x61605150u, 0x90807170u, 0xd0c0b0a0u, 0x0000f0e0u};
;     unsigned c16[16];
; #pragma unroll
;     for (int i = 0; i < 13; ++i) {
;         const unsigned ab = (KT[i] >> (8 * q)) & 255u;
;         const float c = SV[row * 32 + (ab >> 4)] + SV[row * 32 + 16 + (ab & 15u)];
;         c16[i] = (fkey(c) & ~255u) | (255u - ab);
;     }
;     if (q >= 2) c16[12] = 0u;
	v_mov_b32_e32 v6, v1
	v_or_b32_e32 v158, s24, v164
	v_bitop3_b32 v2, v5, s98, v2 bitop3:0x56
	v_and_b32_e32 v2, 0xffffff00, v2
	v_bitop3_b32 v5, v2, s71, v185 bitop3:0x36
	ds_read_b32 v2, v190 offset:53312
	ds_read_b32 v9, v211 offset:53312
	ds_read_b32 v8, v213 offset:53312
	ds_read_b32 v10, v215 offset:53312
	ds_read_b32 v11, v217 offset:53312
	ds_read_b32 v13, v219 offset:53248
	ds_read_b32 v15, v220 offset:53312
	ds_read_b32 v12, v222 offset:53248
	s_waitcnt lgkmcnt(7)
	v_pk_add_f32 v[2:3], v[0:1], v[2:3] op_sel_hi:[0,1]
	v_ashrrev_i32_e32 v14, 31, v3


; DI unsigned fkey(float f) { const unsigned u = __float_as_uint(f); return (u & 0x80000000u) ? ~u : (u | 0x80000000u); }
; DI void topk_phase(unsigned char* smem_, const bf16_t* __restrict__ qp, const bf16_t* __restrict__ keys, int* __restrict__ eidx, float* __restrict__ gate) {
;     ...
;     constexpr unsigned KT[13] = {0x03020100u, 0x07060504u, 0x0b0a0908u, 0x0f0e0d0cu, 0x13121110u, 0x17161514u, 0x23222120u, 0x32313024u, 0x42414033u, 0x61605150u, 0x90807170u, 0xd0c0b0a0u, 0x0000f0e0u};
;     unsigned c16[16];
; #pragma unroll
;     for (int i = 0; i < 13; ++i) {
;         const unsigned ab = (KT[i] >> (8 * q)) & 255u;
;         const float c = SV[row * 32 + (ab >> 4)] + SV[row * 32 + 16 + (ab & 15u)];
;         c16[i] = (fkey(c) & ~255u) | (255u - ab);
;     }
;     if (q >= 2) c16[12] = 0u;
	v_ashrrev_i32_e32 v159, 31, v158
	v_lshlrev_b64 v[158:159], 7, v[158:159]
	v_bitop3_b32 v3, v14, s98, v3 bitop3:0x56
	v_and_b32_e32 v3, 0xffffff00, v3
	v_bitop3_b32 v16, v3, s71, v187 bitop3:0x36
	v_ashrrev_i32_e32 v3, 31, v2


; DI unsigned fkey(float f) { const unsigned u = __float_as_uint(f); return (u & 0x80000000u) ? ~u : (u | 0x80000000u); }
; DI void topk_phase(unsigned char* smem_, const bf16_t* __restrict__ qp, const bf16_t* __restrict__ keys, int* __restrict__ eidx, float* __restrict__ gate) {
;     ...
;     constexpr unsigned KT[13] = {0x03020100u, 0x07060504u, 0x0b0a0908u, 0x0f0e0d0cu, 0x13121110u, 0x17161514u, 0x23222120u, 0x32313024u, 0x42414033u, 0x61605150u, 0x90807170u, 0xd0c0b0a0u, 0x0000f0e0u};
;     unsigned c16[16];
; #pragma unroll
;     for (int i = 0; i < 13; ++i) {
;         const unsigned ab = (KT[i] >> (8 * q)) & 255u;
;         const float c = SV[row * 32 + (ab >> 4)] + SV[row * 32 + 16 + (ab & 15u)];
;         c16[i] = (fkey(c) & ~255u) | (255u - ab);
;     }
;     if (q >= 2) c16[12] = 0u;
	v_lshl_or_b32 v158, s23, 4, v158
	v_lshlrev_b64 v[158:159], 2, v[158:159]
	v_bitop3_b32 v2, v3, s98, v2 bitop3:0x56
	v_and_b32_e32 v2, 0xffffff00, v2
	v_bitop3_b32 v17, v2, s71, v189 bitop3:0x36
	v_mov_b32_e32 v2, v1
	v_mov_b32_e32 v3, v0
	s_waitcnt lgkmcnt(5)
	v_pk_add_f32 v[0:1], v[2:3], v[8:9]
	s_nop 0
	v_ashrrev_i32_e32 v2, 31, v1


; DI unsigned fkey(float f) { const unsigned u = __float_as_uint(f); return (u & 0x80000000u) ? ~u : (u | 0x80000000u); }
; DI void topk_phase(unsigned char* smem_, const bf16_t* __restrict__ qp, const bf16_t* __restrict__ keys, int* __restrict__ eidx, float* __restrict__ gate) {
;     ...
;     constexpr unsigned KT[13] = {0x03020100u, 0x07060504u, 0x0b0a0908u, 0x0f0e0d0cu, 0x13121110u, 0x17161514u, 0x23222120u, 0x32313024u, 0x42414033u, 0x61605150u, 0x90807170u, 0xd0c0b0a0u, 0x0000f0e0u};
;     unsigned c16[16];
; #pragma unroll
;     for (int i = 0; i < 13; ++i) {
;         const unsigned ab = (KT[i] >> (8 * q)) & 255u;
;         const float c = SV[row * 32 + (ab >> 4)] + SV[row * 32 + 16 + (ab & 15u)];
;         c16[i] = (fkey(c) & ~255u) | (255u - ab);
;     }
;     if (q >= 2) c16[12] = 0u;
	s_nop 1
	v_bitop3_b32 v1, v2, s98, v1 bitop3:0x56
	v_and_b32_e32 v1, 0xffffff00, v1
	v_bitop3_b32 v18, v1, s71, v191 bitop3:0x36
	v_ashrrev_i32_e32 v1, 31, v0


; DI unsigned fkey(float f) { const unsigned u = __float_as_uint(f); return (u & 0x80000000u) ? ~u : (u | 0x80000000u); }
; DI void topk_phase(unsigned char* smem_, const bf16_t* __restrict__ qp, const bf16_t* __restrict__ keys, int* __restrict__ eidx, float* __restrict__ gate) {
;     ...
;     constexpr unsigned KT[13] = {0x03020100u, 0x07060504u, 0x0b0a0908u, 0x0f0e0d0cu, 0x13121110u, 0x17161514u, 0x23222120u, 0x32313024u, 0x42414033u, 0x61605150u, 0x90807170u, 0xd0c0b0a0u, 0x0000f0e0u};
;     unsigned c16[16];
; #pragma unroll
;     for (int i = 0; i < 13; ++i) {
;         const unsigned ab = (KT[i] >> (8 * q)) & 255u;
;         const float c = SV[row * 32 + (ab >> 4)] + SV[row * 32 + 16 + (ab & 15u)];
;         c16[i] = (fkey(c) & ~255u) | (255u - ab);
;     }
;     if (q >= 2) c16[12] = 0u;
	s_nop 1
	v_bitop3_b32 v0, v1, s98, v0 bitop3:0x56
	v_and_b32_e32 v0, 0xffffff00, v0
	v_bitop3_b32 v19, v0, s71, v212 bitop3:0x36
	s_waitcnt lgkmcnt(3)
	v_pk_add_f32 v[0:1], v[6:7], v[10:11]
	s_nop 0
	v_ashrrev_i32_e32 v2, 31, v0


; DI unsigned fkey(float f) { const unsigned u = __float_as_uint(f); return (u & 0x80000000u) ? ~u : (u | 0x80000000u); }
; DI void topk_phase(unsigned char* smem_, const bf16_t* __restrict__ qp, const bf16_t* __restrict__ keys, int* __restrict__ eidx, float* __restrict__ gate) {
;     ...
;     constexpr unsigned KT[13] = {0x03020100u, 0x07060504u, 0x0b0a0908u, 0x0f0e0d0cu, 0x13121110u, 0x17161514u, 0x23222120u, 0x32313024u, 0x42414033u, 0x61605150u, 0x90807170u, 0xd0c0b0a0u, 0x0000f0e0u};
;     unsigned c16[16];
; #pragma unroll
;     for (int i = 0; i < 13; ++i) {
;         const unsigned ab = (KT[i] >> (8 * q)) & 255u;
;         const float c = SV[row * 32 + (ab >> 4)] + SV[row * 32 + 16 + (ab & 15u)];
;         c16[i] = (fkey(c) & ~255u) | (255u - ab);
;     }
;     if (q >= 2) c16[12] = 0u;
	s_nop 1
	v_bitop3_b32 v0, v2, s98, v0 bitop3:0x56
	v_and_b32_e32 v0, 0xffffff00, v0
	v_bitop3_b32 v10, v0, s71, v214 bitop3:0x36
	v_ashrrev_i32_e32 v0, 31, v1


; DI unsigned fkey(float f) { const unsigned u = __float_as_uint(f); return (u & 0x80000000u) ? ~u : (u | 0x80000000u); }
; DI void topk_phase(unsigned char* smem_, const bf16_t* __restrict__ qp, const bf16_t* __restrict__ keys, int* __restrict__ eidx, float* __restrict__ gate) {
;     ...
;     constexpr unsigned KT[13] = {0x03020100u, 0x07060504u, 0x0b0a0908u, 0x0f0e0d0cu, 0x13121110u, 0x17161514u, 0x23222120u, 0x32313024u, 0x42414033u, 0x61605150u, 0x90807170u, 0xd0c0b0a0u, 0x0000f0e0u};
;     unsigned c16[16];
; #pragma unroll
;     for (int i = 0; i < 13; ++i) {
;         const unsigned ab = (KT[i] >> (8 * q)) & 255u;
;         const float c = SV[row * 32 + (ab >> 4)] + SV[row * 32 + 16 + (ab & 15u)];
;         c16[i] = (fkey(c) & ~255u) | (255u - ab);
;     }
;     if (q >= 2) c16[12] = 0u;
	s_nop 1
	v_bitop3_b32 v0, v0, s98, v1 bitop3:0x56
	v_and_b32_e32 v0, 0xffffff00, v0
	v_bitop3_b32 v11, v0, s71, v216 bitop3:0x36
	ds_read_b32 v14, v223 offset:53312
	ds_read_b32 v1, v225 offset:53248
	ds_read_b32 v3, v226 offset:53312
	ds_read_b32 v0, v228 offset:53248
	ds_read_b32 v2, v229 offset:53312
	ds_read_b32 v7, v232 offset:53248
	ds_read_b32 v6, v233 offset:53248
	s_waitcnt lgkmcnt(6)
	v_pk_add_f32 v[8:9], v[12:13], v[14:15]
	s_waitcnt lgkmcnt(2)
	v_pk_add_f32 v[0:1], v[0:1], v[2:3]
	v_ashrrev_i32_e32 v12, 31, v9


; DI unsigned fkey(float f) { const unsigned u = __float_as_uint(f); return (u & 0x80000000u) ? ~u : (u | 0x80000000u); }
; DI void topk_phase(unsigned char* smem_, const bf16_t* __restrict__ qp, const bf16_t* __restrict__ keys, int* __restrict__ eidx, float* __restrict__ gate) {
;     ...
;     constexpr unsigned KT[13] = {0x03020100u, 0x07060504u, 0x0b0a0908u, 0x0f0e0d0cu, 0x13121110u, 0x17161514u, 0x23222120u, 0x32313024u, 0x42414033u, 0x61605150u, 0x90807170u, 0xd0c0b0a0u, 0x0000f0e0u};
;     unsigned c16[16];
; #pragma unroll
;     for (int i = 0; i < 13; ++i) {
;         const unsigned ab = (KT[i] >> (8 * q)) & 255u;
;         const float c = SV[row * 32 + (ab >> 4)] + SV[row * 32 + 16 + (ab & 15u)];
;         c16[i] = (fkey(c) & ~255u) | (255u - ab);
;     }
;     if (q >= 2) c16[12] = 0u;
	v_ashrrev_i32_e32 v2, 31, v1

; DI unsigned fkey(float f) { const unsigned u = __float_as_uint(f); return (u & 0x80000000u) ? ~u : (u | 0x80000000u); }
; DI void topk_phase(unsigned char* smem_, const bf16_t* __restrict__ qp, const bf16_t* __restrict__ keys, int* __restrict__ eidx, float* __restrict__ gate) {
;     ...
;     constexpr unsigned KT[13] = {0x03020100u, 0x07060504u, 0x0b0a0908u, 0x0f0e0d0cu, 0x13121110u, 0x17161514u, 0x23222120u, 0x32313024u, 0x42414033u, 0x61605150u, 0x90807170u, 0xd0c0b0a0u, 0x0000f0e0u};
;     unsigned c16[16];
; #pragma unroll
;     for (int i = 0; i < 13; ++i) {
;         const unsigned ab = (KT[i] >> (8 * q)) & 255u;
;         const float c = SV[row * 32 + (ab >> 4)] + SV[row * 32 + 16 + (ab & 15u)];
;         c16[i] = (fkey(c) & ~255u) | (255u - ab);
;     }
;     if (q >= 2) c16[12] = 0u;
	v_bitop3_b32 v9, v12, s98, v9 bitop3:0x56
	v_ashrrev_i32_e32 v12, 31, v8


; DI unsigned fkey(float f) { const unsigned u = __float_as_uint(f); return (u & 0x80000000u) ? ~u : (u | 0x80000000u); }
; DI void topk_phase(unsigned char* smem_, const bf16_t* __restrict__ qp, const bf16_t* __restrict__ keys, int* __restrict__ eidx, float* __restrict__ gate) {
;     ...
;     constexpr unsigned KT[13] = {0x03020100u, 0x07060504u, 0x0b0a0908u, 0x0f0e0d0cu, 0x13121110u, 0x17161514u, 0x23222120u, 0x32313024u, 0x42414033u, 0x61605150u, 0x90807170u, 0xd0c0b0a0u, 0x0000f0e0u};
;     unsigned c16[16];
; #pragma unroll
;     for (int i = 0; i < 13; ++i) {
;         const unsigned ab = (KT[i] >> (8 * q)) & 255u;
;         const float c = SV[row * 32 + (ab >> 4)] + SV[row * 32 + 16 + (ab & 15u)];
;         c16[i] = (fkey(c) & ~255u) | (255u - ab);
;     }
;     if (q >= 2) c16[12] = 0u;
	v_and_b32_e32 v9, 0xffffff00, v9
	v_bitop3_b32 v9, v9, s71, v218 bitop3:0x36
	v_bitop3_b32 v8, v12, s98, v8 bitop3:0x56

; DI unsigned fkey(float f) { const unsigned u = __float_as_uint(f); return (u & 0x80000000u) ? ~u : (u | 0x80000000u); }
; DI void topk_phase(unsigned char* smem_, const bf16_t* __restrict__ qp, const bf16_t* __restrict__ keys, int* __restrict__ eidx, float* __restrict__ gate) {
;     ...
;     constexpr unsigned KT[13] = {0x03020100u, 0x07060504u, 0x0b0a0908u, 0x0f0e0d0cu, 0x13121110u, 0x17161514u, 0x23222120u, 0x32313024u, 0x42414033u, 0x61605150u, 0x90807170u, 0xd0c0b0a0u, 0x0000f0e0u};
;     unsigned c16[16];
; #pragma unroll
;     for (int i = 0; i < 13; ++i) {
;         const unsigned ab = (KT[i] >> (8 * q)) & 255u;
;         const float c = SV[row * 32 + (ab >> 4)] + SV[row * 32 + 16 + (ab & 15u)];
;         c16[i] = (fkey(c) & ~255u) | (255u - ab);
;     }
;     if (q >= 2) c16[12] = 0u;
	v_and_b32_e32 v8, 0xffffff00, v8
	v_bitop3_b32 v8, v8, s71, v221 bitop3:0x36
	v_bitop3_b32 v1, v2, s98, v1 bitop3:0x56
	v_and_b32_e32 v1, 0xffffff00, v1
	v_bitop3_b32 v2, v1, s71, v224 bitop3:0x36
	v_ashrrev_i32_e32 v1, 31, v0


; DI unsigned fkey(float f) { const unsigned u = __float_as_uint(f); return (u & 0x80000000u) ? ~u : (u | 0x80000000u); }
; DI void topk_phase(unsigned char* smem_, const bf16_t* __restrict__ qp, const bf16_t* __restrict__ keys, int* __restrict__ eidx, float* __restrict__ gate) {
;     ...
;     constexpr unsigned KT[13] = {0x03020100u, 0x07060504u, 0x0b0a0908u, 0x0f0e0d0cu, 0x13121110u, 0x17161514u, 0x23222120u, 0x32313024u, 0x42414033u, 0x61605150u, 0x90807170u, 0xd0c0b0a0u, 0x0000f0e0u};
;     unsigned c16[16];
; #pragma unroll
;     for (int i = 0; i < 13; ++i) {
;         const unsigned ab = (KT[i] >> (8 * q)) & 255u;
;         const float c = SV[row * 32 + (ab >> 4)] + SV[row * 32 + 16 + (ab & 15u)];
;         c16[i] = (fkey(c) & ~255u) | (255u - ab);
;     }
;     if (q >= 2) c16[12] = 0u;
	v_max_u32_e32 v12, v19, v10
	v_min_u32_e32 v10, v19, v10
	v_bitop3_b32 v0, v1, s98, v0 bitop3:0x56
	v_and_b32_e32 v0, 0xffffff00, v0
	v_bitop3_b32 v3, v0, s71, v227 bitop3:0x36
	s_waitcnt lgkmcnt(0)
	v_pk_add_f32 v[0:1], v[6:7], v[4:5] op_sel_hi:[1,0]
	v_min_u32_e32 v7, v18, v17
	v_ashrrev_i32_e32 v4, 31, v1


; DI unsigned fkey(float f) { const unsigned u = __float_as_uint(f); return (u & 0x80000000u) ? ~u : (u | 0x80000000u); }
; DI void topk_phase(unsigned char* smem_, const bf16_t* __restrict__ qp, const bf16_t* __restrict__ keys, int* __restrict__ eidx, float* __restrict__ gate) {
;     ...
;     constexpr unsigned KT[13] = {0x03020100u, 0x07060504u, 0x0b0a0908u, 0x0f0e0d0cu, 0x13121110u, 0x17161514u, 0x23222120u, 0x32313024u, 0x42414033u, 0x61605150u, 0x90807170u, 0xd0c0b0a0u, 0x0000f0e0u};
;     unsigned c16[16];
; #pragma unroll
;     for (int i = 0; i < 13; ++i) {
;         const unsigned ab = (KT[i] >> (8 * q)) & 255u;
;         const float c = SV[row * 32 + (ab >> 4)] + SV[row * 32 + 16 + (ab & 15u)];
;         c16[i] = (fkey(c) & ~255u) | (255u - ab);
;     }
;     if (q >= 2) c16[12] = 0u;
	v_max_u32_e32 v13, v9, v11
	v_min_u32_e32 v9, v9, v11
	v_bitop3_b32 v1, v4, s98, v1 bitop3:0x56
	v_and_b32_e32 v1, 0xffffff00, v1
	v_ashrrev_i32_e32 v4, 31, v0


; template <int N> DI void bitonic_sort_desc(unsigned (&v)[N]) {
; #pragma unroll
;     for (int k = 2; k <= N; k <<= 1)
; #pragma unroll
;         for (int j = k >> 1; j > 0; j >>= 1)
; #pragma unroll
;             for (int i = 0; i < N; ++i) { const int l = i ^ j; if (l > i) { if ((i & k) == 0) cswap(v[i], v[l]); else cswap(v[l], v[i]); } }
; }
; DI void merge_top16(unsigned (&v)[16], int st) {
;     unsigned x[16];
; #pragma unroll
;     for (int i = 0; i < 16; ++i) x[i] = (unsigned)__shfl_xor((int)v[15 - i], st);
; #pragma unroll
;     for (int i = 0; i < 16; ++i) v[i] = max(v[i], x[i]);
; #pragma unroll
;     for (int j = 8; j > 0; j >>= 1)
; #pragma unroll
;         for (int i = 0; i < 16; ++i) { const int l = i ^ j; if (l > i) cswap(v[i], v[l]); }
; }
; DI void topk_phase(unsigned char* smem_, const bf16_t* __restrict__ qp, const bf16_t* __restrict__ keys, int* __restrict__ eidx, float* __restrict__ gate) {
;     ...
;     if (q >= 2) c16[12] = 0u;
;     c16[13] = 0u; c16[14] = 0u; c16[15] = 0u;
;     bitonic_sort_desc<16>(c16);
;     merge_top16(c16, 1);
;     merge_top16(c16, 2);
	v_bitop3_b32 v1, v1, s71, v230 bitop3:0x36
	v_max_u32_e32 v11, v8, v2
	v_bitop3_b32 v0, v4, s98, v0 bitop3:0x56
	v_and_b32_e32 v0, 0xffffff00, v0
	v_max_u32_e32 v4, v5, v16
	v_min_u32_e32 v5, v5, v16
	v_max_u32_e32 v6, v18, v17
	v_min_u32_e32 v2, v8, v2
	v_max_u32_e32 v8, v1, v3
	v_min_u32_e32 v1, v1, v3
	v_bitop3_b32 v0, v0, s71, v231 bitop3:0x36
	v_max_u32_e32 v3, v4, v7
	v_min_u32_e32 v4, v4, v7
	v_max_u32_e32 v7, v5, v6
	v_min_u32_e32 v5, v5, v6
	v_max_u32_e32 v6, v9, v12
	v_min_u32_e32 v9, v9, v12
	v_max_u32_e32 v12, v13, v10
	v_min_u32_e32 v10, v13, v10
	v_max_u32_e32 v13, v11, v1
	v_min_u32_e32 v1, v11, v1
	v_max_u32_e32 v11, v2, v8
	v_min_u32_e32 v2, v2, v8
	v_cndmask_b32_e64 v0, v0, 0, s[2:3]
	v_max_u32_e32 v8, v3, v7
	v_min_u32_e32 v3, v3, v7
	v_max_u32_e32 v7, v4, v5
	v_min_u32_e32 v4, v4, v5
	v_max_u32_e32 v5, v10, v9
	v_min_u32_e32 v9, v10, v9
	v_max_u32_e32 v10, v12, v6
	v_min_u32_e32 v6, v12, v6
	v_max_u32_e32 v12, v13, v11
	v_min_u32_e32 v11, v13, v11
	v_max_u32_e32 v13, v1, v2
	v_min_u32_e32 v1, v1, v2
	v_max_u32_e32 v2, v8, v9
	v_min_u32_e32 v8, v8, v9
	v_max_u32_e32 v9, v3, v5
	v_min_u32_e32 v3, v3, v5
	v_max_u32_e32 v5, v7, v6
	v_min_u32_e32 v6, v7, v6
	v_max_u32_e32 v7, v4, v10
	v_min_u32_e32 v4, v4, v10
	v_max_u32_e32 v10, v0, v1
	v_min_u32_e32 v0, v0, v1
	v_max_u32_e32 v1, v2, v5
	v_min_u32_e32 v2, v2, v5
	v_max_u32_e32 v5, v9, v7
	v_min_u32_e32 v7, v9, v7
	v_max_u32_e32 v9, v8, v6
	v_min_u32_e32 v6, v8, v6
	v_max_u32_e32 v8, v3, v4
	v_min_u32_e32 v3, v3, v4
	v_max_u32_e32 v4, v13, v12
	v_min_u32_e32 v12, v13, v12
	v_max_u32_e32 v13, v10, v11
	v_min_u32_e32 v10, v10, v11
	v_max_u32_e32 v11, v1, v5
	v_min_u32_e32 v1, v1, v5
	v_max_u32_e32 v5, v2, v7
	v_min_u32_e32 v2, v2, v7
	v_max_u32_e32 v7, v9, v8
	v_min_u32_e32 v8, v9, v8
	v_max_u32_e32 v9, v6, v3
	v_min_u32_e32 v3, v6, v3
	v_max_u32_e32 v6, v10, v12
	v_min_u32_e32 v10, v10, v12
	v_max_u32_e32 v12, v13, v4
	v_min_u32_e32 v4, v13, v4
	v_max_u32_e32 v13, v2, v0
	v_min_u32_e32 v0, v2, v0
	v_max_u32_e32 v2, v7, v10
	v_min_u32_e32 v7, v7, v10
	v_max_u32_e32 v10, v8, v6
	v_min_u32_e32 v6, v8, v6
	v_max_u32_e32 v8, v9, v4
	v_min_u32_e32 v4, v9, v4
	v_max_u32_e32 v9, v3, v12
	v_min_u32_e32 v3, v3, v12
	v_max_u32_e32 v12, v11, v2
	v_min_u32_e32 v2, v11, v2
	v_max_u32_e32 v11, v1, v10
	v_min_u32_e32 v1, v1, v10
	v_max_u32_e32 v10, v5, v8
	v_min_u32_e32 v5, v5, v8
	v_max_u32_e32 v8, v13, v9
	v_min_u32_e32 v9, v13, v9
	v_max_u32_e32 v13, v0, v3
	v_min_u32_e32 v0, v0, v3
	v_max_u32_e32 v3, v12, v10
	v_min_u32_e32 v10, v12, v10
	v_max_u32_e32 v12, v11, v8
	v_min_u32_e32 v8, v11, v8
	v_max_u32_e32 v11, v2, v5
	v_min_u32_e32 v2, v2, v5
	v_max_u32_e32 v5, v1, v9
	v_min_u32_e32 v1, v1, v9
	v_max_u32_e32 v9, v7, v4
	v_min_u32_e32 v4, v7, v4
	v_max_u32_e32 v7, v6, v13
	v_min_u32_e32 v6, v6, v13
	v_max_u32_e32 v13, v3, v12
	v_min_u32_e32 v3, v3, v12
	v_max_u32_e32 v12, v10, v8
	v_min_u32_e32 v8, v10, v8
	v_max_u32_e32 v10, v11, v5
	v_min_u32_e32 v5, v11, v5
	v_max_u32_e32 v11, v2, v1
	v_min_u32_e32 v1, v2, v1
	v_max_u32_e32 v2, v9, v7
	v_min_u32_e32 v7, v9, v7
	v_max_u32_e32 v9, v4, v6
	v_min_u32_e32 v4, v4, v6
	s_nop 1
	v_mov_b32_dpp v6, v0 quad_perm:[1,0,3,2] row_mask:0xf bank_mask:0xf
	v_mov_b32_dpp v14, v4 quad_perm:[1,0,3,2] row_mask:0xf bank_mask:0xf
	v_mov_b32_dpp v15, v9 quad_perm:[1,0,3,2] row_mask:0xf bank_mask:0xf
	v_mov_b32_dpp v16, v7 quad_perm:[1,0,3,2] row_mask:0xf bank_mask:0xf
	v_mov_b32_dpp v17, v2 quad_perm:[1,0,3,2] row_mask:0xf bank_mask:0xf
	v_mov_b32_dpp v18, v1 quad_perm:[1,0,3,2] row_mask:0xf bank_mask:0xf
	v_mov_b32_dpp v19, v11 quad_perm:[1,0,3,2] row_mask:0xf bank_mask:0xf
	v_mov_b32_dpp v20, v5 quad_perm:[1,0,3,2] row_mask:0xf bank_mask:0xf
	v_mov_b32_dpp v21, v10 quad_perm:[1,0,3,2] row_mask:0xf bank_mask:0xf
	v_mov_b32_dpp v22, v8 quad_perm:[1,0,3,2] row_mask:0xf bank_mask:0xf
	v_mov_b32_dpp v23, v12 quad_perm:[1,0,3,2] row_mask:0xf bank_mask:0xf
	v_mov_b32_dpp v24, v3 quad_perm:[1,0,3,2] row_mask:0xf bank_mask:0xf
	v_mov_b32_dpp v25, v13 quad_perm:[1,0,3,2] row_mask:0xf bank_mask:0xf
	s_waitcnt lgkmcnt(0)
	v_max_u32_e32 v6, v8, v6
	v_max_u32_e32 v8, v10, v14
	v_max_u32_e32 v5, v5, v15
	v_max_u32_e32 v10, v11, v16
	v_max_u32_e32 v1, v1, v17
	v_max_u32_e32 v2, v2, v18
	v_max_u32_e32 v7, v7, v19
	v_max_u32_e32 v9, v9, v20
	v_max_u32_e32 v4, v4, v21
	v_max_u32_e32 v0, v0, v22
	v_max_u32_e32 v11, v13, v2
	v_min_u32_e32 v2, v13, v2
	v_max_u32_e32 v13, v3, v7
	v_min_u32_e32 v3, v3, v7
	v_max_u32_e32 v7, v12, v9
	v_min_u32_e32 v9, v12, v9
	v_max_u32_e32 v12, v6, v4
	v_min_u32_e32 v4, v6, v4
	v_max_u32_e32 v6, v8, v0
	v_min_u32_e32 v0, v8, v0
	v_max_u32_e32 v8, v5, v23
	v_min_u32_e32 v5, v5, v23
	v_max_u32_e32 v14, v10, v24
	v_min_u32_e32 v10, v10, v24
	v_max_u32_e32 v15, v1, v25
	v_min_u32_e32 v1, v1, v25
	v_max_u32_e32 v16, v11, v6
	v_min_u32_e32 v6, v11, v6
	v_max_u32_e32 v11, v13, v8
	v_min_u32_e32 v8, v13, v8
	v_max_u32_e32 v13, v7, v14
	v_min_u32_e32 v7, v7, v14
	v_max_u32_e32 v14, v12, v15
	v_min_u32_e32 v12, v12, v15
	v_max_u32_e32 v15, v2, v0
	v_min_u32_e32 v0, v2, v0
	v_max_u32_e32 v2, v3, v5
	v_min_u32_e32 v3, v3, v5
	v_max_u32_e32 v5, v9, v10
	v_min_u32_e32 v9, v9, v10
	v_max_u32_e32 v10, v4, v1
	v_min_u32_e32 v1, v4, v1
	v_max_u32_e32 v4, v16, v13
	v_min_u32_e32 v13, v16, v13
	v_max_u32_e32 v16, v11, v14
	v_min_u32_e32 v11, v11, v14
	v_max_u32_e32 v14, v6, v7
	v_min_u32_e32 v6, v6, v7
	v_max_u32_e32 v7, v8, v12
	v_min_u32_e32 v8, v8, v12
	v_max_u32_e32 v12, v15, v5
	v_min_u32_e32 v5, v15, v5
	v_max_u32_e32 v15, v2, v10
	v_min_u32_e32 v2, v2, v10
	v_max_u32_e32 v10, v0, v9
	v_min_u32_e32 v0, v0, v9
	v_max_u32_e32 v9, v3, v1
	v_min_u32_e32 v1, v3, v1
; DI void merge_top16(unsigned (&v)[16], int st) {
;     unsigned x[16];
; #pragma unroll
;     for (int i = 0; i < 16; ++i) x[i] = (unsigned)__shfl_xor((int)v[15 - i], st);
; #pragma unroll
;     for (int i = 0; i < 16; ++i) v[i] = max(v[i], x[i]);
; #pragma unroll
;     for (int j = 8; j > 0; j >>= 1)
; #pragma unroll
;         for (int i = 0; i < 16; ++i) { const int l = i ^ j; if (l > i) cswap(v[i], v[l]); }
; }
; DI void topk_phase(unsigned char* smem_, const bf16_t* __restrict__ qp, const bf16_t* __restrict__ keys, int* __restrict__ eidx, float* __restrict__ gate) {
;     ...
;     float bv[16]; int be[16]; float mx = -3.0e38f;
; #pragma unroll
;     for (int i = 0; i < 16; ++i) {
;         const int ab = 255 - (int)(c16[i] & 255u), a = ab >> 4, b = ab & 15;
;         bv[i] = SV[row * 32 + a] + SV[row * 32 + 16 + b];
;         be[i] = SI[row * 32 + a] * 128 + SI[row * 32 + 16 + b];
;         mx = fmaxf(mx, bv[i]);
;     }
	v_max_u32_e32 v3, v4, v16
	v_min_u32_e32 v4, v4, v16
	v_max_u32_e32 v16, v13, v11
	v_min_u32_e32 v11, v13, v11
	v_max_u32_e32 v13, v14, v7
	v_min_u32_e32 v7, v14, v7
	v_max_u32_e32 v14, v6, v8
	v_min_u32_e32 v6, v6, v8
	v_max_u32_e32 v8, v12, v15
	v_min_u32_e32 v12, v12, v15
	v_max_u32_e32 v15, v5, v2
	v_min_u32_e32 v2, v5, v2
	v_max_u32_e32 v5, v10, v9
	v_min_u32_e32 v9, v10, v9
	v_max_u32_e32 v10, v0, v1
	v_min_u32_e32 v0, v0, v1
	s_nop 1
	v_mov_b32_dpp v1, v0 quad_perm:[2,3,0,1] row_mask:0xf bank_mask:0xf
	v_mov_b32_dpp v17, v10 quad_perm:[2,3,0,1] row_mask:0xf bank_mask:0xf
	v_mov_b32_dpp v18, v9 quad_perm:[2,3,0,1] row_mask:0xf bank_mask:0xf
	v_mov_b32_dpp v19, v5 quad_perm:[2,3,0,1] row_mask:0xf bank_mask:0xf
	v_mov_b32_dpp v20, v2 quad_perm:[2,3,0,1] row_mask:0xf bank_mask:0xf
	v_mov_b32_dpp v21, v15 quad_perm:[2,3,0,1] row_mask:0xf bank_mask:0xf
	v_mov_b32_dpp v22, v12 quad_perm:[2,3,0,1] row_mask:0xf bank_mask:0xf
	v_mov_b32_dpp v23, v8 quad_perm:[2,3,0,1] row_mask:0xf bank_mask:0xf
	v_mov_b32_dpp v24, v6 quad_perm:[2,3,0,1] row_mask:0xf bank_mask:0xf
	v_mov_b32_dpp v25, v14 quad_perm:[2,3,0,1] row_mask:0xf bank_mask:0xf
	v_mov_b32_dpp v26, v7 quad_perm:[2,3,0,1] row_mask:0xf bank_mask:0xf
	v_mov_b32_dpp v27, v13 quad_perm:[2,3,0,1] row_mask:0xf bank_mask:0xf
	v_mov_b32_dpp v28, v11 quad_perm:[2,3,0,1] row_mask:0xf bank_mask:0xf
	v_mov_b32_dpp v29, v16 quad_perm:[2,3,0,1] row_mask:0xf bank_mask:0xf
	v_mov_b32_dpp v30, v4 quad_perm:[2,3,0,1] row_mask:0xf bank_mask:0xf
	v_mov_b32_dpp v31, v3 quad_perm:[2,3,0,1] row_mask:0xf bank_mask:0xf
	s_waitcnt lgkmcnt(0)
	v_max_u32_e32 v1, v3, v1
	v_max_u32_e32 v3, v4, v17
	v_max_u32_e32 v4, v16, v18
	v_max_u32_e32 v11, v11, v19
	v_max_u32_e32 v13, v13, v20
	v_max_u32_e32 v7, v7, v21
	v_max_u32_e32 v14, v14, v22
	v_max_u32_e32 v6, v6, v23
	v_max_u32_e32 v8, v8, v24
	v_max_u32_e32 v12, v12, v25
	v_max_u32_e32 v15, v15, v26
	v_max_u32_e32 v2, v2, v27
	v_max_u32_e32 v5, v5, v28
	v_max_u32_e32 v9, v9, v29
	v_max_u32_e32 v10, v10, v30
	v_max_u32_e32 v0, v0, v31
	v_max_u32_e32 v16, v1, v8
	v_min_u32_e32 v1, v1, v8
	v_max_u32_e32 v8, v3, v12
	v_min_u32_e32 v3, v3, v12
	v_max_u32_e32 v12, v4, v15
	v_min_u32_e32 v4, v4, v15
	v_max_u32_e32 v15, v11, v2
	v_min_u32_e32 v2, v11, v2
	v_max_u32_e32 v11, v13, v5
	v_min_u32_e32 v5, v13, v5
	v_max_u32_e32 v13, v7, v9
	v_min_u32_e32 v7, v7, v9
	v_max_u32_e32 v9, v14, v10
	v_min_u32_e32 v10, v14, v10
	v_max_u32_e32 v14, v6, v0
	v_min_u32_e32 v0, v6, v0
	v_max_u32_e32 v6, v16, v11
	v_min_u32_e32 v11, v16, v11
	v_max_u32_e32 v16, v8, v13
	v_min_u32_e32 v8, v8, v13
	v_max_u32_e32 v13, v12, v9
	v_min_u32_e32 v9, v12, v9
	v_max_u32_e32 v12, v15, v14
	v_min_u32_e32 v14, v15, v14
	v_max_u32_e32 v15, v1, v5
	v_min_u32_e32 v1, v1, v5
	v_max_u32_e32 v5, v3, v7
	v_min_u32_e32 v3, v3, v7
	v_max_u32_e32 v7, v4, v10
	v_min_u32_e32 v4, v4, v10
	v_max_u32_e32 v10, v2, v0
	v_min_u32_e32 v0, v2, v0
	v_max_u32_e32 v2, v6, v13
	v_min_u32_e32 v6, v6, v13
	v_max_u32_e32 v13, v16, v12
	v_min_u32_e32 v12, v16, v12
	v_max_u32_e32 v16, v11, v9
	v_min_u32_e32 v9, v11, v9
	v_max_u32_e32 v11, v8, v14
	v_min_u32_e32 v8, v8, v14
	v_max_u32_e32 v14, v15, v7
	v_min_u32_e32 v7, v15, v7
	v_max_u32_e32 v15, v5, v10
	v_min_u32_e32 v5, v5, v10
	v_max_u32_e32 v10, v1, v4
	v_min_u32_e32 v1, v1, v4
	v_max_u32_e32 v4, v3, v0
	v_min_u32_e32 v0, v3, v0
	v_max_u32_e32 v3, v2, v13
	v_not_b32_e32 v17, v3
	v_min_u32_e32 v2, v2, v13
	v_max_u32_e32 v142, v1, v0
	v_min_u32_e32 v144, v1, v0
	v_lshrrev_b32_e32 v0, 4, v17
	v_not_b32_e32 v13, v2
	v_and_or_b32 v0, v0, 15, v174
	v_max_u32_e32 v18, v6, v12
	v_lshl_add_u32 v237, v0, 2, s19
	v_lshrrev_b32_e32 v0, 4, v13
	v_not_b32_e32 v19, v18
	v_and_or_b32 v0, v0, 15, v174
	v_min_u32_e32 v6, v6, v12
	v_bitop3_b32 v1, v3, 15, v3 bitop3:0xc
	v_lshl_add_u32 v239, v0, 2, s19
	v_lshrrev_b32_e32 v0, 4, v19
	v_not_b32_e32 v12, v6
	v_lshl_add_u32 v238, v1, 2, v184
	v_bitop3_b32 v1, v2, 15, v2 bitop3:0xc
	v_and_or_b32 v0, v0, 15, v174
	v_lshl_add_u32 v240, v1, 2, v175
	v_bitop3_b32 v1, v18, 15, v18 bitop3:0xc
	v_lshl_add_u32 v241, v0, 2, s19
	v_lshrrev_b32_e32 v0, 4, v12
	v_lshl_add_u32 v242, v1, 2, v184
	v_bitop3_b32 v1, v6, 15, v6 bitop3:0xc
	v_and_or_b32 v0, v0, 15, v174
	v_max_u32_e32 v30, v7, v5
	v_min_u32_e32 v116, v7, v5
	v_max_u32_e32 v120, v10, v4
	v_min_u32_e32 v124, v10, v4
	v_lshl_add_u32 v243, v0, 2, s19
	v_lshl_add_u32 v244, v1, 2, v175
	ds_read_b32 v0, v237 offset:53248
	ds_read_b32 v1, v238 offset:53312
	ds_read_b32 v2, v239 offset:53248
	ds_read_b32 v3, v240 offset:53312
	ds_read_b32 v4, v241 offset:53248
	ds_read_b32 v5, v242 offset:53312
	ds_read_b32 v6, v243 offset:53248
	ds_read_b32 v7, v244 offset:53312
	v_max_u32_e32 v20, v16, v11
	v_min_u32_e32 v11, v16, v11
	v_not_b32_e32 v16, v11
	s_waitcnt lgkmcnt(2)
	v_add_f32_e32 v148, v4, v5
	v_lshrrev_b32_e32 v5, 4, v16
	v_and_or_b32 v5, v5, 15, v174
	v_bitop3_b32 v10, v11, 15, v11 bitop3:0xc
	v_lshl_add_u32 v5, v5, 2, s19
	v_max_u32_e32 v22, v9, v8
	s_waitcnt lgkmcnt(0)
; DI void topk_phase(unsigned char* smem_, const bf16_t* __restrict__ qp, const bf16_t* __restrict__ keys, int* __restrict__ eidx, float* __restrict__ gate) {
;     ...
;     float bv[16]; int be[16]; float mx = -3.0e38f;
; #pragma unroll
;     for (int i = 0; i < 16; ++i) {
;         const int ab = 255 - (int)(c16[i] & 255u), a = ab >> 4, b = ab & 15;
;         bv[i] = SV[row * 32 + a] + SV[row * 32 + 16 + b];
;         be[i] = SI[row * 32 + a] * 128 + SI[row * 32 + 16 + b];
;         mx = fmaxf(mx, bv[i]);
;     }
;     float sum = 0.f, ex[16];
; #pragma unroll
;     for (int i = 0; i < 16; ++i) { ex[i] = __expf(bv[i] - mx); sum += ex[i]; }
;     const float inv = 1.f / sum;
;     const size_t ob = (size_t)(tok0 + row) * 128 + h * 16;
; #pragma unroll
;     for (int i = 0; i < 16; ++i) if ((i >> 2) == q) { eidx[ob + i] = be[i]; gate[ob + i] = ex[i] * inv; }
	v_add_f32_e32 v149, v6, v7
	ds_read2st64_b32 v[6:7], v5 offset0:208 offset1:240
	v_lshl_add_u32 v5, v10, 2, v175
	v_not_b32_e32 v23, v22
	v_add_u32_e32 v5, 64, v5
	ds_read2st64_b32 v[10:11], v5 offset0:208 offset1:240
	v_lshrrev_b32_e32 v5, 4, v23
	v_and_or_b32 v5, v5, 15, v174
	v_bitop3_b32 v12, v22, 15, v22 bitop3:0xc
	v_lshl_add_u32 v5, v5, 2, s19
	v_min_u32_e32 v8, v9, v8
	v_max_u32_e32 v24, v14, v15
	v_min_u32_e32 v26, v14, v15
	v_add_f32_e32 v146, v0, v1
	v_add_f32_e32 v147, v2, v3
	ds_read2st64_b32 v[14:15], v5 offset0:208 offset1:240
	v_lshl_add_u32 v5, v12, 2, v184
	v_not_b32_e32 v21, v20
	v_not_b32_e32 v9, v8
	v_max3_f32 v0, v146, s16, v147
	v_add_u32_e32 v5, 64, v5
	v_max3_f32 v4, v0, v148, v149
	v_lshrrev_b32_e32 v0, 4, v21
	v_bitop3_b32 v2, v20, 15, v20 bitop3:0xc
	ds_read2st64_b32 v[20:21], v5 offset0:208 offset1:240
	v_lshrrev_b32_e32 v5, 4, v9
	v_and_or_b32 v0, v0, 15, v174
	v_lshl_add_u32 v2, v2, 2, v184
	v_and_or_b32 v5, v5, 15, v174
	v_lshl_add_u32 v0, v0, 2, s19
	v_add_u32_e32 v2, 64, v2
	v_bitop3_b32 v8, v8, 15, v8 bitop3:0xc
	v_lshl_add_u32 v5, v5, 2, s19
	ds_read2st64_b32 v[0:1], v0 offset0:208 offset1:240
	ds_read2st64_b32 v[2:3], v2 offset0:208 offset1:240
	ds_read2st64_b32 v[28:29], v5 offset0:208 offset1:240
	v_lshl_add_u32 v5, v8, 2, v175
	v_add_u32_e32 v5, 64, v5
	v_not_b32_e32 v27, v26
	ds_read2st64_b32 v[118:119], v5 offset0:208 offset1:240
	v_lshrrev_b32_e32 v13, 4, v27
	v_and_or_b32 v13, v13, 15, v174
	s_waitcnt lgkmcnt(2)
	v_add_f32_e32 v0, v0, v2
	v_add_f32_e32 v2, v6, v10
	v_add_f32_e32 v6, v14, v20
	v_bitop3_b32 v14, v26, 15, v26 bitop3:0xc
	v_lshl_add_u32 v13, v13, 2, s19
	ds_read2st64_b32 v[16:17], v13 offset0:208 offset1:240
	v_lshl_add_u32 v13, v14, 2, v175
	v_not_b32_e32 v25, v24
	v_not_b32_e32 v31, v30
	v_max3_f32 v4, v4, v0, v2
	s_waitcnt lgkmcnt(1)
	v_add_f32_e32 v10, v28, v118
	v_add_u32_e32 v13, 64, v13
	v_max3_f32 v12, v4, v6, v10
	v_lshrrev_b32_e32 v4, 4, v25
	v_bitop3_b32 v8, v24, 15, v24 bitop3:0xc
	ds_read2st64_b32 v[22:23], v13 offset0:208 offset1:240
	v_lshrrev_b32_e32 v13, 4, v31
	v_and_or_b32 v4, v4, 15, v174
	v_lshl_add_u32 v8, v8, 2, v184
	v_and_or_b32 v13, v13, 15, v174
	v_lshl_add_u32 v4, v4, 2, s19
	v_add_u32_e32 v8, 64, v8
	v_bitop3_b32 v14, v30, 15, v30 bitop3:0xc
	v_lshl_add_u32 v13, v13, 2, s19
	ds_read2st64_b32 v[4:5], v4 offset0:208 offset1:240
	ds_read2st64_b32 v[8:9], v8 offset0:208 offset1:240
	ds_read2st64_b32 v[24:25], v13 offset0:208 offset1:240
	v_lshl_add_u32 v13, v14, 2, v184
	v_not_b32_e32 v117, v116
	v_add_u32_e32 v13, 64, v13
	ds_read2st64_b32 v[30:31], v13 offset0:208 offset1:240
	v_lshrrev_b32_e32 v13, 4, v117
	v_and_or_b32 v13, v13, 15, v174
	v_not_b32_e32 v125, v124
	v_bitop3_b32 v14, v116, 15, v116 bitop3:0xc
	v_lshl_add_u32 v13, v13, 2, s19
	ds_read2st64_b32 v[122:123], v13 offset0:208 offset1:240
	v_lshl_add_u32 v13, v14, 2, v175
	s_waitcnt lgkmcnt(3)
	v_add_f32_e32 v4, v4, v8
	v_add_f32_e32 v8, v16, v22
	v_lshrrev_b32_e32 v22, 4, v125
	v_add_u32_e32 v13, 64, v13
	v_and_or_b32 v22, v22, 15, v174
	ds_read2st64_b32 v[126:127], v13 offset0:208 offset1:240
	s_waitcnt lgkmcnt(2)
	v_add_f32_e32 v14, v24, v30
	v_bitop3_b32 v24, v124, 15, v124 bitop3:0xc
	v_lshl_add_u32 v22, v22, 2, s19
	ds_read2st64_b32 v[26:27], v22 offset0:208 offset1:240
	v_lshl_add_u32 v22, v24, 2, v175
	v_not_b32_e32 v143, v142
	v_add_u32_e32 v22, 64, v22
	ds_read2st64_b32 v[116:117], v22 offset0:208 offset1:240
	v_lshrrev_b32_e32 v22, 4, v143
	v_and_or_b32 v22, v22, 15, v174
	v_not_b32_e32 v121, v120
	v_max3_f32 v12, v12, v4, v8
	s_waitcnt lgkmcnt(2)
	v_add_f32_e32 v16, v122, v126
	v_bitop3_b32 v24, v142, 15, v142 bitop3:0xc
	v_lshl_add_u32 v22, v22, 2, s19
	v_max3_f32 v20, v12, v14, v16
	v_lshrrev_b32_e32 v12, 4, v121
	v_bitop3_b32 v18, v120, 15, v120 bitop3:0xc
	ds_read2st64_b32 v[120:121], v22 offset0:208 offset1:240
	v_lshl_add_u32 v22, v24, 2, v184
	v_not_b32_e32 v145, v144
	v_add_u32_e32 v22, 64, v22
	ds_read2st64_b32 v[124:125], v22 offset0:208 offset1:240
	v_lshrrev_b32_e32 v22, 4, v145
	v_and_or_b32 v22, v22, 15, v174
	v_and_or_b32 v12, v12, 15, v174
	v_lshl_add_u32 v18, v18, 2, v184
	v_bitop3_b32 v24, v144, 15, v144 bitop3:0xc
	v_lshl_add_u32 v22, v22, 2, s19
	v_lshl_add_u32 v12, v12, 2, s19
	v_add_u32_e32 v18, 64, v18
	ds_read2st64_b32 v[142:143], v22 offset0:208 offset1:240
	v_lshl_add_u32 v22, v24, 2, v175
	ds_read2st64_b32 v[12:13], v12 offset0:208 offset1:240
	ds_read2st64_b32 v[18:19], v18 offset0:208 offset1:240
	v_add_u32_e32 v22, 64, v22
	ds_read2st64_b32 v[144:145], v22 offset0:208 offset1:240
	s_waitcnt lgkmcnt(4)
	v_add_f32_e32 v22, v120, v124
	s_waitcnt lgkmcnt(1)
	v_add_f32_e32 v12, v12, v18
	v_add_f32_e32 v18, v26, v116
	v_max3_f32 v20, v20, v12, v18
	s_waitcnt lgkmcnt(0)
	v_add_f32_e32 v24, v142, v144
	v_max3_f32 v20, v20, v22, v24
	v_sub_f32_e32 v26, v146, v20
	v_mul_f32_e32 v26, 0x3fb8aa3b, v26
	v_exp_f32_e32 v160, v26
	v_sub_f32_e32 v26, v147, v20
	v_sub_f32_e32 v0, v0, v20
	v_mul_f32_e32 v26, 0x3fb8aa3b, v26
	v_mul_f32_e32 v0, 0x3fb8aa3b, v0
	v_exp_f32_e32 v161, v26
	v_sub_f32_e32 v26, v148, v20
	v_exp_f32_e32 v154, v0
	v_sub_f32_e32 v0, v2, v20
	v_sub_f32_e32 v2, v4, v20
	v_mul_f32_e32 v26, 0x3fb8aa3b, v26
	v_mul_f32_e32 v2, 0x3fb8aa3b, v2
	v_exp_f32_e32 v162, v26
	v_sub_f32_e32 v26, v149, v20
	v_exp_f32_e32 v150, v2
	v_sub_f32_e32 v2, v8, v20
	v_mul_f32_e32 v26, 0x3fb8aa3b, v26
	v_mul_f32_e32 v0, 0x3fb8aa3b, v0
	v_mul_f32_e32 v2, 0x3fb8aa3b, v2
	v_exp_f32_e32 v163, v26
	v_exp_f32_e32 v155, v0
	v_sub_f32_e32 v0, v6, v20
	v_exp_f32_e32 v151, v2
	v_sub_f32_e32 v2, v14, v20
	v_add_f32_e32 v26, 0, v160
	v_mul_f32_e32 v0, 0x3fb8aa3b, v0
	v_mul_f32_e32 v2, 0x3fb8aa3b, v2
	v_add_f32_e32 v26, v161, v26
	v_exp_f32_e32 v156, v0
	v_sub_f32_e32 v0, v10, v20
	v_exp_f32_e32 v152, v2
	v_sub_f32_e32 v2, v16, v20
	v_add_f32_e32 v26, v162, v26
	v_mul_f32_e32 v0, 0x3fb8aa3b, v0
	v_mul_f32_e32 v2, 0x3fb8aa3b, v2
	v_add_f32_e32 v26, v163, v26
	v_exp_f32_e32 v157, v0
	v_exp_f32_e32 v153, v2
	v_sub_f32_e32 v2, v12, v20
	v_add_f32_e32 v0, v154, v26
	v_mul_f32_e32 v2, 0x3fb8aa3b, v2
	v_add_f32_e32 v0, v155, v0
	v_exp_f32_e32 v146, v2
	v_sub_f32_e32 v2, v18, v20
	v_add_f32_e32 v0, v156, v0
	v_mul_f32_e32 v2, 0x3fb8aa3b, v2
	v_add_f32_e32 v0, v157, v0
	v_exp_f32_e32 v147, v2
	v_sub_f32_e32 v2, v22, v20
	v_add_f32_e32 v0, v150, v0
	v_mul_f32_e32 v2, 0x3fb8aa3b, v2
	v_add_f32_e32 v0, v151, v0
	v_exp_f32_e32 v148, v2
	v_sub_f32_e32 v2, v24, v20
	v_add_f32_e32 v0, v152, v0
	v_mul_f32_e32 v2, 0x3fb8aa3b, v2
	v_add_f32_e32 v0, v153, v0
	v_exp_f32_e32 v149, v2
	v_add_f32_e32 v0, v146, v0
	v_add_f32_e32 v0, v147, v0
	v_add_f32_e32 v0, v148, v0
	v_add_f32_e32 v0, v149, v0
	v_div_scale_f32 v2, s[16:17], v0, v0, 1.0
	v_rcp_f32_e32 v4, v2
	s_nop 0
	v_fma_f32 v6, -v2, v4, 1.0
	v_fmac_f32_e32 v4, v6, v4
	v_div_scale_f32 v6, vcc, 1.0, v0, 1.0
	v_mul_f32_e32 v8, v6, v4
	v_fma_f32 v10, -v2, v8, v6
	v_fmac_f32_e32 v8, v10, v4
	v_fma_f32 v2, -v2, v8, v6
	v_div_fmas_f32 v2, v2, v4, v8
	v_div_fixup_f32 v0, v2, v0, 1.0
	s_and_saveexec_b64 s[16:17], s[4:5]
	s_cbranch_execnz .LBB0_79
; DI void topk_phase(unsigned char* smem_, const bf16_t* __restrict__ qp, const bf16_t* __restrict__ keys, int* __restrict__ eidx, float* __restrict__ gate) {
;     ...
;     const size_t ob = (size_t)(tok0 + row) * 128 + h * 16;
; #pragma unroll
;     for (int i = 0; i < 16; ++i) if ((i >> 2) == q) { eidx[ob + i] = be[i]; gate[ob + i] = ex[i] * inv; }
	s_or_b64 exec, exec, s[16:17]
	s_and_saveexec_b64 s[16:17], s[6:7]
	s_cbranch_execnz .LBB0_80

; DI void topk_phase(unsigned char* smem_, const bf16_t* __restrict__ qp, const bf16_t* __restrict__ keys, int* __restrict__ eidx, float* __restrict__ gate) {
;     ...
;     const size_t ob = (size_t)(tok0 + row) * 128 + h * 16;
; #pragma unroll
;     for (int i = 0; i < 16; ++i) if ((i >> 2) == q) { eidx[ob + i] = be[i]; gate[ob + i] = ex[i] * inv; }
.LBB0_82:
	v_or_b32_e32 v158, 48, v158
	v_lshl_add_u32 v3, v27, 7, v117
	v_lshl_add_u32 v2, v13, 7, v19
	v_lshl_add_u32 v5, v143, 7, v145
	v_lshl_add_u32 v4, v121, 7, v125
	v_lshl_add_u64 v[10:11], s[92:93], 0, v[158:159]
	v_pk_mul_f32 v[6:7], v[146:147], v[0:1] op_sel_hi:[1,0]
	v_lshl_add_u64 v[12:13], s[76:77], 0, v[158:159]
	v_pk_mul_f32 v[8:9], v[148:149], v[0:1] op_sel_hi:[1,0]
	global_store_dwordx4 v[10:11], v[2:5], off
	global_store_dwordx4 v[12:13], v[6:9], off
	s_branch .LBB0_54
	s_nop 0
	s_nop 0
	s_nop 0
	s_nop 0
	s_nop 0
	s_nop 0
	s_nop 0
	s_nop 0
	s_nop 0
	s_nop 0
	s_nop 0
	s_nop 0
	s_nop 0
	s_nop 0
	s_nop 0
	s_nop 0
	s_nop 0
	s_nop 0
	s_nop 0
	s_nop 0
	s_nop 0
	s_nop 0
	s_nop 0
	s_nop 0
	s_nop 0
	s_nop 0
	s_nop 0
	s_nop 0
	s_nop 0
	s_nop 0
	s_nop 0
	s_nop 0
	s_nop 0
	s_nop 0
	s_nop 0
	s_nop 0
	s_nop 0
	s_nop 0
	s_nop 0
	s_nop 0
	s_nop 0
	s_nop 0
	s_nop 0
	s_nop 0
	s_nop 0
	s_nop 0
	s_nop 0
	s_nop 0
	s_nop 0
	s_nop 0
	s_nop 0
	s_nop 0
	s_nop 0
	s_nop 0
	s_nop 0
	s_nop 0
	s_nop 0
	s_nop 0
	s_nop 0
	s_nop 0
	s_nop 0
	s_nop 0
	s_nop 0
	s_nop 0
	s_nop 0

; DI unsigned xcc_id() { return (unsigned)__builtin_amdgcn_s_getreg((3 << 11) | 20) & 0xFu; }
; __global__ void __launch_bounds__(512) fwd_kernel(Params p) {
;     extern __shared__ __attribute__((aligned(16))) unsigned char smem[];
;     cg::grid_group grid = cg::this_grid();
;     unsigned nsync = 0, my_xcnt = 0, nxcd = 0;
;     unsigned* ctl = (unsigned*)(p.ws + OFF_CTL);
;     const unsigned xcd = __builtin_amdgcn_readfirstlane(xcc_id());
;     if (threadIdx.x == 0) __hip_atomic_fetch_add(ctl + 512 + 16 * xcd, 1u, __ATOMIC_RELAXED, __HIP_MEMORY_SCOPE_AGENT);
;     if (p.ph_hi - p.ph_lo > 1) {
;         if (p.ph_lo < 0) grid.sync();
;         __syncthreads();
;         if (threadIdx.x == 0) {
;             __hip_atomic_fetch_add(ctl + 32, 1u, __ATOMIC_RELAXED, __HIP_MEMORY_SCOPE_AGENT);
;             while (__hip_atomic_load(ctl + 32, __ATOMIC_RELAXED, __HIP_MEMORY_SCOPE_AGENT) < gridDim.x) __builtin_amdgcn_s_sleep(2);
;         }
;         __syncthreads();
;         my_xcnt = __hip_atomic_load(ctl + 512 + 16 * xcd, __ATOMIC_RELAXED, __HIP_MEMORY_SCOPE_AGENT);
;         for (int j = 0; j < 16; ++j) nxcd += (__hip_atomic_load(ctl + 512 + 16 * j, __ATOMIC_RELAXED, __HIP_MEMORY_SCOPE_AGENT) != 0u) ? 1u : 0u;
;     }
;     for (int ph = p.ph_lo; ph < p.ph_hi; ++ph) {
;         const int reps = ((EXP_MASK >> (ph & 7)) & 1) ? 2 : 1;
;         for (int rep = 0; rep < reps; ++rep) {
;             run_phase(smem, p, ph, rep, rep + 1 < reps);
;             if (rep + 1 < reps) { ++nsync; grid_barrier(ctl, nsync, xcd, my_xcnt, nxcd); }
;         }
;         if (ph + 1 < p.ph_hi) {
;             ++nsync; grid_barrier(ctl, nsync, xcd, my_xcnt, nxcd);
;         }
;     }
; }
	.amdhsa_kernel _Z10fwd_kernel6Params
		.amdhsa_group_segment_fixed_size 6144
		.amdhsa_private_segment_fixed_size 0
		.amdhsa_kernarg_size 424
		.amdhsa_user_sgpr_count 2
		.amdhsa_user_sgpr_dispatch_ptr 0
		.amdhsa_user_sgpr_queue_ptr 0
		.amdhsa_user_sgpr_kernarg_segment_ptr 1
		.amdhsa_user_sgpr_dispatch_id 0
		.amdhsa_user_sgpr_kernarg_preload_length 0
		.amdhsa_user_sgpr_kernarg_preload_offset 0
		.amdhsa_user_sgpr_private_segment_size 0
		.amdhsa_uses_dynamic_stack 0
		.amdhsa_enable_private_segment 0
		.amdhsa_system_sgpr_workgroup_id_x 1
		.amdhsa_system_sgpr_workgroup_id_y 0
		.amdhsa_system_sgpr_workgroup_id_z 0
		.amdhsa_system_sgpr_workgroup_info 0
		.amdhsa_system_vgpr_workitem_id 2
		.amdhsa_next_free_vgpr 253
		.amdhsa_next_free_sgpr 99
		.amdhsa_accum_offset 256
		.amdhsa_reserve_vcc 1
		.amdhsa_float_round_mode_32 0
		.amdhsa_float_round_mode_16_64 0
		.amdhsa_float_denorm_mode_32 3
		.amdhsa_float_denorm_mode_16_64 3
		.amdhsa_dx10_clamp 1
		.amdhsa_ieee_mode 1
		.amdhsa_fp16_overflow 0
		.amdhsa_tg_split 0
		.amdhsa_exception_fp_ieee_invalid_op 0
		.amdhsa_exception_fp_denorm_src 0
		.amdhsa_exception_fp_ieee_div_zero 0
		.amdhsa_exception_fp_ieee_overflow 0
		.amdhsa_exception_fp_ieee_underflow 0
		.amdhsa_exception_fp_ieee_inexact 0
		.amdhsa_exception_int_div_zero 0
	.end_amdhsa_kernel

; DI unsigned xcc_id() { return (unsigned)__builtin_amdgcn_s_getreg((3 << 11) | 20) & 0xFu; }
; __global__ void __launch_bounds__(512) fwd_kernel(Params p) {
;     extern __shared__ __attribute__((aligned(16))) unsigned char smem[];
;     cg::grid_group grid = cg::this_grid();
;     unsigned nsync = 0, my_xcnt = 0, nxcd = 0;
;     unsigned* ctl = (unsigned*)(p.ws + OFF_CTL);
;     const unsigned xcd = __builtin_amdgcn_readfirstlane(xcc_id());
;     if (threadIdx.x == 0) __hip_atomic_fetch_add(ctl + 512 + 16 * xcd, 1u, __ATOMIC_RELAXED, __HIP_MEMORY_SCOPE_AGENT);
;     if (p.ph_hi - p.ph_lo > 1) {
;         if (p.ph_lo < 0) grid.sync();
;         __syncthreads();
;         if (threadIdx.x == 0) {
;             __hip_atomic_fetch_add(ctl + 32, 1u, __ATOMIC_RELAXED, __HIP_MEMORY_SCOPE_AGENT);
;             while (__hip_atomic_load(ctl + 32, __ATOMIC_RELAXED, __HIP_MEMORY_SCOPE_AGENT) < gridDim.x) __builtin_amdgcn_s_sleep(2);
;         }
;         __syncthreads();
;         my_xcnt = __hip_atomic_load(ctl + 512 + 16 * xcd, __ATOMIC_RELAXED, __HIP_MEMORY_SCOPE_AGENT);
;         for (int j = 0; j < 16; ++j) nxcd += (__hip_atomic_load(ctl + 512 + 16 * j, __ATOMIC_RELAXED, __HIP_MEMORY_SCOPE_AGENT) != 0u) ? 1u : 0u;
;     }
;     for (int ph = p.ph_lo; ph < p.ph_hi; ++ph) {
;         const int reps = ((EXP_MASK >> (ph & 7)) & 1) ? 2 : 1;
;         for (int rep = 0; rep < reps; ++rep) {
;             run_phase(smem, p, ph, rep, rep + 1 < reps);
;             if (rep + 1 < reps) { ++nsync; grid_barrier(ctl, nsync, xcd, my_xcnt, nxcd); }
;         }
;         if (ph + 1 < p.ph_hi) {
;             ++nsync; grid_barrier(ctl, nsync, xcd, my_xcnt, nxcd);
;         }
;     }
; }
amdhsa.kernels:
  - .agpr_count:     0
    .args:
      - .offset:         0
        .size:           168
        .value_kind:     by_value
      - .offset:         168
        .size:           4
        .value_kind:     hidden_block_count_x
      - .offset:         172
        .size:           4
        .value_kind:     hidden_block_count_y
      - .offset:         176
        .size:           4
        .value_kind:     hidden_block_count_z
      - .offset:         180
        .size:           2
        .value_kind:     hidden_group_size_x
      - .offset:         182
        .size:           2
        .value_kind:     hidden_group_size_y
      - .offset:         184
        .size:           2
        .value_kind:     hidden_group_size_z
      - .offset:         186
        .size:           2
        .value_kind:     hidden_remainder_x
      - .offset:         188
        .size:           2
        .value_kind:     hidden_remainder_y
      - .offset:         190
        .size:           2
        .value_kind:     hidden_remainder_z
      - .offset:         208
        .size:           8
        .value_kind:     hidden_global_offset_x
      - .offset:         216
        .size:           8
        .value_kind:     hidden_global_offset_y
      - .offset:         224
        .size:           8
        .value_kind:     hidden_global_offset_z
      - .offset:         232
        .size:           2
        .value_kind:     hidden_grid_dims
      - .offset:         256
        .size:           8
        .value_kind:     hidden_multigrid_sync_arg
      - .offset:         288
        .size:           4
        .value_kind:     hidden_dynamic_lds_size
    .group_segment_fixed_size: 6144
    .kernarg_segment_align: 8
    .kernarg_segment_size: 424
    .language:       OpenCL C
    .language_version:
      - 2
      - 0
    .max_flat_workgroup_size: 512
    .name:           _Z10fwd_kernel6Params
    .private_segment_fixed_size: 0
    .sgpr_count:     105
    .sgpr_spill_count: 157
    .symbol:         _Z10fwd_kernel6Params.kd
    .uniform_work_group_size: 1
    .uses_dynamic_stack: false
    .vgpr_count:     253
    .vgpr_spill_count: 0
    .wavefront_size: 64
